# GEMM K-loops: the 4 per-iteration VALU adds forming LDS read addresses replaced by one per-unit base register and immediate ds_read offsets
# baseline (speedup 1.0000x reference)
; #define PG8_STAGE(bufoff, gbase, voff) do { _Pragma("unroll") for (int _i = 0; _i < 2; ++_i) \
;         __builtin_amdgcn_global_load_lds((const unsigned*)((const char*)(gbase) + (voff)[_i]), (PG8_LAS unsigned*)(lds + (bufoff) + ldsw + _i * 8192), 16, 0, 0); } while (0)
; #define PG8_LDA(dst, b, h) do { _Pragma("unroll") for (int m = 0; m < 4; ++m) _Pragma("unroll") for (int k = 0; k < 2; ++k) dst[m][k] = *(const PG8_LAS bf16x8*)(lds + PG8_SA(b, h) + aoff + m * 2048 + k * 1024); } while (0)
; #define PG8_LDB(dst, b, h) do { _Pragma("unroll") for (int n = 0; n < 2; ++n) _Pragma("unroll") for (int k = 0; k < 2; ++k) dst[n][k] = *(const PG8_LAS bf16x8*)(lds + PG8_SB(b, h) + boff + n * 2048 + k * 1024); } while (0)
; #define PG8_WAIT_V(n) asm volatile("s_waitcnt vmcnt(" #n ")" ::: "memory")
; #define PG8_WAIT_L(n) asm volatile("s_waitcnt lgkmcnt(" #n ")" ::: "memory")
; #define PG8_BAR __builtin_amdgcn_s_barrier()
; template <class Epi, class Sched, bool ALIGN_EPI = false, bool SP2 = false>
; __device__ __forceinline__ void gemm_phase(PG8_LAS unsigned char* lds, const Gemm g, const Sched& S, const Epi& E, int wave_s) {
;     ...
;         const bool has_next = S.next(ui + 1, nxt);
;         const char* nA = has_next ? (const char*)g.A + (size_t)nxt.pm * tstepA : cA; const char* nB = has_next ? (const char*)g.Bt + (size_t)nxt.pn * tstepB : cB;
;         for (int t = 0; t < nt; t += 2) {
;             const bool last = (t == nt - 2);
;             const char* a1 = cA + (size_t)(t + 1) * kstep;
;             const char* a2 = last ? nA : cA + (size_t)(t + 2) * kstep; const char* b2 = last ? nB : cB + (size_t)(t + 2) * kstep;
;             const char* a3 = a2 + kstep; const char* b3 = b2 + kstep;
;             if (last && has_next) S.a_ready(nxt);
;             if constexpr (SP2) {
;             PG8_LDB(B0, 0, 0); PG8_LDB(B1, 0, 1); PG8_SCHED; PG8_LDA(At, 0, 0); PG8_STAGE(PG8_SA(1, 1), a1 + hstepA, voffA);
;             PG8_WAIT_V(8); PG8_WAIT_L(0); PG8_BAR; PG8_MMA(0, 0, At, B0); PG8_MMA(0, 1, At, B1); PG8_BAR; PG8_SCHED;
;     ...
;         for (int a = 0; a < 2; ++a)
; #pragma unroll
;             for (int b = 0; b < 2; ++b)
; #pragma unroll
;                 for (int m = 0; m < 4; ++m)
; #pragma unroll
;                     for (int n = 0; n < 2; ++n) acc[a][b][m][n] = (f32x4){0.f, 0.f, 0.f, 0.f};
;         cur = nxt; cA = nA; cB = nB; ++ui;
.LBB0_191:
	s_ashr_i32 s23, s22, 31
	s_lshl_b64 s[24:25], s[22:23], 20
	s_add_u32 s24, s2, s24
	s_addc_u32 s25, s30, s25
	s_and_b64 s[36:37], s[34:35], exec
	s_cselect_b32 s23, s25, s27
	s_cselect_b32 s39, s24, s26
	s_ashr_i32 s21, s20, 31
	s_lshl_b64 s[36:37], s[20:21], 20
	s_add_u32 s40, s42, s36
	s_addc_u32 s41, s43, s37
	s_and_b64 s[36:37], s[34:35], exec
	s_cselect_b32 s21, s41, s19
	s_cselect_b32 s52, s40, s18
	s_add_u32 s53, s18, 0x100
	s_addc_u32 s54, s19, 0
	s_add_u32 s18, s26, 0x80080
	v_mov_b32_e32 v36, 0
	s_addc_u32 s19, s27, 0
	s_mov_b32 s55, -2
	v_mov_b32_e32 v37, v36
	v_mov_b32_e32 v38, v36
	v_mov_b32_e32 v39, v36
	v_mov_b32_e32 v40, v36
	v_mov_b32_e32 v41, v36
	v_mov_b32_e32 v42, v36
	v_mov_b32_e32 v43, v36
	v_mov_b32_e32 v76, v36
	v_mov_b32_e32 v77, v36
	v_mov_b32_e32 v78, v36
	v_mov_b32_e32 v79, v36
	v_mov_b32_e32 v80, v36
	v_mov_b32_e32 v81, v36
	v_mov_b32_e32 v82, v36
	v_mov_b32_e32 v83, v36
	v_mov_b32_e32 v84, v36
	v_mov_b32_e32 v85, v36
	v_mov_b32_e32 v86, v36
	v_mov_b32_e32 v87, v36
	v_mov_b32_e32 v88, v36
	v_mov_b32_e32 v89, v36
	v_mov_b32_e32 v90, v36
	v_mov_b32_e32 v91, v36
	v_mov_b32_e32 v92, v36
	v_mov_b32_e32 v93, v36
	v_mov_b32_e32 v94, v36
	v_mov_b32_e32 v95, v36
	v_mov_b32_e32 v96, v36
	v_mov_b32_e32 v97, v36
	v_mov_b32_e32 v98, v36
	v_mov_b32_e32 v99, v36
	v_mov_b32_e32 v4, v36
	v_mov_b32_e32 v5, v36
	v_mov_b32_e32 v6, v36
	v_mov_b32_e32 v7, v36
	v_mov_b32_e32 v8, v36
	v_mov_b32_e32 v9, v36
	v_mov_b32_e32 v10, v36
	v_mov_b32_e32 v11, v36
	v_mov_b32_e32 v12, v36
	v_mov_b32_e32 v13, v36
	v_mov_b32_e32 v14, v36
	v_mov_b32_e32 v15, v36
	v_mov_b32_e32 v16, v36
	v_mov_b32_e32 v17, v36
	v_mov_b32_e32 v18, v36
	v_mov_b32_e32 v19, v36
	v_mov_b32_e32 v20, v36
	v_mov_b32_e32 v21, v36
	v_mov_b32_e32 v22, v36
	v_mov_b32_e32 v23, v36
	v_mov_b32_e32 v24, v36
	v_mov_b32_e32 v25, v36
	v_mov_b32_e32 v26, v36
	v_mov_b32_e32 v27, v36
	v_mov_b32_e32 v28, v36
	v_mov_b32_e32 v29, v36
	v_mov_b32_e32 v30, v36
	v_mov_b32_e32 v31, v36
	v_mov_b32_e32 v32, v36
	v_mov_b32_e32 v33, v36
	v_mov_b32_e32 v34, v36
	v_mov_b32_e32 v35, v36
	v_mov_b32_e32 v100, v36
	v_mov_b32_e32 v101, v36
	v_mov_b32_e32 v102, v36
	v_mov_b32_e32 v103, v36
	v_mov_b32_e32 v104, v36
	v_mov_b32_e32 v105, v36
	v_mov_b32_e32 v106, v36
	v_mov_b32_e32 v107, v36
	s_waitcnt vmcnt(0) lgkmcnt(0)
	v_mov_b32_e32 v108, v36
	v_mov_b32_e32 v109, v36
	v_mov_b32_e32 v110, v36
	v_mov_b32_e32 v111, v36
	v_mov_b32_e32 v112, v36
	v_mov_b32_e32 v113, v36
	v_mov_b32_e32 v114, v36
	v_mov_b32_e32 v115, v36
	v_mov_b32_e32 v116, v36
	v_mov_b32_e32 v117, v36
	v_mov_b32_e32 v118, v36
	v_mov_b32_e32 v119, v36
	v_mov_b32_e32 v120, v36
	v_mov_b32_e32 v121, v36
	v_mov_b32_e32 v122, v36
	v_mov_b32_e32 v123, v36
	v_mov_b32_e32 v124, v36
	v_mov_b32_e32 v125, v36
	v_mov_b32_e32 v126, v36
	v_mov_b32_e32 v127, v36
	v_mov_b32_e32 v128, v36
	v_mov_b32_e32 v129, v36
	v_mov_b32_e32 v130, v36
	v_mov_b32_e32 v131, v36
	v_mov_b32_e32 v44, v36
	v_mov_b32_e32 v45, v36
	v_mov_b32_e32 v46, v36
	v_mov_b32_e32 v47, v36
	v_mov_b32_e32 v48, v36
	v_mov_b32_e32 v49, v36
	v_mov_b32_e32 v50, v36
	v_mov_b32_e32 v51, v36
	v_mov_b32_e32 v52, v36
	v_mov_b32_e32 v53, v36
	v_mov_b32_e32 v54, v36
	v_mov_b32_e32 v55, v36
	v_mov_b32_e32 v56, v36
	v_mov_b32_e32 v57, v36
	v_mov_b32_e32 v58, v36
	v_mov_b32_e32 v59, v36
	v_mov_b32_e32 v60, v36
	v_mov_b32_e32 v61, v36
	v_mov_b32_e32 v62, v36
	v_mov_b32_e32 v63, v36
	v_mov_b32_e32 v64, v36
	v_mov_b32_e32 v65, v36
	v_mov_b32_e32 v66, v36
	v_mov_b32_e32 v67, v36
	v_mov_b32_e32 v68, v36
	v_mov_b32_e32 v69, v36
	v_mov_b32_e32 v70, v36
	v_mov_b32_e32 v71, v36
	v_mov_b32_e32 v72, v36
	v_mov_b32_e32 v73, v36
	v_mov_b32_e32 v74, v36
	v_mov_b32_e32 v75, v36
	v_add_u32_e32 v255, 0x10000, v149
.LBB0_192:
	s_add_u32 s26, s18, 0xfff80080
	s_addc_u32 s27, s19, -1
	s_add_i32 s56, 0, 0x10000
	s_cmp_eq_u32 s55, 28
	s_cselect_b32 s37, s23, s27
	s_cselect_b32 s36, s39, s26
	s_cselect_b32 s27, s21, s54
	s_cselect_b32 s26, s52, s53
	s_add_i32 s58, 0, 0x14000
	ds_read_b128 v[142:145], v255
	ds_read_b128 v[152:155], v255 offset:1024
	ds_read_b128 v[156:159], v255 offset:2048
	ds_read_b128 v[160:163], v255 offset:3072
	ds_read_b128 v[164:167], v255 offset:16384
	ds_read_b128 v[182:185], v255 offset:17408
	ds_read_b128 v[186:189], v255 offset:18432
	ds_read_b128 v[190:193], v255 offset:19456
	s_add_i32 m0, s45, 0xc000
	ds_read_b128 v[194:197], v151
	ds_read_b128 v[198:201], v151 offset:1024
	ds_read_b128 v[212:215], v151 offset:2048
	ds_read_b128 v[216:219], v151 offset:3072
	ds_read_b128 v[220:223], v151 offset:4096
	ds_read_b128 v[224:227], v151 offset:5120
	ds_read_b128 v[228:231], v151 offset:6144
	ds_read_b128 v[232:235], v151 offset:7168
	global_load_lds_dwordx4 v140, s[18:19]
	s_add_i32 m0, s45, 0xe000
	s_nop 0
	global_load_lds_dwordx4 v138, s[18:19]
	s_waitcnt vmcnt(8)
	s_waitcnt lgkmcnt(0)
	s_barrier
; #define PG8_STAGE(bufoff, gbase, voff) do { _Pragma("unroll") for (int _i = 0; _i < 2; ++_i) \
;         __builtin_amdgcn_global_load_lds((const unsigned*)((const char*)(gbase) + (voff)[_i]), (PG8_LAS unsigned*)(lds + (bufoff) + ldsw + _i * 8192), 16, 0, 0); } while (0)
; #define PG8_LDA(dst, b, h) do { _Pragma("unroll") for (int m = 0; m < 4; ++m) _Pragma("unroll") for (int k = 0; k < 2; ++k) dst[m][k] = *(const PG8_LAS bf16x8*)(lds + PG8_SA(b, h) + aoff + m * 2048 + k * 1024); } while (0)
; #define PG8_MMA(ai, bj, At, Bt) do { __builtin_amdgcn_s_setprio(1); _Pragma("unroll") for (int m = 0; m < 4; ++m) _Pragma("unroll") for (int n = 0; n < 2; ++n) _Pragma("unroll") for (int k = 0; k < 2; ++k) \
;         acc[ai][bj][m][n] = __builtin_amdgcn_mfma_f32_16x16x32_bf16(Bt[n][k], At[m][k], acc[ai][bj][m][n], 0, 0, 0); __builtin_amdgcn_s_setprio(0); } while (0)
; #define PG8_WAIT_V(n) asm volatile("s_waitcnt vmcnt(" #n ")" ::: "memory")
; #define PG8_WAIT_L(n) asm volatile("s_waitcnt lgkmcnt(" #n ")" ::: "memory")
; #define PG8_BAR __builtin_amdgcn_s_barrier()
; #define PG8_SCHED __builtin_amdgcn_sched_barrier(0)
; template <class Epi, class Sched, bool ALIGN_EPI = false, bool SP2 = false>
; __device__ __forceinline__ void gemm_phase(PG8_LAS unsigned char* lds, const Gemm g, const Sched& S, const Epi& E, int wave_s) {
;     ...
;             PG8_WAIT_V(8); PG8_WAIT_L(0); PG8_BAR; PG8_MMA(0, 0, At, B0); PG8_MMA(0, 1, At, B1); PG8_BAR; PG8_SCHED;
;             PG8_LDA(At, 0, 1); PG8_STAGE(PG8_SB(0, 0), b2, voffB); PG8_STAGE(PG8_SB(0, 1), b2 + hstepB, voffB); PG8_STAGE(PG8_SA(0, 0), a2, voffA);
;             PG8_WAIT_V(8); PG8_WAIT_L(0); PG8_BAR; PG8_MMA(1, 0, At, B0); PG8_MMA(1, 1, At, B1); PG8_BAR; PG8_SCHED;
	s_setprio 1
	s_waitcnt lgkmcnt(0)
	v_mfma_f32_16x16x32_bf16 v[72:75], v[142:145], v[194:197], v[72:75]
	v_mfma_f32_16x16x32_bf16 v[68:71], v[156:159], v[194:197], v[68:71]
	v_mfma_f32_16x16x32_bf16 v[64:67], v[142:145], v[212:215], v[64:67]
	v_mfma_f32_16x16x32_bf16 v[60:63], v[156:159], v[212:215], v[60:63]
	v_mfma_f32_16x16x32_bf16 v[56:59], v[142:145], v[220:223], v[56:59]
	v_mfma_f32_16x16x32_bf16 v[52:55], v[156:159], v[220:223], v[52:55]
	v_mfma_f32_16x16x32_bf16 v[48:51], v[142:145], v[228:231], v[48:51]
	v_mfma_f32_16x16x32_bf16 v[44:47], v[156:159], v[228:231], v[44:47]
	v_mfma_f32_16x16x32_bf16 v[72:75], v[152:155], v[198:201], v[72:75]
	v_mfma_f32_16x16x32_bf16 v[68:71], v[160:163], v[198:201], v[68:71]
	v_mfma_f32_16x16x32_bf16 v[64:67], v[152:155], v[216:219], v[64:67]
	v_mfma_f32_16x16x32_bf16 v[60:63], v[160:163], v[216:219], v[60:63]
	v_mfma_f32_16x16x32_bf16 v[56:59], v[152:155], v[224:227], v[56:59]
	v_mfma_f32_16x16x32_bf16 v[52:55], v[160:163], v[224:227], v[52:55]
	v_mfma_f32_16x16x32_bf16 v[48:51], v[152:155], v[232:235], v[48:51]
	v_mfma_f32_16x16x32_bf16 v[44:47], v[160:163], v[232:235], v[44:47]
	s_setprio 0
	s_setprio 1
	v_mfma_f32_16x16x32_bf16 v[128:131], v[164:167], v[194:197], v[128:131]
	v_mfma_f32_16x16x32_bf16 v[124:127], v[186:189], v[194:197], v[124:127]
	v_mfma_f32_16x16x32_bf16 v[120:123], v[164:167], v[212:215], v[120:123]
	v_mfma_f32_16x16x32_bf16 v[116:119], v[186:189], v[212:215], v[116:119]
	v_mfma_f32_16x16x32_bf16 v[112:115], v[164:167], v[220:223], v[112:115]
	v_mfma_f32_16x16x32_bf16 v[108:111], v[186:189], v[220:223], v[108:111]
	v_mfma_f32_16x16x32_bf16 v[104:107], v[164:167], v[228:231], v[104:107]
	v_mfma_f32_16x16x32_bf16 v[100:103], v[186:189], v[228:231], v[100:103]
	v_mfma_f32_16x16x32_bf16 v[128:131], v[182:185], v[198:201], v[128:131]
	v_mfma_f32_16x16x32_bf16 v[124:127], v[190:193], v[198:201], v[124:127]
	v_mfma_f32_16x16x32_bf16 v[120:123], v[182:185], v[216:219], v[120:123]
	v_mfma_f32_16x16x32_bf16 v[116:119], v[190:193], v[216:219], v[116:119]
	v_mfma_f32_16x16x32_bf16 v[112:115], v[182:185], v[224:227], v[112:115]
	v_mfma_f32_16x16x32_bf16 v[108:111], v[190:193], v[224:227], v[108:111]
	v_mfma_f32_16x16x32_bf16 v[104:107], v[182:185], v[232:235], v[104:107]
	v_mfma_f32_16x16x32_bf16 v[100:103], v[190:193], v[232:235], v[100:103]
	s_setprio 0
	s_barrier
	s_add_i32 s56, s56, s44
	s_add_u32 s98, s26, s60
	s_addc_u32 s99, s27, s61
	s_mov_b32 m0, s56
	ds_read_b128 v[194:197], v151 offset:16384
	ds_read_b128 v[198:201], v151 offset:17408
	ds_read_b128 v[212:215], v151 offset:18432
	ds_read_b128 v[216:219], v151 offset:19456
	ds_read_b128 v[220:223], v151 offset:20480
	ds_read_b128 v[224:227], v151 offset:21504
	ds_read_b128 v[228:231], v151 offset:22528
	ds_read_b128 v[232:235], v151 offset:23552
	global_load_lds_dwordx4 v2, s[26:27]
	s_add_i32 m0, s56, 0x2000
	s_add_u32 s56, s26, 0x80000
	s_addc_u32 s57, s27, 0
	s_add_i32 s58, s58, s44
	global_load_lds_dwordx4 v0, s[26:27]
	s_mov_b32 m0, s58
	s_nop 0
	global_load_lds_dwordx4 v2, s[56:57]
	s_add_i32 m0, s58, 0x2000
	s_nop 0
	global_load_lds_dwordx4 v0, s[56:57]
	s_mov_b32 m0, s45
	s_nop 0
	global_load_lds_dwordx4 v134, s[36:37]
	s_mov_b32 m0, s46
	s_nop 0
	global_load_lds_dwordx4 v132, s[36:37]
	s_waitcnt vmcnt(8)
	s_waitcnt lgkmcnt(0)
	s_barrier
	s_setprio 1
	s_waitcnt lgkmcnt(0)
	v_mfma_f32_16x16x32_bf16 v[32:35], v[142:145], v[194:197], v[32:35]
	v_mfma_f32_16x16x32_bf16 v[28:31], v[156:159], v[194:197], v[28:31]
	v_mfma_f32_16x16x32_bf16 v[24:27], v[142:145], v[212:215], v[24:27]
	v_mfma_f32_16x16x32_bf16 v[20:23], v[156:159], v[212:215], v[20:23]
	v_mfma_f32_16x16x32_bf16 v[16:19], v[142:145], v[220:223], v[16:19]
	v_mfma_f32_16x16x32_bf16 v[12:15], v[156:159], v[220:223], v[12:15]
	v_mfma_f32_16x16x32_bf16 v[8:11], v[142:145], v[228:231], v[8:11]
	v_mfma_f32_16x16x32_bf16 v[4:7], v[156:159], v[228:231], v[4:7]
	v_mfma_f32_16x16x32_bf16 v[32:35], v[152:155], v[198:201], v[32:35]
	v_mfma_f32_16x16x32_bf16 v[28:31], v[160:163], v[198:201], v[28:31]
	v_mfma_f32_16x16x32_bf16 v[24:27], v[152:155], v[216:219], v[24:27]
	v_mfma_f32_16x16x32_bf16 v[20:23], v[160:163], v[216:219], v[20:23]
	v_mfma_f32_16x16x32_bf16 v[16:19], v[152:155], v[224:227], v[16:19]
	v_mfma_f32_16x16x32_bf16 v[12:15], v[160:163], v[224:227], v[12:15]
	v_mfma_f32_16x16x32_bf16 v[8:11], v[152:155], v[232:235], v[8:11]
	v_mfma_f32_16x16x32_bf16 v[4:7], v[160:163], v[232:235], v[4:7]
	s_setprio 0
	s_setprio 1
	v_mfma_f32_16x16x32_bf16 v[96:99], v[164:167], v[194:197], v[96:99]
	v_mfma_f32_16x16x32_bf16 v[92:95], v[186:189], v[194:197], v[92:95]
	v_mfma_f32_16x16x32_bf16 v[88:91], v[164:167], v[212:215], v[88:91]
	v_mfma_f32_16x16x32_bf16 v[84:87], v[186:189], v[212:215], v[84:87]
	v_mfma_f32_16x16x32_bf16 v[80:83], v[164:167], v[220:223], v[80:83]
	v_mfma_f32_16x16x32_bf16 v[76:79], v[186:189], v[220:223], v[76:79]
	v_mfma_f32_16x16x32_bf16 v[40:43], v[164:167], v[228:231], v[40:43]
	v_mfma_f32_16x16x32_bf16 v[36:39], v[186:189], v[228:231], v[36:39]
	v_mfma_f32_16x16x32_bf16 v[96:99], v[182:185], v[198:201], v[96:99]
	v_mfma_f32_16x16x32_bf16 v[92:95], v[190:193], v[198:201], v[92:95]
	v_mfma_f32_16x16x32_bf16 v[88:91], v[182:185], v[216:219], v[88:91]
	v_mfma_f32_16x16x32_bf16 v[84:87], v[190:193], v[216:219], v[84:87]
	v_mfma_f32_16x16x32_bf16 v[80:83], v[182:185], v[224:227], v[80:83]
	v_mfma_f32_16x16x32_bf16 v[76:79], v[190:193], v[224:227], v[76:79]
	v_mfma_f32_16x16x32_bf16 v[40:43], v[182:185], v[232:235], v[40:43]
	v_mfma_f32_16x16x32_bf16 v[36:39], v[190:193], v[232:235], v[36:39]
	s_setprio 0
	s_barrier
; #define PG8_STAGE(bufoff, gbase, voff) do { _Pragma("unroll") for (int _i = 0; _i < 2; ++_i) \
;         __builtin_amdgcn_global_load_lds((const unsigned*)((const char*)(gbase) + (voff)[_i]), (PG8_LAS unsigned*)(lds + (bufoff) + ldsw + _i * 8192), 16, 0, 0); } while (0)
; #define PG8_LDA(dst, b, h) do { _Pragma("unroll") for (int m = 0; m < 4; ++m) _Pragma("unroll") for (int k = 0; k < 2; ++k) dst[m][k] = *(const PG8_LAS bf16x8*)(lds + PG8_SA(b, h) + aoff + m * 2048 + k * 1024); } while (0)
; #define PG8_LDB(dst, b, h) do { _Pragma("unroll") for (int n = 0; n < 2; ++n) _Pragma("unroll") for (int k = 0; k < 2; ++k) dst[n][k] = *(const PG8_LAS bf16x8*)(lds + PG8_SB(b, h) + boff + n * 2048 + k * 1024); } while (0)
; #define PG8_MMA(ai, bj, At, Bt) do { __builtin_amdgcn_s_setprio(1); _Pragma("unroll") for (int m = 0; m < 4; ++m) _Pragma("unroll") for (int n = 0; n < 2; ++n) _Pragma("unroll") for (int k = 0; k < 2; ++k) \
;         acc[ai][bj][m][n] = __builtin_amdgcn_mfma_f32_16x16x32_bf16(Bt[n][k], At[m][k], acc[ai][bj][m][n], 0, 0, 0); __builtin_amdgcn_s_setprio(0); } while (0)
; #define PG8_WAIT_V(n) asm volatile("s_waitcnt vmcnt(" #n ")" ::: "memory")
; #define PG8_WAIT_L(n) asm volatile("s_waitcnt lgkmcnt(" #n ")" ::: "memory")
; template <class Epi, class Sched, bool ALIGN_EPI = false, bool SP2 = false>
; __device__ __forceinline__ void gemm_phase(PG8_LAS unsigned char* lds, const Gemm g, const Sched& S, const Epi& E, int wave_s) {
;     ...
;         for (int t = 0; t < nt; t += 2) {
;             const bool last = (t == nt - 2);
;             const char* a1 = cA + (size_t)(t + 1) * kstep;
;             const char* a2 = last ? nA : cA + (size_t)(t + 2) * kstep; const char* b2 = last ? nB : cB + (size_t)(t + 2) * kstep;
;             const char* a3 = a2 + kstep; const char* b3 = b2 + kstep;
;             if (last && has_next) S.a_ready(nxt);
;     ...
;             PG8_LDB(B0, 1, 0); PG8_LDB(B1, 1, 1); PG8_SCHED; PG8_LDA(At, 1, 0); PG8_STAGE(PG8_SA(0, 1), a2 + hstepA, voffA);
;             PG8_WAIT_V(8); PG8_WAIT_L(0); PG8_BAR; PG8_MMA(0, 0, At, B0); PG8_MMA(0, 1, At, B1); PG8_BAR; PG8_SCHED;
;             PG8_LDA(At, 1, 1); PG8_STAGE(PG8_SB(1, 0), b3, voffB); PG8_STAGE(PG8_SB(1, 1), b3 + hstepB, voffB); PG8_STAGE(PG8_SA(1, 0), a3, voffA);
;             PG8_WAIT_V(8); PG8_WAIT_L(0); PG8_BAR; PG8_MMA(1, 0, At, B0); PG8_MMA(1, 1, At, B1); PG8_BAR; PG8_SCHED;
	s_add_i32 s56, 0, 0x18000
	s_add_i32 s57, 0, 0x1c000
	ds_read_b128 v[142:145], v255 offset:32768
	ds_read_b128 v[152:155], v255 offset:33792
	ds_read_b128 v[156:159], v255 offset:34816
	ds_read_b128 v[160:163], v255 offset:35840
	ds_read_b128 v[164:167], v255 offset:49152
	ds_read_b128 v[182:185], v255 offset:50176
	ds_read_b128 v[186:189], v255 offset:51200
	ds_read_b128 v[190:193], v255 offset:52224
	s_add_u32 s100, s36, s60
	s_addc_u32 s101, s37, s61
	s_add_u32 s36, s36, 0x80000
	s_addc_u32 s37, s37, 0
	s_mov_b32 m0, s47
	ds_read_b128 v[194:197], v151 offset:32768
	ds_read_b128 v[198:201], v151 offset:33792
	ds_read_b128 v[212:215], v151 offset:34816
	ds_read_b128 v[216:219], v151 offset:35840
	ds_read_b128 v[220:223], v151 offset:36864
	ds_read_b128 v[224:227], v151 offset:37888
	ds_read_b128 v[228:231], v151 offset:38912
	ds_read_b128 v[232:235], v151 offset:39936
	global_load_lds_dwordx4 v134, s[36:37]
	s_mov_b32 m0, s48
	s_nop 0
	global_load_lds_dwordx4 v132, s[36:37]
	s_waitcnt vmcnt(8)
	s_waitcnt lgkmcnt(0)
	s_barrier
	s_setprio 1
	s_waitcnt lgkmcnt(0)
	v_mfma_f32_16x16x32_bf16 v[72:75], v[142:145], v[194:197], v[72:75]
	v_mfma_f32_16x16x32_bf16 v[68:71], v[156:159], v[194:197], v[68:71]
	v_mfma_f32_16x16x32_bf16 v[64:67], v[142:145], v[212:215], v[64:67]
	v_mfma_f32_16x16x32_bf16 v[60:63], v[156:159], v[212:215], v[60:63]
	v_mfma_f32_16x16x32_bf16 v[56:59], v[142:145], v[220:223], v[56:59]
	v_mfma_f32_16x16x32_bf16 v[52:55], v[156:159], v[220:223], v[52:55]
	v_mfma_f32_16x16x32_bf16 v[48:51], v[142:145], v[228:231], v[48:51]
	v_mfma_f32_16x16x32_bf16 v[44:47], v[156:159], v[228:231], v[44:47]
	v_mfma_f32_16x16x32_bf16 v[72:75], v[152:155], v[198:201], v[72:75]
	v_mfma_f32_16x16x32_bf16 v[68:71], v[160:163], v[198:201], v[68:71]
	v_mfma_f32_16x16x32_bf16 v[64:67], v[152:155], v[216:219], v[64:67]
	v_mfma_f32_16x16x32_bf16 v[60:63], v[160:163], v[216:219], v[60:63]
	v_mfma_f32_16x16x32_bf16 v[56:59], v[152:155], v[224:227], v[56:59]
	v_mfma_f32_16x16x32_bf16 v[52:55], v[160:163], v[224:227], v[52:55]
	v_mfma_f32_16x16x32_bf16 v[48:51], v[152:155], v[232:235], v[48:51]
	v_mfma_f32_16x16x32_bf16 v[44:47], v[160:163], v[232:235], v[44:47]
	s_setprio 0
	s_setprio 1
	v_mfma_f32_16x16x32_bf16 v[128:131], v[164:167], v[194:197], v[128:131]
	v_mfma_f32_16x16x32_bf16 v[124:127], v[186:189], v[194:197], v[124:127]
	v_mfma_f32_16x16x32_bf16 v[120:123], v[164:167], v[212:215], v[120:123]
	v_mfma_f32_16x16x32_bf16 v[116:119], v[186:189], v[212:215], v[116:119]
	v_mfma_f32_16x16x32_bf16 v[112:115], v[164:167], v[220:223], v[112:115]
	v_mfma_f32_16x16x32_bf16 v[108:111], v[186:189], v[220:223], v[108:111]
	v_mfma_f32_16x16x32_bf16 v[104:107], v[164:167], v[228:231], v[104:107]
	v_mfma_f32_16x16x32_bf16 v[100:103], v[186:189], v[228:231], v[100:103]
	v_mfma_f32_16x16x32_bf16 v[128:131], v[182:185], v[198:201], v[128:131]
	v_mfma_f32_16x16x32_bf16 v[124:127], v[190:193], v[198:201], v[124:127]
	v_mfma_f32_16x16x32_bf16 v[120:123], v[182:185], v[216:219], v[120:123]
	v_mfma_f32_16x16x32_bf16 v[116:119], v[190:193], v[216:219], v[116:119]
	v_mfma_f32_16x16x32_bf16 v[112:115], v[182:185], v[224:227], v[112:115]
	v_mfma_f32_16x16x32_bf16 v[108:111], v[190:193], v[224:227], v[108:111]
	v_mfma_f32_16x16x32_bf16 v[104:107], v[182:185], v[232:235], v[104:107]
	v_mfma_f32_16x16x32_bf16 v[100:103], v[190:193], v[232:235], v[100:103]
	s_setprio 0
	s_barrier
	s_add_i32 s36, s56, s44
	s_mov_b32 m0, s36
	ds_read_b128 v[194:197], v151 offset:49152
	ds_read_b128 v[198:201], v151 offset:50176
	ds_read_b128 v[212:215], v151 offset:51200
	ds_read_b128 v[216:219], v151 offset:52224
	ds_read_b128 v[220:223], v151 offset:53248
	ds_read_b128 v[224:227], v151 offset:54272
	ds_read_b128 v[228:231], v151 offset:55296
	ds_read_b128 v[232:235], v151 offset:56320
	global_load_lds_dwordx4 v2, s[98:99]
	s_add_i32 m0, s36, 0x2000
	s_add_u32 s26, s26, 0x80080
	s_addc_u32 s27, s27, 0
	s_add_i32 s36, s57, s44
	global_load_lds_dwordx4 v0, s[98:99]
	s_mov_b32 m0, s36
	s_nop 0
	global_load_lds_dwordx4 v2, s[26:27]
	s_add_i32 m0, s36, 0x2000
	s_nop 0
	global_load_lds_dwordx4 v0, s[26:27]
	s_mov_b32 m0, s49
	s_nop 0
	global_load_lds_dwordx4 v134, s[100:101]
	s_mov_b32 m0, s50
	s_nop 0
	global_load_lds_dwordx4 v132, s[100:101]
	s_waitcnt vmcnt(8)
	s_waitcnt lgkmcnt(0)
	s_barrier
	s_setprio 1
	s_waitcnt lgkmcnt(0)
	v_mfma_f32_16x16x32_bf16 v[32:35], v[142:145], v[194:197], v[32:35]
	v_mfma_f32_16x16x32_bf16 v[28:31], v[156:159], v[194:197], v[28:31]
	v_mfma_f32_16x16x32_bf16 v[24:27], v[142:145], v[212:215], v[24:27]
	v_mfma_f32_16x16x32_bf16 v[20:23], v[156:159], v[212:215], v[20:23]
	v_mfma_f32_16x16x32_bf16 v[16:19], v[142:145], v[220:223], v[16:19]
	v_mfma_f32_16x16x32_bf16 v[12:15], v[156:159], v[220:223], v[12:15]
	v_mfma_f32_16x16x32_bf16 v[8:11], v[142:145], v[228:231], v[8:11]
	v_mfma_f32_16x16x32_bf16 v[4:7], v[156:159], v[228:231], v[4:7]
	v_mfma_f32_16x16x32_bf16 v[32:35], v[152:155], v[198:201], v[32:35]
	v_mfma_f32_16x16x32_bf16 v[28:31], v[160:163], v[198:201], v[28:31]
	v_mfma_f32_16x16x32_bf16 v[24:27], v[152:155], v[216:219], v[24:27]
	v_mfma_f32_16x16x32_bf16 v[20:23], v[160:163], v[216:219], v[20:23]
	v_mfma_f32_16x16x32_bf16 v[16:19], v[152:155], v[224:227], v[16:19]
	v_mfma_f32_16x16x32_bf16 v[12:15], v[160:163], v[224:227], v[12:15]
	v_mfma_f32_16x16x32_bf16 v[8:11], v[152:155], v[232:235], v[8:11]
	v_mfma_f32_16x16x32_bf16 v[4:7], v[160:163], v[232:235], v[4:7]
	s_setprio 0
	s_setprio 1
	v_mfma_f32_16x16x32_bf16 v[96:99], v[164:167], v[194:197], v[96:99]
	v_mfma_f32_16x16x32_bf16 v[92:95], v[186:189], v[194:197], v[92:95]
	v_mfma_f32_16x16x32_bf16 v[88:91], v[164:167], v[212:215], v[88:91]
	v_mfma_f32_16x16x32_bf16 v[84:87], v[186:189], v[212:215], v[84:87]
	v_mfma_f32_16x16x32_bf16 v[80:83], v[164:167], v[220:223], v[80:83]
	v_mfma_f32_16x16x32_bf16 v[76:79], v[186:189], v[220:223], v[76:79]
	v_mfma_f32_16x16x32_bf16 v[40:43], v[164:167], v[228:231], v[40:43]
	v_mfma_f32_16x16x32_bf16 v[36:39], v[186:189], v[228:231], v[36:39]
	v_mfma_f32_16x16x32_bf16 v[96:99], v[182:185], v[198:201], v[96:99]
	v_mfma_f32_16x16x32_bf16 v[92:95], v[190:193], v[198:201], v[92:95]
	v_mfma_f32_16x16x32_bf16 v[88:91], v[182:185], v[216:219], v[88:91]
	v_mfma_f32_16x16x32_bf16 v[84:87], v[190:193], v[216:219], v[84:87]
	v_mfma_f32_16x16x32_bf16 v[80:83], v[182:185], v[224:227], v[80:83]
	v_mfma_f32_16x16x32_bf16 v[76:79], v[190:193], v[224:227], v[76:79]
	v_mfma_f32_16x16x32_bf16 v[40:43], v[182:185], v[232:235], v[40:43]
	v_mfma_f32_16x16x32_bf16 v[36:39], v[190:193], v[232:235], v[36:39]
	s_setprio 0
	s_barrier
	s_add_i32 s55, s55, 2
	s_add_u32 s53, s53, 0x100
	s_addc_u32 s54, s54, 0
	s_add_u32 s18, s18, 0x100
	s_addc_u32 s19, s19, 0
	s_cmp_gt_u32 s55, 29
	s_cbranch_scc0 .LBB0_192
	s_and_b64 vcc, exec, s[6:7]
	s_cbranch_vccnz .LBB0_196
	v_lshl_add_u32 v142, s38, 8, v148
	s_cmpk_lg_i32 s33, 0x4a
	s_mov_b64 s[18:19], -1
	s_cbranch_scc1 .LBB0_197

; #define PG8_STAGE(bufoff, gbase, voff) do { _Pragma("unroll") for (int _i = 0; _i < 2; ++_i) \
;         __builtin_amdgcn_global_load_lds((const unsigned*)((const char*)(gbase) + (voff)[_i]), (PG8_LAS unsigned*)(lds + (bufoff) + ldsw + _i * 8192), 16, 0, 0); } while (0)
; #define PG8_LDA(dst, b, h) do { _Pragma("unroll") for (int m = 0; m < 4; ++m) _Pragma("unroll") for (int k = 0; k < 2; ++k) dst[m][k] = *(const PG8_LAS bf16x8*)(lds + PG8_SA(b, h) + aoff + m * 2048 + k * 1024); } while (0)
; #define PG8_LDB(dst, b, h) do { _Pragma("unroll") for (int n = 0; n < 2; ++n) _Pragma("unroll") for (int k = 0; k < 2; ++k) dst[n][k] = *(const PG8_LAS bf16x8*)(lds + PG8_SB(b, h) + boff + n * 2048 + k * 1024); } while (0)
; #define PG8_WAIT_V(n) asm volatile("s_waitcnt vmcnt(" #n ")" ::: "memory")
; #define PG8_WAIT_L(n) asm volatile("s_waitcnt lgkmcnt(" #n ")" ::: "memory")
; #define PG8_BAR __builtin_amdgcn_s_barrier()
; template <class Epi, class Sched, bool ALIGN_EPI = false, bool SP2 = false>
; __device__ __forceinline__ void gemm_phase(PG8_LAS unsigned char* lds, const Gemm g, const Sched& S, const Epi& E, int wave_s) {
;     ...
;         const bool has_next = S.next(ui + 1, nxt);
;         const char* nA = has_next ? (const char*)g.A + (size_t)nxt.pm * tstepA : cA; const char* nB = has_next ? (const char*)g.Bt + (size_t)nxt.pn * tstepB : cB;
;         for (int t = 0; t < nt; t += 2) {
;             const bool last = (t == nt - 2);
;             const char* a1 = cA + (size_t)(t + 1) * kstep;
;             const char* a2 = last ? nA : cA + (size_t)(t + 2) * kstep; const char* b2 = last ? nB : cB + (size_t)(t + 2) * kstep;
;             const char* a3 = a2 + kstep; const char* b3 = b2 + kstep;
;             if (last && has_next) S.a_ready(nxt);
;             if constexpr (SP2) {
;             PG8_LDB(B0, 0, 0); PG8_LDB(B1, 0, 1); PG8_SCHED; PG8_LDA(At, 0, 0); PG8_STAGE(PG8_SA(1, 1), a1 + hstepA, voffA);
;             PG8_WAIT_V(8); PG8_WAIT_L(0); PG8_BAR; PG8_MMA(0, 0, At, B0); PG8_MMA(0, 1, At, B1); PG8_BAR; PG8_SCHED;
;     ...
;         for (int a = 0; a < 2; ++a)
; #pragma unroll
;             for (int b = 0; b < 2; ++b)
; #pragma unroll
;                 for (int m = 0; m < 4; ++m)
; #pragma unroll
;                     for (int n = 0; n < 2; ++n) acc[a][b][m][n] = (f32x4){0.f, 0.f, 0.f, 0.f};
;         cur = nxt; cA = nA; cB = nB; ++ui;
.LBB0_567:
	s_ashr_i32 s19, s18, 31
	s_lshl_b64 s[22:23], s[18:19], 18
	s_add_u32 s22, s46, s22
	s_addc_u32 s23, s47, s23
	s_and_b64 s[38:39], s[38:39], exec
	s_cselect_b32 s19, s23, s27
	s_cselect_b32 s58, s22, s26
	s_add_u32 s59, s26, 0x100
	v_mov_b32_e32 v4, 0
	s_addc_u32 s66, s27, 0
	s_mov_b32 s67, -2
	v_mov_b32_e32 v5, v4
	v_mov_b32_e32 v6, v4
	v_mov_b32_e32 v7, v4
	v_mov_b32_e32 v8, v4
	v_mov_b32_e32 v9, v4
	v_mov_b32_e32 v10, v4
	v_mov_b32_e32 v11, v4
	v_mov_b32_e32 v16, v4
	v_mov_b32_e32 v17, v4
	v_mov_b32_e32 v18, v4
	v_mov_b32_e32 v19, v4
	v_mov_b32_e32 v24, v4
	v_mov_b32_e32 v25, v4
	v_mov_b32_e32 v26, v4
	v_mov_b32_e32 v27, v4
	v_mov_b32_e32 v32, v4
	v_mov_b32_e32 v33, v4
	v_mov_b32_e32 v34, v4
	v_mov_b32_e32 v35, v4
	v_mov_b32_e32 v40, v4
	v_mov_b32_e32 v41, v4
	v_mov_b32_e32 v42, v4
	v_mov_b32_e32 v43, v4
	v_mov_b32_e32 v48, v4
	v_mov_b32_e32 v49, v4
	v_mov_b32_e32 v50, v4
	v_mov_b32_e32 v51, v4
	v_mov_b32_e32 v56, v4
	v_mov_b32_e32 v57, v4
	v_mov_b32_e32 v58, v4
	v_mov_b32_e32 v59, v4
	v_mov_b32_e32 v12, v4
	v_mov_b32_e32 v13, v4
	v_mov_b32_e32 v14, v4
	v_mov_b32_e32 v15, v4
	v_mov_b32_e32 v20, v4
	v_mov_b32_e32 v21, v4
	v_mov_b32_e32 v22, v4
	v_mov_b32_e32 v23, v4
	v_mov_b32_e32 v28, v4
	v_mov_b32_e32 v29, v4
	v_mov_b32_e32 v30, v4
	v_mov_b32_e32 v31, v4
	v_mov_b32_e32 v36, v4
	v_mov_b32_e32 v37, v4
	v_mov_b32_e32 v38, v4
	v_mov_b32_e32 v39, v4
	v_mov_b32_e32 v44, v4
	v_mov_b32_e32 v45, v4
	v_mov_b32_e32 v46, v4
	v_mov_b32_e32 v47, v4
	v_mov_b32_e32 v52, v4
	v_mov_b32_e32 v53, v4
	v_mov_b32_e32 v54, v4
	v_mov_b32_e32 v55, v4
	v_mov_b32_e32 v60, v4
	v_mov_b32_e32 v61, v4
	v_mov_b32_e32 v62, v4
	v_mov_b32_e32 v63, v4
	v_mov_b32_e32 v64, v4
	v_mov_b32_e32 v65, v4
	v_mov_b32_e32 v66, v4
	v_mov_b32_e32 v67, v4
	v_mov_b32_e32 v68, v4
	v_mov_b32_e32 v69, v4
	v_mov_b32_e32 v70, v4
	v_mov_b32_e32 v71, v4
	v_mov_b32_e32 v72, v4
	v_mov_b32_e32 v73, v4
	v_mov_b32_e32 v74, v4
	v_mov_b32_e32 v75, v4
	v_mov_b32_e32 v80, v4
	v_mov_b32_e32 v81, v4
	v_mov_b32_e32 v82, v4
	v_mov_b32_e32 v83, v4
	v_mov_b32_e32 v88, v4
	v_mov_b32_e32 v89, v4
	v_mov_b32_e32 v90, v4
	v_mov_b32_e32 v91, v4
	v_mov_b32_e32 v96, v4
	v_mov_b32_e32 v97, v4
	v_mov_b32_e32 v98, v4
	v_mov_b32_e32 v99, v4
	v_mov_b32_e32 v104, v4
	v_mov_b32_e32 v105, v4
	v_mov_b32_e32 v106, v4
	v_mov_b32_e32 v107, v4
	s_waitcnt vmcnt(0) lgkmcnt(0)
	v_mov_b32_e32 v108, v4
	v_mov_b32_e32 v109, v4
	v_mov_b32_e32 v110, v4
	v_mov_b32_e32 v111, v4
	v_mov_b32_e32 v116, v4
	v_mov_b32_e32 v117, v4
	v_mov_b32_e32 v118, v4
	v_mov_b32_e32 v119, v4
	v_mov_b32_e32 v76, v4
	v_mov_b32_e32 v77, v4
	v_mov_b32_e32 v78, v4
	v_mov_b32_e32 v79, v4
	v_mov_b32_e32 v84, v4
	v_mov_b32_e32 v85, v4
	v_mov_b32_e32 v86, v4
	v_mov_b32_e32 v87, v4
	v_mov_b32_e32 v92, v4
	v_mov_b32_e32 v93, v4
	v_mov_b32_e32 v94, v4
	v_mov_b32_e32 v95, v4
	v_mov_b32_e32 v100, v4
	v_mov_b32_e32 v101, v4
	v_mov_b32_e32 v102, v4
	v_mov_b32_e32 v103, v4
	v_mov_b32_e32 v112, v4
	v_mov_b32_e32 v113, v4
	v_mov_b32_e32 v114, v4
	v_mov_b32_e32 v115, v4
	v_mov_b32_e32 v120, v4
	v_mov_b32_e32 v121, v4
	v_mov_b32_e32 v122, v4
	v_mov_b32_e32 v123, v4
	v_mov_b32_e32 v124, v4
	v_mov_b32_e32 v125, v4
	v_mov_b32_e32 v126, v4
	v_mov_b32_e32 v127, v4
	v_mov_b32_e32 v128, v4
	v_mov_b32_e32 v129, v4
	v_mov_b32_e32 v130, v4
	v_mov_b32_e32 v131, v4
	v_add_u32_e32 v255, 0x10000, v186
.LBB0_568:
	s_add_u32 s26, s24, 0x100
	s_addc_u32 s27, s25, 0
	s_add_i32 s74, 0, 0x10000
	s_cmp_eq_u32 s67, 4
	s_cselect_b32 s43, s21, s27
	s_cselect_b32 s42, s20, s26
	s_cselect_b32 s39, s19, s66
	s_cselect_b32 s38, s58, s59
	s_add_i32 s75, 0, 0x14000
	ds_read_b128 v[132:135], v255
	ds_read_b128 v[136:139], v255 offset:1024
	ds_read_b128 v[140:143], v255 offset:2048
	ds_read_b128 v[144:147], v255 offset:3072
	ds_read_b128 v[148:151], v255 offset:16384
	ds_read_b128 v[160:163], v255 offset:17408
	ds_read_b128 v[164:167], v255 offset:18432
	ds_read_b128 v[182:185], v255 offset:19456
	v_lshl_add_u64 v[232:233], s[24:25], 0, v[158:159]
	s_add_i32 m0, s49, 0xc000
	ds_read_b128 v[190:193], v188
	ds_read_b128 v[194:197], v188 offset:1024
	ds_read_b128 v[198:201], v188 offset:2048
	ds_read_b128 v[212:215], v188 offset:3072
	ds_read_b128 v[216:219], v188 offset:4096
	ds_read_b128 v[220:223], v188 offset:5120
	ds_read_b128 v[224:227], v188 offset:6144
	ds_read_b128 v[228:231], v188 offset:7168
	global_load_lds_dwordx4 v[232:233], off
	v_lshl_add_u64 v[232:233], s[24:25], 0, v[156:157]
	s_add_i32 m0, s49, 0xe000
	s_nop 0
	global_load_lds_dwordx4 v[232:233], off
	s_waitcnt vmcnt(8)
	s_waitcnt lgkmcnt(0)
	s_barrier
; #define PG8_STAGE(bufoff, gbase, voff) do { _Pragma("unroll") for (int _i = 0; _i < 2; ++_i) \
;         __builtin_amdgcn_global_load_lds((const unsigned*)((const char*)(gbase) + (voff)[_i]), (PG8_LAS unsigned*)(lds + (bufoff) + ldsw + _i * 8192), 16, 0, 0); } while (0)
; #define PG8_LDA(dst, b, h) do { _Pragma("unroll") for (int m = 0; m < 4; ++m) _Pragma("unroll") for (int k = 0; k < 2; ++k) dst[m][k] = *(const PG8_LAS bf16x8*)(lds + PG8_SA(b, h) + aoff + m * 2048 + k * 1024); } while (0)
; #define PG8_MMA(ai, bj, At, Bt) do { __builtin_amdgcn_s_setprio(1); _Pragma("unroll") for (int m = 0; m < 4; ++m) _Pragma("unroll") for (int n = 0; n < 2; ++n) _Pragma("unroll") for (int k = 0; k < 2; ++k) \
;         acc[ai][bj][m][n] = __builtin_amdgcn_mfma_f32_16x16x32_bf16(Bt[n][k], At[m][k], acc[ai][bj][m][n], 0, 0, 0); __builtin_amdgcn_s_setprio(0); } while (0)
; #define PG8_WAIT_V(n) asm volatile("s_waitcnt vmcnt(" #n ")" ::: "memory")
; #define PG8_WAIT_L(n) asm volatile("s_waitcnt lgkmcnt(" #n ")" ::: "memory")
; #define PG8_BAR __builtin_amdgcn_s_barrier()
; #define PG8_SCHED __builtin_amdgcn_sched_barrier(0)
; template <class Epi, class Sched, bool ALIGN_EPI = false, bool SP2 = false>
; __device__ __forceinline__ void gemm_phase(PG8_LAS unsigned char* lds, const Gemm g, const Sched& S, const Epi& E, int wave_s) {
;     ...
;             PG8_WAIT_V(8); PG8_WAIT_L(0); PG8_BAR; PG8_MMA(0, 0, At, B0); PG8_MMA(0, 1, At, B1); PG8_BAR; PG8_SCHED;
;             PG8_LDA(At, 0, 1); PG8_STAGE(PG8_SB(0, 0), b2, voffB); PG8_STAGE(PG8_SB(0, 1), b2 + hstepB, voffB); PG8_STAGE(PG8_SA(0, 0), a2, voffA);
;             PG8_WAIT_V(8); PG8_WAIT_L(0); PG8_BAR; PG8_MMA(1, 0, At, B0); PG8_MMA(1, 1, At, B1); PG8_BAR; PG8_SCHED;
	s_setprio 1
	s_waitcnt lgkmcnt(0)
	v_mfma_f32_16x16x32_bf16 v[128:131], v[132:135], v[190:193], v[128:131]
	v_mfma_f32_16x16x32_bf16 v[124:127], v[140:143], v[190:193], v[124:127]
	v_mfma_f32_16x16x32_bf16 v[120:123], v[132:135], v[198:201], v[120:123]
	v_mfma_f32_16x16x32_bf16 v[112:115], v[140:143], v[198:201], v[112:115]
	v_mfma_f32_16x16x32_bf16 v[100:103], v[132:135], v[216:219], v[100:103]
	v_mfma_f32_16x16x32_bf16 v[92:95], v[140:143], v[216:219], v[92:95]
	v_mfma_f32_16x16x32_bf16 v[84:87], v[132:135], v[224:227], v[84:87]
	v_mfma_f32_16x16x32_bf16 v[76:79], v[140:143], v[224:227], v[76:79]
	v_mfma_f32_16x16x32_bf16 v[128:131], v[136:139], v[194:197], v[128:131]
	v_mfma_f32_16x16x32_bf16 v[124:127], v[144:147], v[194:197], v[124:127]
	v_mfma_f32_16x16x32_bf16 v[120:123], v[136:139], v[212:215], v[120:123]
	v_mfma_f32_16x16x32_bf16 v[112:115], v[144:147], v[212:215], v[112:115]
	v_mfma_f32_16x16x32_bf16 v[100:103], v[136:139], v[220:223], v[100:103]
	v_mfma_f32_16x16x32_bf16 v[92:95], v[144:147], v[220:223], v[92:95]
	v_mfma_f32_16x16x32_bf16 v[84:87], v[136:139], v[228:231], v[84:87]
	v_mfma_f32_16x16x32_bf16 v[76:79], v[144:147], v[228:231], v[76:79]
	s_setprio 0
	s_setprio 1
	v_mfma_f32_16x16x32_bf16 v[116:119], v[148:151], v[190:193], v[116:119]
	v_mfma_f32_16x16x32_bf16 v[108:111], v[164:167], v[190:193], v[108:111]
	v_mfma_f32_16x16x32_bf16 v[104:107], v[148:151], v[198:201], v[104:107]
	v_mfma_f32_16x16x32_bf16 v[96:99], v[164:167], v[198:201], v[96:99]
	v_mfma_f32_16x16x32_bf16 v[88:91], v[148:151], v[216:219], v[88:91]
	v_mfma_f32_16x16x32_bf16 v[80:83], v[164:167], v[216:219], v[80:83]
	v_mfma_f32_16x16x32_bf16 v[72:75], v[148:151], v[224:227], v[72:75]
	v_mfma_f32_16x16x32_bf16 v[68:71], v[164:167], v[224:227], v[68:71]
	v_mfma_f32_16x16x32_bf16 v[116:119], v[160:163], v[194:197], v[116:119]
	v_mfma_f32_16x16x32_bf16 v[108:111], v[182:185], v[194:197], v[108:111]
	v_mfma_f32_16x16x32_bf16 v[104:107], v[160:163], v[212:215], v[104:107]
	v_mfma_f32_16x16x32_bf16 v[96:99], v[182:185], v[212:215], v[96:99]
	v_mfma_f32_16x16x32_bf16 v[88:91], v[160:163], v[220:223], v[88:91]
	v_mfma_f32_16x16x32_bf16 v[80:83], v[182:185], v[220:223], v[80:83]
	v_mfma_f32_16x16x32_bf16 v[72:75], v[160:163], v[228:231], v[72:75]
	v_mfma_f32_16x16x32_bf16 v[68:71], v[182:185], v[228:231], v[68:71]
	s_setprio 0
	s_barrier
	s_add_i32 s24, s74, s48
	s_add_u32 s98, s38, s60
	s_addc_u32 s99, s39, s61
	s_mov_b32 m0, s24
	ds_read_b128 v[190:193], v188 offset:16384
	ds_read_b128 v[194:197], v188 offset:17408
	ds_read_b128 v[198:201], v188 offset:18432
	ds_read_b128 v[212:215], v188 offset:19456
	ds_read_b128 v[216:219], v188 offset:20480
	ds_read_b128 v[220:223], v188 offset:21504
	ds_read_b128 v[224:227], v188 offset:22528
	ds_read_b128 v[228:231], v188 offset:23552
	global_load_lds_dwordx4 v2, s[38:39]
	s_add_i32 m0, s24, 0x2000
	s_add_u32 s24, s38, 0x20000
	s_addc_u32 s25, s39, 0
	s_add_i32 s74, s75, s48
	global_load_lds_dwordx4 v0, s[38:39]
	s_mov_b32 m0, s74
	s_add_u32 s100, s42, s60
	s_addc_u32 s101, s43, s61
	s_nop 0
	global_load_lds_dwordx4 v2, s[24:25]
	s_add_i32 m0, s74, 0x2000
	s_nop 0
	global_load_lds_dwordx4 v0, s[24:25]
	s_mov_b32 m0, s49
	s_nop 0
	global_load_lds_dwordx4 v154, s[42:43]
	s_mov_b32 m0, s50
	s_nop 0
	global_load_lds_dwordx4 v152, s[42:43]
	s_waitcnt vmcnt(8)
	s_waitcnt lgkmcnt(0)
	s_barrier
	s_setprio 1
	s_waitcnt lgkmcnt(0)
	v_mfma_f32_16x16x32_bf16 v[64:67], v[132:135], v[190:193], v[64:67]
	v_mfma_f32_16x16x32_bf16 v[60:63], v[140:143], v[190:193], v[60:63]
	v_mfma_f32_16x16x32_bf16 v[52:55], v[132:135], v[198:201], v[52:55]
	v_mfma_f32_16x16x32_bf16 v[44:47], v[140:143], v[198:201], v[44:47]
	v_mfma_f32_16x16x32_bf16 v[36:39], v[132:135], v[216:219], v[36:39]
	v_mfma_f32_16x16x32_bf16 v[28:31], v[140:143], v[216:219], v[28:31]
	v_mfma_f32_16x16x32_bf16 v[20:23], v[132:135], v[224:227], v[20:23]
	v_mfma_f32_16x16x32_bf16 v[12:15], v[140:143], v[224:227], v[12:15]
	v_mfma_f32_16x16x32_bf16 v[64:67], v[136:139], v[194:197], v[64:67]
	v_mfma_f32_16x16x32_bf16 v[60:63], v[144:147], v[194:197], v[60:63]
	v_mfma_f32_16x16x32_bf16 v[52:55], v[136:139], v[212:215], v[52:55]
	v_mfma_f32_16x16x32_bf16 v[44:47], v[144:147], v[212:215], v[44:47]
	v_mfma_f32_16x16x32_bf16 v[36:39], v[136:139], v[220:223], v[36:39]
	v_mfma_f32_16x16x32_bf16 v[28:31], v[144:147], v[220:223], v[28:31]
	v_mfma_f32_16x16x32_bf16 v[20:23], v[136:139], v[228:231], v[20:23]
	v_mfma_f32_16x16x32_bf16 v[12:15], v[144:147], v[228:231], v[12:15]
	s_setprio 0
	s_setprio 1
	v_mfma_f32_16x16x32_bf16 v[56:59], v[148:151], v[190:193], v[56:59]
	v_mfma_f32_16x16x32_bf16 v[48:51], v[164:167], v[190:193], v[48:51]
	v_mfma_f32_16x16x32_bf16 v[40:43], v[148:151], v[198:201], v[40:43]
	v_mfma_f32_16x16x32_bf16 v[32:35], v[164:167], v[198:201], v[32:35]
	v_mfma_f32_16x16x32_bf16 v[24:27], v[148:151], v[216:219], v[24:27]
	v_mfma_f32_16x16x32_bf16 v[16:19], v[164:167], v[216:219], v[16:19]
	v_mfma_f32_16x16x32_bf16 v[8:11], v[148:151], v[224:227], v[8:11]
	v_mfma_f32_16x16x32_bf16 v[4:7], v[164:167], v[224:227], v[4:7]
	v_mfma_f32_16x16x32_bf16 v[56:59], v[160:163], v[194:197], v[56:59]
	v_mfma_f32_16x16x32_bf16 v[48:51], v[182:185], v[194:197], v[48:51]
	v_mfma_f32_16x16x32_bf16 v[40:43], v[160:163], v[212:215], v[40:43]
	v_mfma_f32_16x16x32_bf16 v[32:35], v[182:185], v[212:215], v[32:35]
	v_mfma_f32_16x16x32_bf16 v[24:27], v[160:163], v[220:223], v[24:27]
	v_mfma_f32_16x16x32_bf16 v[16:19], v[182:185], v[220:223], v[16:19]
	v_mfma_f32_16x16x32_bf16 v[8:11], v[160:163], v[228:231], v[8:11]
	v_mfma_f32_16x16x32_bf16 v[4:7], v[182:185], v[228:231], v[4:7]
	s_setprio 0
	s_barrier
; #define PG8_STAGE(bufoff, gbase, voff) do { _Pragma("unroll") for (int _i = 0; _i < 2; ++_i) \
;         __builtin_amdgcn_global_load_lds((const unsigned*)((const char*)(gbase) + (voff)[_i]), (PG8_LAS unsigned*)(lds + (bufoff) + ldsw + _i * 8192), 16, 0, 0); } while (0)
; #define PG8_LDA(dst, b, h) do { _Pragma("unroll") for (int m = 0; m < 4; ++m) _Pragma("unroll") for (int k = 0; k < 2; ++k) dst[m][k] = *(const PG8_LAS bf16x8*)(lds + PG8_SA(b, h) + aoff + m * 2048 + k * 1024); } while (0)
; #define PG8_LDB(dst, b, h) do { _Pragma("unroll") for (int n = 0; n < 2; ++n) _Pragma("unroll") for (int k = 0; k < 2; ++k) dst[n][k] = *(const PG8_LAS bf16x8*)(lds + PG8_SB(b, h) + boff + n * 2048 + k * 1024); } while (0)
; #define PG8_MMA(ai, bj, At, Bt) do { __builtin_amdgcn_s_setprio(1); _Pragma("unroll") for (int m = 0; m < 4; ++m) _Pragma("unroll") for (int n = 0; n < 2; ++n) _Pragma("unroll") for (int k = 0; k < 2; ++k) \
;         acc[ai][bj][m][n] = __builtin_amdgcn_mfma_f32_16x16x32_bf16(Bt[n][k], At[m][k], acc[ai][bj][m][n], 0, 0, 0); __builtin_amdgcn_s_setprio(0); } while (0)
; #define PG8_WAIT_V(n) asm volatile("s_waitcnt vmcnt(" #n ")" ::: "memory")
; #define PG8_WAIT_L(n) asm volatile("s_waitcnt lgkmcnt(" #n ")" ::: "memory")
; template <class Epi, class Sched, bool ALIGN_EPI = false, bool SP2 = false>
; __device__ __forceinline__ void gemm_phase(PG8_LAS unsigned char* lds, const Gemm g, const Sched& S, const Epi& E, int wave_s) {
;     ...
;         for (int t = 0; t < nt; t += 2) {
;             const bool last = (t == nt - 2);
;             const char* a1 = cA + (size_t)(t + 1) * kstep;
;             const char* a2 = last ? nA : cA + (size_t)(t + 2) * kstep; const char* b2 = last ? nB : cB + (size_t)(t + 2) * kstep;
;             const char* a3 = a2 + kstep; const char* b3 = b2 + kstep;
;             if (last && has_next) S.a_ready(nxt);
;     ...
;             PG8_LDB(B0, 1, 0); PG8_LDB(B1, 1, 1); PG8_SCHED; PG8_LDA(At, 1, 0); PG8_STAGE(PG8_SA(0, 1), a2 + hstepA, voffA);
;             PG8_WAIT_V(8); PG8_WAIT_L(0); PG8_BAR; PG8_MMA(0, 0, At, B0); PG8_MMA(0, 1, At, B1); PG8_BAR; PG8_SCHED;
;             PG8_LDA(At, 1, 1); PG8_STAGE(PG8_SB(1, 0), b3, voffB); PG8_STAGE(PG8_SB(1, 1), b3 + hstepB, voffB); PG8_STAGE(PG8_SA(1, 0), a3, voffA);
;             PG8_WAIT_V(8); PG8_WAIT_L(0); PG8_BAR; PG8_MMA(1, 0, At, B0); PG8_MMA(1, 1, At, B1); PG8_BAR; PG8_SCHED;
	s_add_i32 s74, 0, 0x18000
	s_add_i32 s75, 0, 0x1c000
	ds_read_b128 v[132:135], v255 offset:32768
	ds_read_b128 v[136:139], v255 offset:33792
	ds_read_b128 v[140:143], v255 offset:34816
	ds_read_b128 v[144:147], v255 offset:35840
	ds_read_b128 v[148:151], v255 offset:49152
	ds_read_b128 v[160:163], v255 offset:50176
	ds_read_b128 v[164:167], v255 offset:51200
	ds_read_b128 v[182:185], v255 offset:52224
	s_add_u32 s24, s42, 0x4b0000
	s_addc_u32 s25, s43, 0
	s_mov_b32 m0, s51
	ds_read_b128 v[190:193], v188 offset:32768
	ds_read_b128 v[194:197], v188 offset:33792
	ds_read_b128 v[198:201], v188 offset:34816
	ds_read_b128 v[212:215], v188 offset:35840
	ds_read_b128 v[216:219], v188 offset:36864
	ds_read_b128 v[220:223], v188 offset:37888
	ds_read_b128 v[224:227], v188 offset:38912
	ds_read_b128 v[228:231], v188 offset:39936
	global_load_lds_dwordx4 v154, s[24:25]
	s_mov_b32 m0, s52
	s_nop 0
	global_load_lds_dwordx4 v152, s[24:25]
	s_waitcnt vmcnt(8)
	s_waitcnt lgkmcnt(0)
	s_barrier
	s_setprio 1
	s_waitcnt lgkmcnt(0)
	v_mfma_f32_16x16x32_bf16 v[128:131], v[132:135], v[190:193], v[128:131]
	v_mfma_f32_16x16x32_bf16 v[124:127], v[140:143], v[190:193], v[124:127]
	v_mfma_f32_16x16x32_bf16 v[120:123], v[132:135], v[198:201], v[120:123]
	v_mfma_f32_16x16x32_bf16 v[112:115], v[140:143], v[198:201], v[112:115]
	v_mfma_f32_16x16x32_bf16 v[100:103], v[132:135], v[216:219], v[100:103]
	v_mfma_f32_16x16x32_bf16 v[92:95], v[140:143], v[216:219], v[92:95]
	v_mfma_f32_16x16x32_bf16 v[84:87], v[132:135], v[224:227], v[84:87]
	v_mfma_f32_16x16x32_bf16 v[76:79], v[140:143], v[224:227], v[76:79]
	v_mfma_f32_16x16x32_bf16 v[128:131], v[136:139], v[194:197], v[128:131]
	v_mfma_f32_16x16x32_bf16 v[124:127], v[144:147], v[194:197], v[124:127]
	v_mfma_f32_16x16x32_bf16 v[120:123], v[136:139], v[212:215], v[120:123]
	v_mfma_f32_16x16x32_bf16 v[112:115], v[144:147], v[212:215], v[112:115]
	v_mfma_f32_16x16x32_bf16 v[100:103], v[136:139], v[220:223], v[100:103]
	v_mfma_f32_16x16x32_bf16 v[92:95], v[144:147], v[220:223], v[92:95]
	v_mfma_f32_16x16x32_bf16 v[84:87], v[136:139], v[228:231], v[84:87]
	v_mfma_f32_16x16x32_bf16 v[76:79], v[144:147], v[228:231], v[76:79]
	s_setprio 0
	s_setprio 1
	v_mfma_f32_16x16x32_bf16 v[116:119], v[148:151], v[190:193], v[116:119]
	v_mfma_f32_16x16x32_bf16 v[108:111], v[164:167], v[190:193], v[108:111]
	v_mfma_f32_16x16x32_bf16 v[104:107], v[148:151], v[198:201], v[104:107]
	v_mfma_f32_16x16x32_bf16 v[96:99], v[164:167], v[198:201], v[96:99]
	v_mfma_f32_16x16x32_bf16 v[88:91], v[148:151], v[216:219], v[88:91]
	v_mfma_f32_16x16x32_bf16 v[80:83], v[164:167], v[216:219], v[80:83]
	v_mfma_f32_16x16x32_bf16 v[72:75], v[148:151], v[224:227], v[72:75]
	v_mfma_f32_16x16x32_bf16 v[68:71], v[164:167], v[224:227], v[68:71]
	v_mfma_f32_16x16x32_bf16 v[116:119], v[160:163], v[194:197], v[116:119]
	v_mfma_f32_16x16x32_bf16 v[108:111], v[182:185], v[194:197], v[108:111]
	v_mfma_f32_16x16x32_bf16 v[104:107], v[160:163], v[212:215], v[104:107]
	v_mfma_f32_16x16x32_bf16 v[96:99], v[182:185], v[212:215], v[96:99]
	v_mfma_f32_16x16x32_bf16 v[88:91], v[160:163], v[220:223], v[88:91]
	v_mfma_f32_16x16x32_bf16 v[80:83], v[182:185], v[220:223], v[80:83]
	v_mfma_f32_16x16x32_bf16 v[72:75], v[160:163], v[228:231], v[72:75]
	v_mfma_f32_16x16x32_bf16 v[68:71], v[182:185], v[228:231], v[68:71]
	s_setprio 0
	s_barrier
	s_add_i32 s24, s74, s48
	s_mov_b32 m0, s24
	ds_read_b128 v[190:193], v188 offset:49152
	ds_read_b128 v[194:197], v188 offset:50176
	ds_read_b128 v[198:201], v188 offset:51200
	ds_read_b128 v[212:215], v188 offset:52224
	ds_read_b128 v[216:219], v188 offset:53248
	ds_read_b128 v[220:223], v188 offset:54272
	ds_read_b128 v[224:227], v188 offset:55296
	ds_read_b128 v[228:231], v188 offset:56320
	global_load_lds_dwordx4 v2, s[98:99]
	s_add_i32 m0, s24, 0x2000
	s_add_u32 s24, s38, 0x20080
	s_addc_u32 s25, s39, 0
	s_add_i32 s38, s75, s48
	global_load_lds_dwordx4 v0, s[98:99]
	s_mov_b32 m0, s38
	s_nop 0
	global_load_lds_dwordx4 v2, s[24:25]
	s_add_i32 m0, s38, 0x2000
	s_nop 0
	global_load_lds_dwordx4 v0, s[24:25]
	s_mov_b32 m0, s53
	s_nop 0
	global_load_lds_dwordx4 v154, s[100:101]
	s_mov_b32 m0, s54
	s_nop 0
	global_load_lds_dwordx4 v152, s[100:101]
	s_waitcnt vmcnt(8)
	s_waitcnt lgkmcnt(0)
	s_barrier
	s_setprio 1
	s_waitcnt lgkmcnt(0)
	v_mfma_f32_16x16x32_bf16 v[64:67], v[132:135], v[190:193], v[64:67]
	v_mfma_f32_16x16x32_bf16 v[60:63], v[140:143], v[190:193], v[60:63]
	v_mfma_f32_16x16x32_bf16 v[52:55], v[132:135], v[198:201], v[52:55]
	v_mfma_f32_16x16x32_bf16 v[44:47], v[140:143], v[198:201], v[44:47]
	v_mfma_f32_16x16x32_bf16 v[36:39], v[132:135], v[216:219], v[36:39]
	v_mfma_f32_16x16x32_bf16 v[28:31], v[140:143], v[216:219], v[28:31]
	v_mfma_f32_16x16x32_bf16 v[20:23], v[132:135], v[224:227], v[20:23]
	v_mfma_f32_16x16x32_bf16 v[12:15], v[140:143], v[224:227], v[12:15]
	v_mfma_f32_16x16x32_bf16 v[64:67], v[136:139], v[194:197], v[64:67]
	v_mfma_f32_16x16x32_bf16 v[60:63], v[144:147], v[194:197], v[60:63]
	v_mfma_f32_16x16x32_bf16 v[52:55], v[136:139], v[212:215], v[52:55]
	v_mfma_f32_16x16x32_bf16 v[44:47], v[144:147], v[212:215], v[44:47]
	v_mfma_f32_16x16x32_bf16 v[36:39], v[136:139], v[220:223], v[36:39]
	v_mfma_f32_16x16x32_bf16 v[28:31], v[144:147], v[220:223], v[28:31]
	v_mfma_f32_16x16x32_bf16 v[20:23], v[136:139], v[228:231], v[20:23]
	v_mfma_f32_16x16x32_bf16 v[12:15], v[144:147], v[228:231], v[12:15]
	s_setprio 0
	s_setprio 1
	v_mfma_f32_16x16x32_bf16 v[56:59], v[148:151], v[190:193], v[56:59]
	v_mfma_f32_16x16x32_bf16 v[48:51], v[164:167], v[190:193], v[48:51]
	v_mfma_f32_16x16x32_bf16 v[40:43], v[148:151], v[198:201], v[40:43]
	v_mfma_f32_16x16x32_bf16 v[32:35], v[164:167], v[198:201], v[32:35]
	v_mfma_f32_16x16x32_bf16 v[24:27], v[148:151], v[216:219], v[24:27]
	v_mfma_f32_16x16x32_bf16 v[16:19], v[164:167], v[216:219], v[16:19]
	v_mfma_f32_16x16x32_bf16 v[8:11], v[148:151], v[224:227], v[8:11]
	v_mfma_f32_16x16x32_bf16 v[4:7], v[164:167], v[224:227], v[4:7]
	v_mfma_f32_16x16x32_bf16 v[56:59], v[160:163], v[194:197], v[56:59]
	v_mfma_f32_16x16x32_bf16 v[48:51], v[182:185], v[194:197], v[48:51]
	v_mfma_f32_16x16x32_bf16 v[40:43], v[160:163], v[212:215], v[40:43]
	v_mfma_f32_16x16x32_bf16 v[32:35], v[182:185], v[212:215], v[32:35]
	v_mfma_f32_16x16x32_bf16 v[24:27], v[160:163], v[220:223], v[24:27]
	v_mfma_f32_16x16x32_bf16 v[16:19], v[182:185], v[220:223], v[16:19]
	v_mfma_f32_16x16x32_bf16 v[8:11], v[160:163], v[228:231], v[8:11]
	v_mfma_f32_16x16x32_bf16 v[4:7], v[182:185], v[228:231], v[4:7]
	s_setprio 0
	s_barrier
	s_add_i32 s67, s67, 2
	s_add_u32 s59, s59, 0x100
	s_addc_u32 s66, s66, 0
	s_cmp_gt_u32 s67, 5
	s_mov_b64 s[24:25], s[26:27]
	s_cbranch_scc0 .LBB0_568
	s_and_b64 vcc, exec, s[16:17]
	s_cbranch_vccz .LBB0_571
	s_barrier

; #define PG8_STAGE(bufoff, gbase, voff) do { _Pragma("unroll") for (int _i = 0; _i < 2; ++_i) \
;         __builtin_amdgcn_global_load_lds((const unsigned*)((const char*)(gbase) + (voff)[_i]), (PG8_LAS unsigned*)(lds + (bufoff) + ldsw + _i * 8192), 16, 0, 0); } while (0)
; #define PG8_LDA(dst, b, h) do { _Pragma("unroll") for (int m = 0; m < 4; ++m) _Pragma("unroll") for (int k = 0; k < 2; ++k) dst[m][k] = *(const PG8_LAS bf16x8*)(lds + PG8_SA(b, h) + aoff + m * 2048 + k * 1024); } while (0)
; #define PG8_LDB(dst, b, h) do { _Pragma("unroll") for (int n = 0; n < 2; ++n) _Pragma("unroll") for (int k = 0; k < 2; ++k) dst[n][k] = *(const PG8_LAS bf16x8*)(lds + PG8_SB(b, h) + boff + n * 2048 + k * 1024); } while (0)
; #define PG8_WAIT_V(n) asm volatile("s_waitcnt vmcnt(" #n ")" ::: "memory")
; #define PG8_WAIT_L(n) asm volatile("s_waitcnt lgkmcnt(" #n ")" ::: "memory")
; #define PG8_BAR __builtin_amdgcn_s_barrier()
; template <class Epi, class Sched, bool ALIGN_EPI = false, bool SP2 = false>
; __device__ __forceinline__ void gemm_phase(PG8_LAS unsigned char* lds, const Gemm g, const Sched& S, const Epi& E, int wave_s) {
;     ...
;         const bool has_next = S.next(ui + 1, nxt);
;         const char* nA = has_next ? (const char*)g.A + (size_t)nxt.pm * tstepA : cA; const char* nB = has_next ? (const char*)g.Bt + (size_t)nxt.pn * tstepB : cB;
;         for (int t = 0; t < nt; t += 2) {
;             const bool last = (t == nt - 2);
;             const char* a1 = cA + (size_t)(t + 1) * kstep;
;             const char* a2 = last ? nA : cA + (size_t)(t + 2) * kstep; const char* b2 = last ? nB : cB + (size_t)(t + 2) * kstep;
;             const char* a3 = a2 + kstep; const char* b3 = b2 + kstep;
;             if (last && has_next) S.a_ready(nxt);
;             if constexpr (SP2) {
;             PG8_LDB(B0, 0, 0); PG8_LDB(B1, 0, 1); PG8_SCHED; PG8_LDA(At, 0, 0); PG8_STAGE(PG8_SA(1, 1), a1 + hstepA, voffA);
;             PG8_WAIT_V(8); PG8_WAIT_L(0); PG8_BAR; PG8_MMA(0, 0, At, B0); PG8_MMA(0, 1, At, B1); PG8_BAR; PG8_SCHED;
;     ...
;         for (int a = 0; a < 2; ++a)
; #pragma unroll
;             for (int b = 0; b < 2; ++b)
; #pragma unroll
;                 for (int m = 0; m < 4; ++m)
; #pragma unroll
;                     for (int n = 0; n < 2; ++n) acc[a][b][m][n] = (f32x4){0.f, 0.f, 0.f, 0.f};
;         cur = nxt; cA = nA; cB = nB; ++ui;
.LBB0_589:
	s_ashr_i32 s47, s46, 31
	s_lshl_b64 s[0:1], s[46:47], 21
	s_add_u32 s50, s22, s0
	s_addc_u32 s51, s23, s1
	s_and_b64 s[0:1], s[38:39], exec
	s_cselect_b32 s38, s51, s7
	s_cselect_b32 s39, s50, s6
	s_add_u32 s47, s6, 0x100
	v_mov_b32_e32 v4, 0
	s_addc_u32 s56, s7, 0
	s_mov_b32 s57, -2
	v_mov_b32_e32 v5, v4
	v_mov_b32_e32 v6, v4
	v_mov_b32_e32 v7, v4
	v_mov_b32_e32 v8, v4
	v_mov_b32_e32 v9, v4
	v_mov_b32_e32 v10, v4
	v_mov_b32_e32 v11, v4
	v_mov_b32_e32 v20, v4
	v_mov_b32_e32 v21, v4
	v_mov_b32_e32 v22, v4
	v_mov_b32_e32 v23, v4
	v_mov_b32_e32 v24, v4
	v_mov_b32_e32 v25, v4
	v_mov_b32_e32 v26, v4
	v_mov_b32_e32 v27, v4
	v_mov_b32_e32 v36, v4
	v_mov_b32_e32 v37, v4
	v_mov_b32_e32 v38, v4
	v_mov_b32_e32 v39, v4
	v_mov_b32_e32 v40, v4
	v_mov_b32_e32 v41, v4
	v_mov_b32_e32 v42, v4
	v_mov_b32_e32 v43, v4
	v_mov_b32_e32 v52, v4
	v_mov_b32_e32 v53, v4
	v_mov_b32_e32 v54, v4
	v_mov_b32_e32 v55, v4
	v_mov_b32_e32 v56, v4
	v_mov_b32_e32 v57, v4
	v_mov_b32_e32 v58, v4
	v_mov_b32_e32 v59, v4
	v_mov_b32_e32 v12, v4
	v_mov_b32_e32 v13, v4
	v_mov_b32_e32 v14, v4
	v_mov_b32_e32 v15, v4
	v_mov_b32_e32 v16, v4
	v_mov_b32_e32 v17, v4
	v_mov_b32_e32 v18, v4
	v_mov_b32_e32 v19, v4
	v_mov_b32_e32 v28, v4
	v_mov_b32_e32 v29, v4
	v_mov_b32_e32 v30, v4
	v_mov_b32_e32 v31, v4
	v_mov_b32_e32 v32, v4
	v_mov_b32_e32 v33, v4
	v_mov_b32_e32 v34, v4
	v_mov_b32_e32 v35, v4
	v_mov_b32_e32 v44, v4
	v_mov_b32_e32 v45, v4
	v_mov_b32_e32 v46, v4
	v_mov_b32_e32 v47, v4
	v_mov_b32_e32 v48, v4
	v_mov_b32_e32 v49, v4
	v_mov_b32_e32 v50, v4
	v_mov_b32_e32 v51, v4
	v_mov_b32_e32 v60, v4
	v_mov_b32_e32 v61, v4
	v_mov_b32_e32 v62, v4
	v_mov_b32_e32 v63, v4
	v_mov_b32_e32 v64, v4
	v_mov_b32_e32 v65, v4
	v_mov_b32_e32 v66, v4
	v_mov_b32_e32 v67, v4
	v_mov_b32_e32 v68, v4
	v_mov_b32_e32 v69, v4
	v_mov_b32_e32 v70, v4
	v_mov_b32_e32 v71, v4
	v_mov_b32_e32 v72, v4
	v_mov_b32_e32 v73, v4
	v_mov_b32_e32 v74, v4
	v_mov_b32_e32 v75, v4
	v_mov_b32_e32 v84, v4
	v_mov_b32_e32 v85, v4
	v_mov_b32_e32 v86, v4
	v_mov_b32_e32 v87, v4
	v_mov_b32_e32 v88, v4
	v_mov_b32_e32 v89, v4
	v_mov_b32_e32 v90, v4
	v_mov_b32_e32 v91, v4
	v_mov_b32_e32 v104, v4
	v_mov_b32_e32 v105, v4
	v_mov_b32_e32 v106, v4
	v_mov_b32_e32 v107, v4
	s_waitcnt vmcnt(0) lgkmcnt(0)
	v_mov_b32_e32 v108, v4
	v_mov_b32_e32 v109, v4
	v_mov_b32_e32 v110, v4
	v_mov_b32_e32 v111, v4
	v_mov_b32_e32 v128, v4
	v_mov_b32_e32 v129, v4
	v_mov_b32_e32 v130, v4
	v_mov_b32_e32 v131, v4
	v_mov_b32_e32 v132, v4
	v_mov_b32_e32 v133, v4
	v_mov_b32_e32 v134, v4
	v_mov_b32_e32 v135, v4
	v_mov_b32_e32 v76, v4
	v_mov_b32_e32 v77, v4
	v_mov_b32_e32 v78, v4
	v_mov_b32_e32 v79, v4
	v_mov_b32_e32 v80, v4
	v_mov_b32_e32 v81, v4
	v_mov_b32_e32 v82, v4
	v_mov_b32_e32 v83, v4
	v_mov_b32_e32 v92, v4
	v_mov_b32_e32 v93, v4
	v_mov_b32_e32 v94, v4
	v_mov_b32_e32 v95, v4
	v_mov_b32_e32 v96, v4
	v_mov_b32_e32 v97, v4
	v_mov_b32_e32 v98, v4
	v_mov_b32_e32 v99, v4
	v_mov_b32_e32 v112, v4
	v_mov_b32_e32 v113, v4
	v_mov_b32_e32 v114, v4
	v_mov_b32_e32 v115, v4
	v_mov_b32_e32 v116, v4
	v_mov_b32_e32 v117, v4
	v_mov_b32_e32 v118, v4
	v_mov_b32_e32 v119, v4
	v_mov_b32_e32 v136, v4
	v_mov_b32_e32 v137, v4
	v_mov_b32_e32 v138, v4
	v_mov_b32_e32 v139, v4
	v_mov_b32_e32 v140, v4
	v_mov_b32_e32 v141, v4
	v_mov_b32_e32 v142, v4
	v_mov_b32_e32 v143, v4
	v_add_u32_e32 v255, 0x10000, v194
.LBB0_590:
	s_add_u32 s0, s4, 0x100
	s_addc_u32 s1, s5, 0
	s_add_i32 s58, 0, 0x10000
	s_cmp_eq_u32 s57, 60
	s_cselect_b32 s17, s49, s1
	s_cselect_b32 s16, s48, s0
	s_cselect_b32 s7, s38, s56
	s_cselect_b32 s6, s39, s47
	s_add_i32 s59, 0, 0x14000
	ds_read_b128 v[100:103], v255
	ds_read_b128 v[120:123], v255 offset:1024
	ds_read_b128 v[124:127], v255 offset:2048
	ds_read_b128 v[144:147], v255 offset:3072
	ds_read_b128 v[148:151], v255 offset:16384
	ds_read_b128 v[152:155], v255 offset:17408
	ds_read_b128 v[156:159], v255 offset:18432
	ds_read_b128 v[182:185], v255 offset:19456
	v_lshl_add_u64 v[232:233], s[4:5], 0, v[166:167]
	s_add_i32 m0, s25, 0xc000
	ds_read_b128 v[186:189], v196
	ds_read_b128 v[190:193], v196 offset:1024
	ds_read_b128 v[198:201], v196 offset:2048
	ds_read_b128 v[212:215], v196 offset:3072
	ds_read_b128 v[216:219], v196 offset:4096
	ds_read_b128 v[220:223], v196 offset:5120
	ds_read_b128 v[224:227], v196 offset:6144
	ds_read_b128 v[228:231], v196 offset:7168
	global_load_lds_dwordx4 v[232:233], off
	v_lshl_add_u64 v[232:233], s[4:5], 0, v[164:165]
	s_add_i32 m0, s25, 0xe000
	s_nop 0
	global_load_lds_dwordx4 v[232:233], off
	s_waitcnt vmcnt(8)
	s_waitcnt lgkmcnt(0)
	s_barrier
; #define PG8_STAGE(bufoff, gbase, voff) do { _Pragma("unroll") for (int _i = 0; _i < 2; ++_i) \
;         __builtin_amdgcn_global_load_lds((const unsigned*)((const char*)(gbase) + (voff)[_i]), (PG8_LAS unsigned*)(lds + (bufoff) + ldsw + _i * 8192), 16, 0, 0); } while (0)
; #define PG8_LDA(dst, b, h) do { _Pragma("unroll") for (int m = 0; m < 4; ++m) _Pragma("unroll") for (int k = 0; k < 2; ++k) dst[m][k] = *(const PG8_LAS bf16x8*)(lds + PG8_SA(b, h) + aoff + m * 2048 + k * 1024); } while (0)
; #define PG8_MMA(ai, bj, At, Bt) do { __builtin_amdgcn_s_setprio(1); _Pragma("unroll") for (int m = 0; m < 4; ++m) _Pragma("unroll") for (int n = 0; n < 2; ++n) _Pragma("unroll") for (int k = 0; k < 2; ++k) \
;         acc[ai][bj][m][n] = __builtin_amdgcn_mfma_f32_16x16x32_bf16(Bt[n][k], At[m][k], acc[ai][bj][m][n], 0, 0, 0); __builtin_amdgcn_s_setprio(0); } while (0)
; #define PG8_WAIT_V(n) asm volatile("s_waitcnt vmcnt(" #n ")" ::: "memory")
; #define PG8_WAIT_L(n) asm volatile("s_waitcnt lgkmcnt(" #n ")" ::: "memory")
; #define PG8_BAR __builtin_amdgcn_s_barrier()
; #define PG8_SCHED __builtin_amdgcn_sched_barrier(0)
; template <class Epi, class Sched, bool ALIGN_EPI = false, bool SP2 = false>
; __device__ __forceinline__ void gemm_phase(PG8_LAS unsigned char* lds, const Gemm g, const Sched& S, const Epi& E, int wave_s) {
;     ...
;             PG8_WAIT_V(8); PG8_WAIT_L(0); PG8_BAR; PG8_MMA(0, 0, At, B0); PG8_MMA(0, 1, At, B1); PG8_BAR; PG8_SCHED;
;             PG8_LDA(At, 0, 1); PG8_STAGE(PG8_SB(0, 0), b2, voffB); PG8_STAGE(PG8_SB(0, 1), b2 + hstepB, voffB); PG8_STAGE(PG8_SA(0, 0), a2, voffA);
;             PG8_WAIT_V(8); PG8_WAIT_L(0); PG8_BAR; PG8_MMA(1, 0, At, B0); PG8_MMA(1, 1, At, B1); PG8_BAR; PG8_SCHED;
	s_setprio 1
	s_waitcnt lgkmcnt(0)
	v_mfma_f32_16x16x32_bf16 v[140:143], v[100:103], v[186:189], v[140:143]
	v_mfma_f32_16x16x32_bf16 v[136:139], v[124:127], v[186:189], v[136:139]
	v_mfma_f32_16x16x32_bf16 v[116:119], v[100:103], v[198:201], v[116:119]
	v_mfma_f32_16x16x32_bf16 v[112:115], v[124:127], v[198:201], v[112:115]
	v_mfma_f32_16x16x32_bf16 v[96:99], v[100:103], v[216:219], v[96:99]
	v_mfma_f32_16x16x32_bf16 v[92:95], v[124:127], v[216:219], v[92:95]
	v_mfma_f32_16x16x32_bf16 v[80:83], v[100:103], v[224:227], v[80:83]
	v_mfma_f32_16x16x32_bf16 v[76:79], v[124:127], v[224:227], v[76:79]
	v_mfma_f32_16x16x32_bf16 v[140:143], v[120:123], v[190:193], v[140:143]
	v_mfma_f32_16x16x32_bf16 v[136:139], v[144:147], v[190:193], v[136:139]
	v_mfma_f32_16x16x32_bf16 v[116:119], v[120:123], v[212:215], v[116:119]
	v_mfma_f32_16x16x32_bf16 v[112:115], v[144:147], v[212:215], v[112:115]
	v_mfma_f32_16x16x32_bf16 v[96:99], v[120:123], v[220:223], v[96:99]
	v_mfma_f32_16x16x32_bf16 v[92:95], v[144:147], v[220:223], v[92:95]
	v_mfma_f32_16x16x32_bf16 v[80:83], v[120:123], v[228:231], v[80:83]
	v_mfma_f32_16x16x32_bf16 v[76:79], v[144:147], v[228:231], v[76:79]
	s_setprio 0
	s_setprio 1
	v_mfma_f32_16x16x32_bf16 v[132:135], v[148:151], v[186:189], v[132:135]
	v_mfma_f32_16x16x32_bf16 v[128:131], v[156:159], v[186:189], v[128:131]
	v_mfma_f32_16x16x32_bf16 v[108:111], v[148:151], v[198:201], v[108:111]
	v_mfma_f32_16x16x32_bf16 v[104:107], v[156:159], v[198:201], v[104:107]
	v_mfma_f32_16x16x32_bf16 v[88:91], v[148:151], v[216:219], v[88:91]
	v_mfma_f32_16x16x32_bf16 v[84:87], v[156:159], v[216:219], v[84:87]
	v_mfma_f32_16x16x32_bf16 v[72:75], v[148:151], v[224:227], v[72:75]
	v_mfma_f32_16x16x32_bf16 v[68:71], v[156:159], v[224:227], v[68:71]
	v_mfma_f32_16x16x32_bf16 v[132:135], v[152:155], v[190:193], v[132:135]
	v_mfma_f32_16x16x32_bf16 v[128:131], v[182:185], v[190:193], v[128:131]
	v_mfma_f32_16x16x32_bf16 v[108:111], v[152:155], v[212:215], v[108:111]
	v_mfma_f32_16x16x32_bf16 v[104:107], v[182:185], v[212:215], v[104:107]
	v_mfma_f32_16x16x32_bf16 v[88:91], v[152:155], v[220:223], v[88:91]
	v_mfma_f32_16x16x32_bf16 v[84:87], v[182:185], v[220:223], v[84:87]
	v_mfma_f32_16x16x32_bf16 v[72:75], v[152:155], v[228:231], v[72:75]
	v_mfma_f32_16x16x32_bf16 v[68:71], v[182:185], v[228:231], v[68:71]
	s_setprio 0
	s_barrier
	s_add_i32 s4, s58, s24
	s_add_u32 s98, s6, s60
	s_addc_u32 s99, s7, s61
	s_mov_b32 m0, s4
	ds_read_b128 v[186:189], v196 offset:16384
	ds_read_b128 v[190:193], v196 offset:17408
	ds_read_b128 v[198:201], v196 offset:18432
	ds_read_b128 v[212:215], v196 offset:19456
	ds_read_b128 v[216:219], v196 offset:20480
	ds_read_b128 v[220:223], v196 offset:21504
	ds_read_b128 v[224:227], v196 offset:22528
	ds_read_b128 v[228:231], v196 offset:23552
	global_load_lds_dwordx4 v2, s[6:7]
	s_add_i32 m0, s4, 0x2000
	s_add_u32 s4, s6, 0x100000
	s_addc_u32 s5, s7, 0
	s_add_i32 s58, s59, s24
	global_load_lds_dwordx4 v0, s[6:7]
	s_mov_b32 m0, s58
	s_add_u32 s100, s16, s60
	s_addc_u32 s101, s17, s61
	s_nop 0
	global_load_lds_dwordx4 v2, s[4:5]
	s_add_i32 m0, s58, 0x2000
	s_nop 0
	global_load_lds_dwordx4 v0, s[4:5]
	s_mov_b32 m0, s25
	s_nop 0
	global_load_lds_dwordx4 v162, s[16:17]
	s_mov_b32 m0, s26
	s_nop 0
	global_load_lds_dwordx4 v160, s[16:17]
	s_waitcnt vmcnt(8)
	s_waitcnt lgkmcnt(0)
	s_barrier
	s_setprio 1
	s_waitcnt lgkmcnt(0)
	v_mfma_f32_16x16x32_bf16 v[64:67], v[100:103], v[186:189], v[64:67]
	v_mfma_f32_16x16x32_bf16 v[60:63], v[124:127], v[186:189], v[60:63]
	v_mfma_f32_16x16x32_bf16 v[48:51], v[100:103], v[198:201], v[48:51]
	v_mfma_f32_16x16x32_bf16 v[44:47], v[124:127], v[198:201], v[44:47]
	v_mfma_f32_16x16x32_bf16 v[32:35], v[100:103], v[216:219], v[32:35]
	v_mfma_f32_16x16x32_bf16 v[28:31], v[124:127], v[216:219], v[28:31]
	v_mfma_f32_16x16x32_bf16 v[16:19], v[100:103], v[224:227], v[16:19]
	v_mfma_f32_16x16x32_bf16 v[12:15], v[124:127], v[224:227], v[12:15]
	v_mfma_f32_16x16x32_bf16 v[64:67], v[120:123], v[190:193], v[64:67]
	v_mfma_f32_16x16x32_bf16 v[60:63], v[144:147], v[190:193], v[60:63]
	v_mfma_f32_16x16x32_bf16 v[48:51], v[120:123], v[212:215], v[48:51]
	v_mfma_f32_16x16x32_bf16 v[44:47], v[144:147], v[212:215], v[44:47]
	v_mfma_f32_16x16x32_bf16 v[32:35], v[120:123], v[220:223], v[32:35]
	v_mfma_f32_16x16x32_bf16 v[28:31], v[144:147], v[220:223], v[28:31]
	v_mfma_f32_16x16x32_bf16 v[16:19], v[120:123], v[228:231], v[16:19]
	v_mfma_f32_16x16x32_bf16 v[12:15], v[144:147], v[228:231], v[12:15]
	s_setprio 0
	s_setprio 1
	v_mfma_f32_16x16x32_bf16 v[56:59], v[148:151], v[186:189], v[56:59]
	v_mfma_f32_16x16x32_bf16 v[52:55], v[156:159], v[186:189], v[52:55]
	v_mfma_f32_16x16x32_bf16 v[40:43], v[148:151], v[198:201], v[40:43]
	v_mfma_f32_16x16x32_bf16 v[36:39], v[156:159], v[198:201], v[36:39]
	v_mfma_f32_16x16x32_bf16 v[24:27], v[148:151], v[216:219], v[24:27]
	v_mfma_f32_16x16x32_bf16 v[20:23], v[156:159], v[216:219], v[20:23]
	v_mfma_f32_16x16x32_bf16 v[8:11], v[148:151], v[224:227], v[8:11]
	v_mfma_f32_16x16x32_bf16 v[4:7], v[156:159], v[224:227], v[4:7]
	v_mfma_f32_16x16x32_bf16 v[56:59], v[152:155], v[190:193], v[56:59]
	v_mfma_f32_16x16x32_bf16 v[52:55], v[182:185], v[190:193], v[52:55]
	v_mfma_f32_16x16x32_bf16 v[40:43], v[152:155], v[212:215], v[40:43]
	v_mfma_f32_16x16x32_bf16 v[36:39], v[182:185], v[212:215], v[36:39]
	v_mfma_f32_16x16x32_bf16 v[24:27], v[152:155], v[220:223], v[24:27]
	v_mfma_f32_16x16x32_bf16 v[20:23], v[182:185], v[220:223], v[20:23]
	v_mfma_f32_16x16x32_bf16 v[8:11], v[152:155], v[228:231], v[8:11]
	v_mfma_f32_16x16x32_bf16 v[4:7], v[182:185], v[228:231], v[4:7]
	s_setprio 0
	s_barrier
; #define PG8_STAGE(bufoff, gbase, voff) do { _Pragma("unroll") for (int _i = 0; _i < 2; ++_i) \
;         __builtin_amdgcn_global_load_lds((const unsigned*)((const char*)(gbase) + (voff)[_i]), (PG8_LAS unsigned*)(lds + (bufoff) + ldsw + _i * 8192), 16, 0, 0); } while (0)
; #define PG8_LDA(dst, b, h) do { _Pragma("unroll") for (int m = 0; m < 4; ++m) _Pragma("unroll") for (int k = 0; k < 2; ++k) dst[m][k] = *(const PG8_LAS bf16x8*)(lds + PG8_SA(b, h) + aoff + m * 2048 + k * 1024); } while (0)
; #define PG8_LDB(dst, b, h) do { _Pragma("unroll") for (int n = 0; n < 2; ++n) _Pragma("unroll") for (int k = 0; k < 2; ++k) dst[n][k] = *(const PG8_LAS bf16x8*)(lds + PG8_SB(b, h) + boff + n * 2048 + k * 1024); } while (0)
; #define PG8_MMA(ai, bj, At, Bt) do { __builtin_amdgcn_s_setprio(1); _Pragma("unroll") for (int m = 0; m < 4; ++m) _Pragma("unroll") for (int n = 0; n < 2; ++n) _Pragma("unroll") for (int k = 0; k < 2; ++k) \
;         acc[ai][bj][m][n] = __builtin_amdgcn_mfma_f32_16x16x32_bf16(Bt[n][k], At[m][k], acc[ai][bj][m][n], 0, 0, 0); __builtin_amdgcn_s_setprio(0); } while (0)
; #define PG8_WAIT_V(n) asm volatile("s_waitcnt vmcnt(" #n ")" ::: "memory")
; #define PG8_WAIT_L(n) asm volatile("s_waitcnt lgkmcnt(" #n ")" ::: "memory")
; template <class Epi, class Sched, bool ALIGN_EPI = false, bool SP2 = false>
; __device__ __forceinline__ void gemm_phase(PG8_LAS unsigned char* lds, const Gemm g, const Sched& S, const Epi& E, int wave_s) {
;     ...
;         for (int t = 0; t < nt; t += 2) {
;             const bool last = (t == nt - 2);
;             const char* a1 = cA + (size_t)(t + 1) * kstep;
;             const char* a2 = last ? nA : cA + (size_t)(t + 2) * kstep; const char* b2 = last ? nB : cB + (size_t)(t + 2) * kstep;
;             const char* a3 = a2 + kstep; const char* b3 = b2 + kstep;
;             if (last && has_next) S.a_ready(nxt);
;     ...
;             PG8_LDB(B0, 1, 0); PG8_LDB(B1, 1, 1); PG8_SCHED; PG8_LDA(At, 1, 0); PG8_STAGE(PG8_SA(0, 1), a2 + hstepA, voffA);
;             PG8_WAIT_V(8); PG8_WAIT_L(0); PG8_BAR; PG8_MMA(0, 0, At, B0); PG8_MMA(0, 1, At, B1); PG8_BAR; PG8_SCHED;
;             PG8_LDA(At, 1, 1); PG8_STAGE(PG8_SB(1, 0), b3, voffB); PG8_STAGE(PG8_SB(1, 1), b3 + hstepB, voffB); PG8_STAGE(PG8_SA(1, 0), a3, voffA);
;             PG8_WAIT_V(8); PG8_WAIT_L(0); PG8_BAR; PG8_MMA(1, 0, At, B0); PG8_MMA(1, 1, At, B1); PG8_BAR; PG8_SCHED;
	s_add_i32 s58, 0, 0x18000
	s_add_i32 s59, 0, 0x1c000
	ds_read_b128 v[100:103], v255 offset:32768
	ds_read_b128 v[120:123], v255 offset:33792
	ds_read_b128 v[124:127], v255 offset:34816
	ds_read_b128 v[144:147], v255 offset:35840
	ds_read_b128 v[148:151], v255 offset:49152
	ds_read_b128 v[152:155], v255 offset:50176
	ds_read_b128 v[156:159], v255 offset:51200
	ds_read_b128 v[182:185], v255 offset:52224
	s_add_u32 s4, s16, 0x4b0000
	s_addc_u32 s5, s17, 0
	s_mov_b32 m0, s27
	ds_read_b128 v[186:189], v196 offset:32768
	ds_read_b128 v[190:193], v196 offset:33792
	ds_read_b128 v[198:201], v196 offset:34816
	ds_read_b128 v[212:215], v196 offset:35840
	ds_read_b128 v[216:219], v196 offset:36864
	ds_read_b128 v[220:223], v196 offset:37888
	ds_read_b128 v[224:227], v196 offset:38912
	ds_read_b128 v[228:231], v196 offset:39936
	global_load_lds_dwordx4 v162, s[4:5]
	s_mov_b32 m0, s30
	s_nop 0
	global_load_lds_dwordx4 v160, s[4:5]
	s_waitcnt vmcnt(8)
	s_waitcnt lgkmcnt(0)
	s_barrier
	s_setprio 1
	s_waitcnt lgkmcnt(0)
	v_mfma_f32_16x16x32_bf16 v[140:143], v[100:103], v[186:189], v[140:143]
	v_mfma_f32_16x16x32_bf16 v[136:139], v[124:127], v[186:189], v[136:139]
	v_mfma_f32_16x16x32_bf16 v[116:119], v[100:103], v[198:201], v[116:119]
	v_mfma_f32_16x16x32_bf16 v[112:115], v[124:127], v[198:201], v[112:115]
	v_mfma_f32_16x16x32_bf16 v[96:99], v[100:103], v[216:219], v[96:99]
	v_mfma_f32_16x16x32_bf16 v[92:95], v[124:127], v[216:219], v[92:95]
	v_mfma_f32_16x16x32_bf16 v[80:83], v[100:103], v[224:227], v[80:83]
	v_mfma_f32_16x16x32_bf16 v[76:79], v[124:127], v[224:227], v[76:79]
	v_mfma_f32_16x16x32_bf16 v[140:143], v[120:123], v[190:193], v[140:143]
	v_mfma_f32_16x16x32_bf16 v[136:139], v[144:147], v[190:193], v[136:139]
	v_mfma_f32_16x16x32_bf16 v[116:119], v[120:123], v[212:215], v[116:119]
	v_mfma_f32_16x16x32_bf16 v[112:115], v[144:147], v[212:215], v[112:115]
	v_mfma_f32_16x16x32_bf16 v[96:99], v[120:123], v[220:223], v[96:99]
	v_mfma_f32_16x16x32_bf16 v[92:95], v[144:147], v[220:223], v[92:95]
	v_mfma_f32_16x16x32_bf16 v[80:83], v[120:123], v[228:231], v[80:83]
	v_mfma_f32_16x16x32_bf16 v[76:79], v[144:147], v[228:231], v[76:79]
	s_setprio 0
	s_setprio 1
	v_mfma_f32_16x16x32_bf16 v[132:135], v[148:151], v[186:189], v[132:135]
	v_mfma_f32_16x16x32_bf16 v[128:131], v[156:159], v[186:189], v[128:131]
	v_mfma_f32_16x16x32_bf16 v[108:111], v[148:151], v[198:201], v[108:111]
	v_mfma_f32_16x16x32_bf16 v[104:107], v[156:159], v[198:201], v[104:107]
	v_mfma_f32_16x16x32_bf16 v[88:91], v[148:151], v[216:219], v[88:91]
	v_mfma_f32_16x16x32_bf16 v[84:87], v[156:159], v[216:219], v[84:87]
	v_mfma_f32_16x16x32_bf16 v[72:75], v[148:151], v[224:227], v[72:75]
	v_mfma_f32_16x16x32_bf16 v[68:71], v[156:159], v[224:227], v[68:71]
	v_mfma_f32_16x16x32_bf16 v[132:135], v[152:155], v[190:193], v[132:135]
	v_mfma_f32_16x16x32_bf16 v[128:131], v[182:185], v[190:193], v[128:131]
	v_mfma_f32_16x16x32_bf16 v[108:111], v[152:155], v[212:215], v[108:111]
	v_mfma_f32_16x16x32_bf16 v[104:107], v[182:185], v[212:215], v[104:107]
	v_mfma_f32_16x16x32_bf16 v[88:91], v[152:155], v[220:223], v[88:91]
	v_mfma_f32_16x16x32_bf16 v[84:87], v[182:185], v[220:223], v[84:87]
	v_mfma_f32_16x16x32_bf16 v[72:75], v[152:155], v[228:231], v[72:75]
	v_mfma_f32_16x16x32_bf16 v[68:71], v[182:185], v[228:231], v[68:71]
	s_setprio 0
	s_barrier
	s_add_i32 s4, s58, s24
	s_mov_b32 m0, s4
	ds_read_b128 v[186:189], v196 offset:49152
	ds_read_b128 v[190:193], v196 offset:50176
	ds_read_b128 v[198:201], v196 offset:51200
	ds_read_b128 v[212:215], v196 offset:52224
	ds_read_b128 v[216:219], v196 offset:53248
	ds_read_b128 v[220:223], v196 offset:54272
	ds_read_b128 v[224:227], v196 offset:55296
	ds_read_b128 v[228:231], v196 offset:56320
	global_load_lds_dwordx4 v2, s[98:99]
	s_add_i32 m0, s4, 0x2000
	s_add_u32 s4, s6, 0x100080
	s_addc_u32 s5, s7, 0
	s_add_i32 s6, s59, s24
	global_load_lds_dwordx4 v0, s[98:99]
	s_mov_b32 m0, s6
	s_nop 0
	global_load_lds_dwordx4 v2, s[4:5]
	s_add_i32 m0, s6, 0x2000
	s_nop 0
	global_load_lds_dwordx4 v0, s[4:5]
	s_mov_b32 m0, s52
	s_nop 0
	global_load_lds_dwordx4 v162, s[100:101]
	s_mov_b32 m0, s53
	s_nop 0
	global_load_lds_dwordx4 v160, s[100:101]
	s_waitcnt vmcnt(8)
	s_waitcnt lgkmcnt(0)
	s_barrier
	s_setprio 1
	s_waitcnt lgkmcnt(0)
	v_mfma_f32_16x16x32_bf16 v[64:67], v[100:103], v[186:189], v[64:67]
	v_mfma_f32_16x16x32_bf16 v[60:63], v[124:127], v[186:189], v[60:63]
	v_mfma_f32_16x16x32_bf16 v[48:51], v[100:103], v[198:201], v[48:51]
	v_mfma_f32_16x16x32_bf16 v[44:47], v[124:127], v[198:201], v[44:47]
	v_mfma_f32_16x16x32_bf16 v[32:35], v[100:103], v[216:219], v[32:35]
	v_mfma_f32_16x16x32_bf16 v[28:31], v[124:127], v[216:219], v[28:31]
	v_mfma_f32_16x16x32_bf16 v[16:19], v[100:103], v[224:227], v[16:19]
	v_mfma_f32_16x16x32_bf16 v[12:15], v[124:127], v[224:227], v[12:15]
	v_mfma_f32_16x16x32_bf16 v[64:67], v[120:123], v[190:193], v[64:67]
	v_mfma_f32_16x16x32_bf16 v[60:63], v[144:147], v[190:193], v[60:63]
	v_mfma_f32_16x16x32_bf16 v[48:51], v[120:123], v[212:215], v[48:51]
	v_mfma_f32_16x16x32_bf16 v[44:47], v[144:147], v[212:215], v[44:47]
	v_mfma_f32_16x16x32_bf16 v[32:35], v[120:123], v[220:223], v[32:35]
	v_mfma_f32_16x16x32_bf16 v[28:31], v[144:147], v[220:223], v[28:31]
	v_mfma_f32_16x16x32_bf16 v[16:19], v[120:123], v[228:231], v[16:19]
	v_mfma_f32_16x16x32_bf16 v[12:15], v[144:147], v[228:231], v[12:15]
	s_setprio 0
	s_setprio 1
	v_mfma_f32_16x16x32_bf16 v[56:59], v[148:151], v[186:189], v[56:59]
	v_mfma_f32_16x16x32_bf16 v[52:55], v[156:159], v[186:189], v[52:55]
	v_mfma_f32_16x16x32_bf16 v[40:43], v[148:151], v[198:201], v[40:43]
	v_mfma_f32_16x16x32_bf16 v[36:39], v[156:159], v[198:201], v[36:39]
	v_mfma_f32_16x16x32_bf16 v[24:27], v[148:151], v[216:219], v[24:27]
	v_mfma_f32_16x16x32_bf16 v[20:23], v[156:159], v[216:219], v[20:23]
	v_mfma_f32_16x16x32_bf16 v[8:11], v[148:151], v[224:227], v[8:11]
	v_mfma_f32_16x16x32_bf16 v[4:7], v[156:159], v[224:227], v[4:7]
	v_mfma_f32_16x16x32_bf16 v[56:59], v[152:155], v[190:193], v[56:59]
	v_mfma_f32_16x16x32_bf16 v[52:55], v[182:185], v[190:193], v[52:55]
	v_mfma_f32_16x16x32_bf16 v[40:43], v[152:155], v[212:215], v[40:43]
	v_mfma_f32_16x16x32_bf16 v[36:39], v[182:185], v[212:215], v[36:39]
	v_mfma_f32_16x16x32_bf16 v[24:27], v[152:155], v[220:223], v[24:27]
	v_mfma_f32_16x16x32_bf16 v[20:23], v[182:185], v[220:223], v[20:23]
	v_mfma_f32_16x16x32_bf16 v[8:11], v[152:155], v[228:231], v[8:11]
	v_mfma_f32_16x16x32_bf16 v[4:7], v[182:185], v[228:231], v[4:7]
	s_setprio 0
	s_barrier
	s_add_i32 s57, s57, 2
	s_add_u32 s47, s47, 0x100
	s_addc_u32 s56, s56, 0
	s_cmp_gt_u32 s57, 61
	s_mov_b64 s[4:5], s[0:1]
	s_cbranch_scc0 .LBB0_590
	s_and_b64 vcc, exec, s[20:21]
	s_cbranch_vccz .LBB0_593
	s_barrier

; #define PG8_STAGE(bufoff, gbase, voff) do { _Pragma("unroll") for (int _i = 0; _i < 2; ++_i) \
;         __builtin_amdgcn_global_load_lds((const unsigned*)((const char*)(gbase) + (voff)[_i]), (PG8_LAS unsigned*)(lds + (bufoff) + ldsw + _i * 8192), 16, 0, 0); } while (0)
; #define PG8_LDA(dst, b, h) do { _Pragma("unroll") for (int m = 0; m < 4; ++m) _Pragma("unroll") for (int k = 0; k < 2; ++k) dst[m][k] = *(const PG8_LAS bf16x8*)(lds + PG8_SA(b, h) + aoff + m * 2048 + k * 1024); } while (0)
; #define PG8_LDB(dst, b, h) do { _Pragma("unroll") for (int n = 0; n < 2; ++n) _Pragma("unroll") for (int k = 0; k < 2; ++k) dst[n][k] = *(const PG8_LAS bf16x8*)(lds + PG8_SB(b, h) + boff + n * 2048 + k * 1024); } while (0)
; #define PG8_WAIT_V(n) asm volatile("s_waitcnt vmcnt(" #n ")" ::: "memory")
; #define PG8_WAIT_L(n) asm volatile("s_waitcnt lgkmcnt(" #n ")" ::: "memory")
; #define PG8_BAR __builtin_amdgcn_s_barrier()
; template <class Epi, class Sched, bool ALIGN_EPI = false, bool SP2 = false>
; __device__ __forceinline__ void gemm_phase(PG8_LAS unsigned char* lds, const Gemm g, const Sched& S, const Epi& E, int wave_s) {
;     ...
;         const bool has_next = S.next(ui + 1, nxt);
;         const char* nA = has_next ? (const char*)g.A + (size_t)nxt.pm * tstepA : cA; const char* nB = has_next ? (const char*)g.Bt + (size_t)nxt.pn * tstepB : cB;
;         for (int t = 0; t < nt; t += 2) {
;             const bool last = (t == nt - 2);
;             const char* a1 = cA + (size_t)(t + 1) * kstep;
;             const char* a2 = last ? nA : cA + (size_t)(t + 2) * kstep; const char* b2 = last ? nB : cB + (size_t)(t + 2) * kstep;
;             const char* a3 = a2 + kstep; const char* b3 = b2 + kstep;
;             if (last && has_next) S.a_ready(nxt);
;             if constexpr (SP2) {
;             PG8_LDB(B0, 0, 0); PG8_LDB(B1, 0, 1); PG8_SCHED; PG8_LDA(At, 0, 0); PG8_STAGE(PG8_SA(1, 1), a1 + hstepA, voffA);
;             PG8_WAIT_V(8); PG8_WAIT_L(0); PG8_BAR; PG8_MMA(0, 0, At, B0); PG8_MMA(0, 1, At, B1); PG8_BAR; PG8_SCHED;
;     ...
;         for (int a = 0; a < 2; ++a)
; #pragma unroll
;             for (int b = 0; b < 2; ++b)
; #pragma unroll
;                 for (int m = 0; m < 4; ++m)
; #pragma unroll
;                     for (int n = 0; n < 2; ++n) acc[a][b][m][n] = (f32x4){0.f, 0.f, 0.f, 0.f};
;         cur = nxt; cA = nA; cB = nB; ++ui;
.LBB0_660:
	s_ashr_i32 s7, s6, 31
	s_lshl_b64 s[16:17], s[6:7], 20
	s_add_u32 s22, s2, s16
	s_addc_u32 s23, s30, s17
	s_and_b64 s[16:17], s[36:37], exec
	s_cselect_b32 s7, s23, s27
	s_cselect_b32 s57, s22, s26
	s_ashr_i32 s5, s4, 31
	s_lshl_b64 s[16:17], s[4:5], 20
	s_add_u32 s16, s44, s16
	s_addc_u32 s17, s45, s17
	s_and_b64 s[42:43], s[36:37], exec
	s_cselect_b32 s5, s17, s19
	s_cselect_b32 s58, s16, s18
	s_add_u32 s59, s18, 0x100
	s_addc_u32 s66, s19, 0
	s_add_u32 s18, s26, 0x80080
	v_mov_b32_e32 v4, 0
	s_addc_u32 s19, s27, 0
	s_mov_b32 s67, -2
	v_mov_b32_e32 v5, v4
	v_mov_b32_e32 v6, v4
	v_mov_b32_e32 v7, v4
	v_mov_b32_e32 v8, v4
	v_mov_b32_e32 v9, v4
	v_mov_b32_e32 v10, v4
	v_mov_b32_e32 v11, v4
	v_mov_b32_e32 v20, v4
	v_mov_b32_e32 v21, v4
	v_mov_b32_e32 v22, v4
	v_mov_b32_e32 v23, v4
	v_mov_b32_e32 v24, v4
	v_mov_b32_e32 v25, v4
	v_mov_b32_e32 v26, v4
	v_mov_b32_e32 v27, v4
	v_mov_b32_e32 v36, v4
	v_mov_b32_e32 v37, v4
	v_mov_b32_e32 v38, v4
	v_mov_b32_e32 v39, v4
	v_mov_b32_e32 v40, v4
	v_mov_b32_e32 v41, v4
	v_mov_b32_e32 v42, v4
	v_mov_b32_e32 v43, v4
	v_mov_b32_e32 v52, v4
	v_mov_b32_e32 v53, v4
	v_mov_b32_e32 v54, v4
	v_mov_b32_e32 v55, v4
	v_mov_b32_e32 v56, v4
	v_mov_b32_e32 v57, v4
	v_mov_b32_e32 v58, v4
	v_mov_b32_e32 v59, v4
	v_mov_b32_e32 v12, v4
	v_mov_b32_e32 v13, v4
	v_mov_b32_e32 v14, v4
	v_mov_b32_e32 v15, v4
	v_mov_b32_e32 v16, v4
	v_mov_b32_e32 v17, v4
	v_mov_b32_e32 v18, v4
	v_mov_b32_e32 v19, v4
	v_mov_b32_e32 v28, v4
	v_mov_b32_e32 v29, v4
	v_mov_b32_e32 v30, v4
	v_mov_b32_e32 v31, v4
	v_mov_b32_e32 v32, v4
	v_mov_b32_e32 v33, v4
	v_mov_b32_e32 v34, v4
	v_mov_b32_e32 v35, v4
	v_mov_b32_e32 v44, v4
	v_mov_b32_e32 v45, v4
	v_mov_b32_e32 v46, v4
	v_mov_b32_e32 v47, v4
	v_mov_b32_e32 v48, v4
	v_mov_b32_e32 v49, v4
	v_mov_b32_e32 v50, v4
	v_mov_b32_e32 v51, v4
	v_mov_b32_e32 v60, v4
	v_mov_b32_e32 v61, v4
	v_mov_b32_e32 v62, v4
	v_mov_b32_e32 v63, v4
	v_mov_b32_e32 v64, v4
	v_mov_b32_e32 v65, v4
	v_mov_b32_e32 v66, v4
	v_mov_b32_e32 v67, v4
	v_mov_b32_e32 v68, v4
	v_mov_b32_e32 v69, v4
	v_mov_b32_e32 v70, v4
	v_mov_b32_e32 v71, v4
	v_mov_b32_e32 v72, v4
	v_mov_b32_e32 v73, v4
	v_mov_b32_e32 v74, v4
	v_mov_b32_e32 v75, v4
	v_mov_b32_e32 v84, v4
	v_mov_b32_e32 v85, v4
	v_mov_b32_e32 v86, v4
	v_mov_b32_e32 v87, v4
	v_mov_b32_e32 v88, v4
	v_mov_b32_e32 v89, v4
	v_mov_b32_e32 v90, v4
	v_mov_b32_e32 v91, v4
	v_mov_b32_e32 v100, v4
	v_mov_b32_e32 v101, v4
	v_mov_b32_e32 v102, v4
	v_mov_b32_e32 v103, v4
	v_mov_b32_e32 v104, v4
	v_mov_b32_e32 v105, v4
	v_mov_b32_e32 v106, v4
	v_mov_b32_e32 v107, v4
	v_mov_b32_e32 v124, v4
	v_mov_b32_e32 v125, v4
	v_mov_b32_e32 v126, v4
	v_mov_b32_e32 v127, v4
	v_mov_b32_e32 v128, v4
	v_mov_b32_e32 v129, v4
	v_mov_b32_e32 v130, v4
	v_mov_b32_e32 v131, v4
	v_mov_b32_e32 v76, v4
	v_mov_b32_e32 v77, v4
	v_mov_b32_e32 v78, v4
	v_mov_b32_e32 v79, v4
	v_mov_b32_e32 v80, v4
	v_mov_b32_e32 v81, v4
	v_mov_b32_e32 v82, v4
	v_mov_b32_e32 v83, v4
	v_mov_b32_e32 v92, v4
	v_mov_b32_e32 v93, v4
	v_mov_b32_e32 v94, v4
	v_mov_b32_e32 v95, v4
	v_mov_b32_e32 v96, v4
	v_mov_b32_e32 v97, v4
	v_mov_b32_e32 v98, v4
	v_mov_b32_e32 v99, v4
	v_mov_b32_e32 v132, v4
	v_mov_b32_e32 v133, v4
	v_mov_b32_e32 v134, v4
	v_mov_b32_e32 v135, v4
	v_mov_b32_e32 v136, v4
	v_mov_b32_e32 v137, v4
	v_mov_b32_e32 v138, v4
	v_mov_b32_e32 v139, v4
	v_mov_b32_e32 v140, v4
	v_mov_b32_e32 v141, v4
	v_mov_b32_e32 v142, v4
	v_mov_b32_e32 v143, v4
	v_mov_b32_e32 v144, v4
	v_mov_b32_e32 v145, v4
	v_mov_b32_e32 v146, v4
	v_mov_b32_e32 v147, v4
	v_add_u32_e32 v255, 0x10000, v211
.LBB0_661:
	s_add_u32 s26, s18, 0xfff80080
	s_addc_u32 s27, s19, -1
	s_add_i32 s74, 0, 0x10000
	s_cmp_eq_u32 s67, 28
	s_cselect_b32 s43, s7, s27
	s_cselect_b32 s42, s57, s26
	s_cselect_b32 s27, s5, s66
	s_cselect_b32 s26, s58, s59
	s_add_i32 s76, 0, 0x14000
	s_waitcnt vmcnt(0) lgkmcnt(0)
	ds_read_b128 v[108:111], v255
	ds_read_b128 v[112:115], v255 offset:1024
	ds_read_b128 v[116:119], v255 offset:2048
	ds_read_b128 v[120:123], v255 offset:3072
	ds_read_b128 v[148:151], v255 offset:16384
	ds_read_b128 v[152:155], v255 offset:17408
	ds_read_b128 v[156:159], v255 offset:18432
	ds_read_b128 v[160:163], v255 offset:19456
	s_add_i32 m0, s47, 0xc000
	ds_read_b128 v[164:167], v213
	ds_read_b128 v[190:193], v213 offset:1024
	ds_read_b128 v[194:197], v213 offset:2048
	ds_read_b128 v[198:201], v213 offset:3072
	ds_read_b128 v[214:217], v213 offset:4096
	ds_read_b128 v[218:221], v213 offset:5120
	ds_read_b128 v[222:225], v213 offset:6144
	ds_read_b128 v[226:229], v213 offset:7168
	global_load_lds_dwordx4 v188, s[18:19]
	s_add_i32 m0, s47, 0xe000
	s_nop 0
	global_load_lds_dwordx4 v186, s[18:19]
	s_waitcnt vmcnt(8)
	s_waitcnt lgkmcnt(0)
	s_barrier
; #define PG8_STAGE(bufoff, gbase, voff) do { _Pragma("unroll") for (int _i = 0; _i < 2; ++_i) \
;         __builtin_amdgcn_global_load_lds((const unsigned*)((const char*)(gbase) + (voff)[_i]), (PG8_LAS unsigned*)(lds + (bufoff) + ldsw + _i * 8192), 16, 0, 0); } while (0)
; #define PG8_LDA(dst, b, h) do { _Pragma("unroll") for (int m = 0; m < 4; ++m) _Pragma("unroll") for (int k = 0; k < 2; ++k) dst[m][k] = *(const PG8_LAS bf16x8*)(lds + PG8_SA(b, h) + aoff + m * 2048 + k * 1024); } while (0)
; #define PG8_MMA(ai, bj, At, Bt) do { __builtin_amdgcn_s_setprio(1); _Pragma("unroll") for (int m = 0; m < 4; ++m) _Pragma("unroll") for (int n = 0; n < 2; ++n) _Pragma("unroll") for (int k = 0; k < 2; ++k) \
;         acc[ai][bj][m][n] = __builtin_amdgcn_mfma_f32_16x16x32_bf16(Bt[n][k], At[m][k], acc[ai][bj][m][n], 0, 0, 0); __builtin_amdgcn_s_setprio(0); } while (0)
; #define PG8_WAIT_V(n) asm volatile("s_waitcnt vmcnt(" #n ")" ::: "memory")
; #define PG8_WAIT_L(n) asm volatile("s_waitcnt lgkmcnt(" #n ")" ::: "memory")
; #define PG8_BAR __builtin_amdgcn_s_barrier()
; #define PG8_SCHED __builtin_amdgcn_sched_barrier(0)
; template <class Epi, class Sched, bool ALIGN_EPI = false, bool SP2 = false>
; __device__ __forceinline__ void gemm_phase(PG8_LAS unsigned char* lds, const Gemm g, const Sched& S, const Epi& E, int wave_s) {
;     ...
;             PG8_WAIT_V(8); PG8_WAIT_L(0); PG8_BAR; PG8_MMA(0, 0, At, B0); PG8_MMA(0, 1, At, B1); PG8_BAR; PG8_SCHED;
;             PG8_LDA(At, 0, 1); PG8_STAGE(PG8_SB(0, 0), b2, voffB); PG8_STAGE(PG8_SB(0, 1), b2 + hstepB, voffB); PG8_STAGE(PG8_SA(0, 0), a2, voffA);
;             PG8_WAIT_V(8); PG8_WAIT_L(0); PG8_BAR; PG8_MMA(1, 0, At, B0); PG8_MMA(1, 1, At, B1); PG8_BAR; PG8_SCHED;
	s_setprio 1
	s_waitcnt lgkmcnt(0)
	v_mfma_f32_16x16x32_bf16 v[144:147], v[108:111], v[164:167], v[144:147]
	v_mfma_f32_16x16x32_bf16 v[140:143], v[116:119], v[164:167], v[140:143]
	v_mfma_f32_16x16x32_bf16 v[136:139], v[108:111], v[194:197], v[136:139]
	v_mfma_f32_16x16x32_bf16 v[132:135], v[116:119], v[194:197], v[132:135]
	v_mfma_f32_16x16x32_bf16 v[96:99], v[108:111], v[214:217], v[96:99]
	v_mfma_f32_16x16x32_bf16 v[92:95], v[116:119], v[214:217], v[92:95]
	v_mfma_f32_16x16x32_bf16 v[80:83], v[108:111], v[222:225], v[80:83]
	v_mfma_f32_16x16x32_bf16 v[76:79], v[116:119], v[222:225], v[76:79]
	v_mfma_f32_16x16x32_bf16 v[144:147], v[112:115], v[190:193], v[144:147]
	v_mfma_f32_16x16x32_bf16 v[140:143], v[120:123], v[190:193], v[140:143]
	v_mfma_f32_16x16x32_bf16 v[136:139], v[112:115], v[198:201], v[136:139]
	v_mfma_f32_16x16x32_bf16 v[132:135], v[120:123], v[198:201], v[132:135]
	v_mfma_f32_16x16x32_bf16 v[96:99], v[112:115], v[218:221], v[96:99]
	v_mfma_f32_16x16x32_bf16 v[92:95], v[120:123], v[218:221], v[92:95]
	v_mfma_f32_16x16x32_bf16 v[80:83], v[112:115], v[226:229], v[80:83]
	v_mfma_f32_16x16x32_bf16 v[76:79], v[120:123], v[226:229], v[76:79]
	s_setprio 0
	s_setprio 1
	v_mfma_f32_16x16x32_bf16 v[128:131], v[148:151], v[164:167], v[128:131]
	v_mfma_f32_16x16x32_bf16 v[124:127], v[156:159], v[164:167], v[124:127]
	v_mfma_f32_16x16x32_bf16 v[104:107], v[148:151], v[194:197], v[104:107]
	v_mfma_f32_16x16x32_bf16 v[100:103], v[156:159], v[194:197], v[100:103]
	v_mfma_f32_16x16x32_bf16 v[88:91], v[148:151], v[214:217], v[88:91]
	v_mfma_f32_16x16x32_bf16 v[84:87], v[156:159], v[214:217], v[84:87]
	v_mfma_f32_16x16x32_bf16 v[72:75], v[148:151], v[222:225], v[72:75]
	v_mfma_f32_16x16x32_bf16 v[68:71], v[156:159], v[222:225], v[68:71]
	v_mfma_f32_16x16x32_bf16 v[128:131], v[152:155], v[190:193], v[128:131]
	v_mfma_f32_16x16x32_bf16 v[124:127], v[160:163], v[190:193], v[124:127]
	v_mfma_f32_16x16x32_bf16 v[104:107], v[152:155], v[198:201], v[104:107]
	v_mfma_f32_16x16x32_bf16 v[100:103], v[160:163], v[198:201], v[100:103]
	v_mfma_f32_16x16x32_bf16 v[88:91], v[152:155], v[218:221], v[88:91]
	v_mfma_f32_16x16x32_bf16 v[84:87], v[160:163], v[218:221], v[84:87]
	v_mfma_f32_16x16x32_bf16 v[72:75], v[152:155], v[226:229], v[72:75]
	v_mfma_f32_16x16x32_bf16 v[68:71], v[160:163], v[226:229], v[68:71]
	s_setprio 0
	s_barrier
	s_add_i32 s74, s74, s46
	s_add_u32 s98, s26, s60
	s_addc_u32 s99, s27, s61
	s_mov_b32 m0, s74
	ds_read_b128 v[164:167], v213 offset:16384
	ds_read_b128 v[190:193], v213 offset:17408
	ds_read_b128 v[194:197], v213 offset:18432
	ds_read_b128 v[198:201], v213 offset:19456
	ds_read_b128 v[214:217], v213 offset:20480
	ds_read_b128 v[218:221], v213 offset:21504
	ds_read_b128 v[222:225], v213 offset:22528
	ds_read_b128 v[226:229], v213 offset:23552
	global_load_lds_dwordx4 v2, s[26:27]
	s_add_i32 m0, s74, 0x2000
	s_add_u32 s74, s26, 0x80000
	s_addc_u32 s75, s27, 0
	s_add_i32 s76, s76, s46
	global_load_lds_dwordx4 v0, s[26:27]
	s_mov_b32 m0, s76
	s_add_u32 s100, s42, s60
	s_addc_u32 s101, s43, s61
	s_nop 0
	global_load_lds_dwordx4 v2, s[74:75]
	s_add_i32 m0, s76, 0x2000
	s_nop 0
	global_load_lds_dwordx4 v0, s[74:75]
	s_mov_b32 m0, s47
	s_nop 0
	global_load_lds_dwordx4 v184, s[42:43]
	s_mov_b32 m0, s48
	s_nop 0
	global_load_lds_dwordx4 v182, s[42:43]
	s_waitcnt vmcnt(8)
	s_waitcnt lgkmcnt(0)
	s_barrier
	s_setprio 1
	s_waitcnt lgkmcnt(0)
	v_mfma_f32_16x16x32_bf16 v[64:67], v[108:111], v[164:167], v[64:67]
	v_mfma_f32_16x16x32_bf16 v[60:63], v[116:119], v[164:167], v[60:63]
	v_mfma_f32_16x16x32_bf16 v[48:51], v[108:111], v[194:197], v[48:51]
	v_mfma_f32_16x16x32_bf16 v[44:47], v[116:119], v[194:197], v[44:47]
	v_mfma_f32_16x16x32_bf16 v[32:35], v[108:111], v[214:217], v[32:35]
	v_mfma_f32_16x16x32_bf16 v[28:31], v[116:119], v[214:217], v[28:31]
	v_mfma_f32_16x16x32_bf16 v[16:19], v[108:111], v[222:225], v[16:19]
	v_mfma_f32_16x16x32_bf16 v[12:15], v[116:119], v[222:225], v[12:15]
	v_mfma_f32_16x16x32_bf16 v[64:67], v[112:115], v[190:193], v[64:67]
	v_mfma_f32_16x16x32_bf16 v[60:63], v[120:123], v[190:193], v[60:63]
	v_mfma_f32_16x16x32_bf16 v[48:51], v[112:115], v[198:201], v[48:51]
	v_mfma_f32_16x16x32_bf16 v[44:47], v[120:123], v[198:201], v[44:47]
	v_mfma_f32_16x16x32_bf16 v[32:35], v[112:115], v[218:221], v[32:35]
	v_mfma_f32_16x16x32_bf16 v[28:31], v[120:123], v[218:221], v[28:31]
	v_mfma_f32_16x16x32_bf16 v[16:19], v[112:115], v[226:229], v[16:19]
	v_mfma_f32_16x16x32_bf16 v[12:15], v[120:123], v[226:229], v[12:15]
	s_setprio 0
	s_setprio 1
	v_mfma_f32_16x16x32_bf16 v[56:59], v[148:151], v[164:167], v[56:59]
	v_mfma_f32_16x16x32_bf16 v[52:55], v[156:159], v[164:167], v[52:55]
	v_mfma_f32_16x16x32_bf16 v[40:43], v[148:151], v[194:197], v[40:43]
	v_mfma_f32_16x16x32_bf16 v[36:39], v[156:159], v[194:197], v[36:39]
	v_mfma_f32_16x16x32_bf16 v[24:27], v[148:151], v[214:217], v[24:27]
	v_mfma_f32_16x16x32_bf16 v[20:23], v[156:159], v[214:217], v[20:23]
	v_mfma_f32_16x16x32_bf16 v[8:11], v[148:151], v[222:225], v[8:11]
	v_mfma_f32_16x16x32_bf16 v[4:7], v[156:159], v[222:225], v[4:7]
	v_mfma_f32_16x16x32_bf16 v[56:59], v[152:155], v[190:193], v[56:59]
	v_mfma_f32_16x16x32_bf16 v[52:55], v[160:163], v[190:193], v[52:55]
	v_mfma_f32_16x16x32_bf16 v[40:43], v[152:155], v[198:201], v[40:43]
	v_mfma_f32_16x16x32_bf16 v[36:39], v[160:163], v[198:201], v[36:39]
	v_mfma_f32_16x16x32_bf16 v[24:27], v[152:155], v[218:221], v[24:27]
	v_mfma_f32_16x16x32_bf16 v[20:23], v[160:163], v[218:221], v[20:23]
	v_mfma_f32_16x16x32_bf16 v[8:11], v[152:155], v[226:229], v[8:11]
	v_mfma_f32_16x16x32_bf16 v[4:7], v[160:163], v[226:229], v[4:7]
	s_setprio 0
	s_barrier
; #define PG8_STAGE(bufoff, gbase, voff) do { _Pragma("unroll") for (int _i = 0; _i < 2; ++_i) \
;         __builtin_amdgcn_global_load_lds((const unsigned*)((const char*)(gbase) + (voff)[_i]), (PG8_LAS unsigned*)(lds + (bufoff) + ldsw + _i * 8192), 16, 0, 0); } while (0)
; #define PG8_LDA(dst, b, h) do { _Pragma("unroll") for (int m = 0; m < 4; ++m) _Pragma("unroll") for (int k = 0; k < 2; ++k) dst[m][k] = *(const PG8_LAS bf16x8*)(lds + PG8_SA(b, h) + aoff + m * 2048 + k * 1024); } while (0)
; #define PG8_LDB(dst, b, h) do { _Pragma("unroll") for (int n = 0; n < 2; ++n) _Pragma("unroll") for (int k = 0; k < 2; ++k) dst[n][k] = *(const PG8_LAS bf16x8*)(lds + PG8_SB(b, h) + boff + n * 2048 + k * 1024); } while (0)
; #define PG8_MMA(ai, bj, At, Bt) do { __builtin_amdgcn_s_setprio(1); _Pragma("unroll") for (int m = 0; m < 4; ++m) _Pragma("unroll") for (int n = 0; n < 2; ++n) _Pragma("unroll") for (int k = 0; k < 2; ++k) \
;         acc[ai][bj][m][n] = __builtin_amdgcn_mfma_f32_16x16x32_bf16(Bt[n][k], At[m][k], acc[ai][bj][m][n], 0, 0, 0); __builtin_amdgcn_s_setprio(0); } while (0)
; #define PG8_WAIT_V(n) asm volatile("s_waitcnt vmcnt(" #n ")" ::: "memory")
; #define PG8_WAIT_L(n) asm volatile("s_waitcnt lgkmcnt(" #n ")" ::: "memory")
; template <class Epi, class Sched, bool ALIGN_EPI = false, bool SP2 = false>
; __device__ __forceinline__ void gemm_phase(PG8_LAS unsigned char* lds, const Gemm g, const Sched& S, const Epi& E, int wave_s) {
;     ...
;         for (int t = 0; t < nt; t += 2) {
;             const bool last = (t == nt - 2);
;             const char* a1 = cA + (size_t)(t + 1) * kstep;
;             const char* a2 = last ? nA : cA + (size_t)(t + 2) * kstep; const char* b2 = last ? nB : cB + (size_t)(t + 2) * kstep;
;             const char* a3 = a2 + kstep; const char* b3 = b2 + kstep;
;             if (last && has_next) S.a_ready(nxt);
;     ...
;             PG8_LDB(B0, 1, 0); PG8_LDB(B1, 1, 1); PG8_SCHED; PG8_LDA(At, 1, 0); PG8_STAGE(PG8_SA(0, 1), a2 + hstepA, voffA);
;             PG8_WAIT_V(8); PG8_WAIT_L(0); PG8_BAR; PG8_MMA(0, 0, At, B0); PG8_MMA(0, 1, At, B1); PG8_BAR; PG8_SCHED;
;             PG8_LDA(At, 1, 1); PG8_STAGE(PG8_SB(1, 0), b3, voffB); PG8_STAGE(PG8_SB(1, 1), b3 + hstepB, voffB); PG8_STAGE(PG8_SA(1, 0), a3, voffA);
;             PG8_WAIT_V(8); PG8_WAIT_L(0); PG8_BAR; PG8_MMA(1, 0, At, B0); PG8_MMA(1, 1, At, B1); PG8_BAR; PG8_SCHED;
	s_add_i32 s74, 0, 0x18000
	s_add_i32 s75, 0, 0x1c000
	ds_read_b128 v[108:111], v255 offset:32768
	ds_read_b128 v[112:115], v255 offset:33792
	ds_read_b128 v[116:119], v255 offset:34816
	ds_read_b128 v[120:123], v255 offset:35840
	ds_read_b128 v[148:151], v255 offset:49152
	ds_read_b128 v[152:155], v255 offset:50176
	ds_read_b128 v[156:159], v255 offset:51200
	ds_read_b128 v[160:163], v255 offset:52224
	s_add_u32 s42, s42, 0x80000
	s_addc_u32 s43, s43, 0
	s_mov_b32 m0, s49
	ds_read_b128 v[164:167], v213 offset:32768
	ds_read_b128 v[190:193], v213 offset:33792
	ds_read_b128 v[194:197], v213 offset:34816
	ds_read_b128 v[198:201], v213 offset:35840
	ds_read_b128 v[214:217], v213 offset:36864
	ds_read_b128 v[218:221], v213 offset:37888
	ds_read_b128 v[222:225], v213 offset:38912
	ds_read_b128 v[226:229], v213 offset:39936
	global_load_lds_dwordx4 v184, s[42:43]
	s_mov_b32 m0, s50
	s_nop 0
	global_load_lds_dwordx4 v182, s[42:43]
	s_waitcnt vmcnt(8)
	s_waitcnt lgkmcnt(0)
	s_barrier
	s_setprio 1
	s_waitcnt lgkmcnt(0)
	v_mfma_f32_16x16x32_bf16 v[144:147], v[108:111], v[164:167], v[144:147]
	v_mfma_f32_16x16x32_bf16 v[140:143], v[116:119], v[164:167], v[140:143]
	v_mfma_f32_16x16x32_bf16 v[136:139], v[108:111], v[194:197], v[136:139]
	v_mfma_f32_16x16x32_bf16 v[132:135], v[116:119], v[194:197], v[132:135]
	v_mfma_f32_16x16x32_bf16 v[96:99], v[108:111], v[214:217], v[96:99]
	v_mfma_f32_16x16x32_bf16 v[92:95], v[116:119], v[214:217], v[92:95]
	v_mfma_f32_16x16x32_bf16 v[80:83], v[108:111], v[222:225], v[80:83]
	v_mfma_f32_16x16x32_bf16 v[76:79], v[116:119], v[222:225], v[76:79]
	v_mfma_f32_16x16x32_bf16 v[144:147], v[112:115], v[190:193], v[144:147]
	v_mfma_f32_16x16x32_bf16 v[140:143], v[120:123], v[190:193], v[140:143]
	v_mfma_f32_16x16x32_bf16 v[136:139], v[112:115], v[198:201], v[136:139]
	v_mfma_f32_16x16x32_bf16 v[132:135], v[120:123], v[198:201], v[132:135]
	v_mfma_f32_16x16x32_bf16 v[96:99], v[112:115], v[218:221], v[96:99]
	v_mfma_f32_16x16x32_bf16 v[92:95], v[120:123], v[218:221], v[92:95]
	v_mfma_f32_16x16x32_bf16 v[80:83], v[112:115], v[226:229], v[80:83]
	v_mfma_f32_16x16x32_bf16 v[76:79], v[120:123], v[226:229], v[76:79]
	s_setprio 0
	s_setprio 1
	v_mfma_f32_16x16x32_bf16 v[128:131], v[148:151], v[164:167], v[128:131]
	v_mfma_f32_16x16x32_bf16 v[124:127], v[156:159], v[164:167], v[124:127]
	v_mfma_f32_16x16x32_bf16 v[104:107], v[148:151], v[194:197], v[104:107]
	v_mfma_f32_16x16x32_bf16 v[100:103], v[156:159], v[194:197], v[100:103]
	v_mfma_f32_16x16x32_bf16 v[88:91], v[148:151], v[214:217], v[88:91]
	v_mfma_f32_16x16x32_bf16 v[84:87], v[156:159], v[214:217], v[84:87]
	v_mfma_f32_16x16x32_bf16 v[72:75], v[148:151], v[222:225], v[72:75]
	v_mfma_f32_16x16x32_bf16 v[68:71], v[156:159], v[222:225], v[68:71]
	v_mfma_f32_16x16x32_bf16 v[128:131], v[152:155], v[190:193], v[128:131]
	v_mfma_f32_16x16x32_bf16 v[124:127], v[160:163], v[190:193], v[124:127]
	v_mfma_f32_16x16x32_bf16 v[104:107], v[152:155], v[198:201], v[104:107]
	v_mfma_f32_16x16x32_bf16 v[100:103], v[160:163], v[198:201], v[100:103]
	v_mfma_f32_16x16x32_bf16 v[88:91], v[152:155], v[218:221], v[88:91]
	v_mfma_f32_16x16x32_bf16 v[84:87], v[160:163], v[218:221], v[84:87]
	v_mfma_f32_16x16x32_bf16 v[72:75], v[152:155], v[226:229], v[72:75]
	v_mfma_f32_16x16x32_bf16 v[68:71], v[160:163], v[226:229], v[68:71]
	s_setprio 0
	s_barrier
	s_add_i32 s42, s74, s46
	s_mov_b32 m0, s42
	ds_read_b128 v[164:167], v213 offset:49152
	ds_read_b128 v[190:193], v213 offset:50176
	ds_read_b128 v[194:197], v213 offset:51200
	ds_read_b128 v[198:201], v213 offset:52224
	ds_read_b128 v[214:217], v213 offset:53248
	ds_read_b128 v[218:221], v213 offset:54272
	ds_read_b128 v[222:225], v213 offset:55296
	ds_read_b128 v[226:229], v213 offset:56320
	global_load_lds_dwordx4 v2, s[98:99]
	s_add_i32 m0, s42, 0x2000
	s_add_u32 s26, s26, 0x80080
	s_addc_u32 s27, s27, 0
	s_add_i32 s42, s75, s46
	global_load_lds_dwordx4 v0, s[98:99]
	s_mov_b32 m0, s42
	s_nop 0
	global_load_lds_dwordx4 v2, s[26:27]
	s_add_i32 m0, s42, 0x2000
	s_nop 0
	global_load_lds_dwordx4 v0, s[26:27]
	s_mov_b32 m0, s54
	s_nop 0
	global_load_lds_dwordx4 v184, s[100:101]
	s_mov_b32 m0, s55
	s_nop 0
	global_load_lds_dwordx4 v182, s[100:101]
	s_waitcnt vmcnt(8)
	s_waitcnt lgkmcnt(0)
	s_barrier
	s_setprio 1
	s_waitcnt lgkmcnt(0)
	v_mfma_f32_16x16x32_bf16 v[64:67], v[108:111], v[164:167], v[64:67]
	v_mfma_f32_16x16x32_bf16 v[60:63], v[116:119], v[164:167], v[60:63]
	v_mfma_f32_16x16x32_bf16 v[48:51], v[108:111], v[194:197], v[48:51]
	v_mfma_f32_16x16x32_bf16 v[44:47], v[116:119], v[194:197], v[44:47]
	v_mfma_f32_16x16x32_bf16 v[32:35], v[108:111], v[214:217], v[32:35]
	v_mfma_f32_16x16x32_bf16 v[28:31], v[116:119], v[214:217], v[28:31]
	v_mfma_f32_16x16x32_bf16 v[16:19], v[108:111], v[222:225], v[16:19]
	v_mfma_f32_16x16x32_bf16 v[12:15], v[116:119], v[222:225], v[12:15]
	v_mfma_f32_16x16x32_bf16 v[64:67], v[112:115], v[190:193], v[64:67]
	v_mfma_f32_16x16x32_bf16 v[60:63], v[120:123], v[190:193], v[60:63]
	v_mfma_f32_16x16x32_bf16 v[48:51], v[112:115], v[198:201], v[48:51]
	v_mfma_f32_16x16x32_bf16 v[44:47], v[120:123], v[198:201], v[44:47]
	v_mfma_f32_16x16x32_bf16 v[32:35], v[112:115], v[218:221], v[32:35]
	v_mfma_f32_16x16x32_bf16 v[28:31], v[120:123], v[218:221], v[28:31]
	v_mfma_f32_16x16x32_bf16 v[16:19], v[112:115], v[226:229], v[16:19]
	v_mfma_f32_16x16x32_bf16 v[12:15], v[120:123], v[226:229], v[12:15]
	s_setprio 0
	s_setprio 1
	v_mfma_f32_16x16x32_bf16 v[56:59], v[148:151], v[164:167], v[56:59]
	v_mfma_f32_16x16x32_bf16 v[52:55], v[156:159], v[164:167], v[52:55]
	v_mfma_f32_16x16x32_bf16 v[40:43], v[148:151], v[194:197], v[40:43]
	v_mfma_f32_16x16x32_bf16 v[36:39], v[156:159], v[194:197], v[36:39]
	v_mfma_f32_16x16x32_bf16 v[24:27], v[148:151], v[214:217], v[24:27]
	v_mfma_f32_16x16x32_bf16 v[20:23], v[156:159], v[214:217], v[20:23]
	v_mfma_f32_16x16x32_bf16 v[8:11], v[148:151], v[222:225], v[8:11]
	v_mfma_f32_16x16x32_bf16 v[4:7], v[156:159], v[222:225], v[4:7]
	v_mfma_f32_16x16x32_bf16 v[56:59], v[152:155], v[190:193], v[56:59]
	v_mfma_f32_16x16x32_bf16 v[52:55], v[160:163], v[190:193], v[52:55]
	v_mfma_f32_16x16x32_bf16 v[40:43], v[152:155], v[198:201], v[40:43]
	v_mfma_f32_16x16x32_bf16 v[36:39], v[160:163], v[198:201], v[36:39]
	v_mfma_f32_16x16x32_bf16 v[24:27], v[152:155], v[218:221], v[24:27]
	v_mfma_f32_16x16x32_bf16 v[20:23], v[160:163], v[218:221], v[20:23]
	v_mfma_f32_16x16x32_bf16 v[8:11], v[152:155], v[226:229], v[8:11]
	v_mfma_f32_16x16x32_bf16 v[4:7], v[160:163], v[226:229], v[4:7]
	s_setprio 0
	s_barrier
	s_add_i32 s67, s67, 2
	s_add_u32 s59, s59, 0x100
	s_addc_u32 s66, s66, 0
	s_add_u32 s18, s18, 0x100
	s_addc_u32 s19, s19, 0
	s_cmp_gt_u32 s67, 29
	s_cbranch_scc0 .LBB0_661
	s_and_b64 vcc, exec, s[38:39]
	s_cbranch_vccz .LBB0_664
	s_barrier

; #define PG8_STAGE(bufoff, gbase, voff) do { _Pragma("unroll") for (int _i = 0; _i < 2; ++_i) \
;         __builtin_amdgcn_global_load_lds((const unsigned*)((const char*)(gbase) + (voff)[_i]), (PG8_LAS unsigned*)(lds + (bufoff) + ldsw + _i * 8192), 16, 0, 0); } while (0)
; #define PG8_LDA(dst, b, h) do { _Pragma("unroll") for (int m = 0; m < 4; ++m) _Pragma("unroll") for (int k = 0; k < 2; ++k) dst[m][k] = *(const PG8_LAS bf16x8*)(lds + PG8_SA(b, h) + aoff + m * 2048 + k * 1024); } while (0)
; #define PG8_LDB(dst, b, h) do { _Pragma("unroll") for (int n = 0; n < 2; ++n) _Pragma("unroll") for (int k = 0; k < 2; ++k) dst[n][k] = *(const PG8_LAS bf16x8*)(lds + PG8_SB(b, h) + boff + n * 2048 + k * 1024); } while (0)
; #define PG8_WAIT_V(n) asm volatile("s_waitcnt vmcnt(" #n ")" ::: "memory")
; #define PG8_WAIT_L(n) asm volatile("s_waitcnt lgkmcnt(" #n ")" ::: "memory")
; #define PG8_BAR __builtin_amdgcn_s_barrier()
; template <class Epi, class Sched, bool ALIGN_EPI = false, bool SP2 = false>
; __device__ __forceinline__ void gemm_phase(PG8_LAS unsigned char* lds, const Gemm g, const Sched& S, const Epi& E, int wave_s) {
;     ...
;         const bool has_next = S.next(ui + 1, nxt);
;         const char* nA = has_next ? (const char*)g.A + (size_t)nxt.pm * tstepA : cA; const char* nB = has_next ? (const char*)g.Bt + (size_t)nxt.pn * tstepB : cB;
;         for (int t = 0; t < nt; t += 2) {
;             const bool last = (t == nt - 2);
;             const char* a1 = cA + (size_t)(t + 1) * kstep;
;             const char* a2 = last ? nA : cA + (size_t)(t + 2) * kstep; const char* b2 = last ? nB : cB + (size_t)(t + 2) * kstep;
;             const char* a3 = a2 + kstep; const char* b3 = b2 + kstep;
;             if (last && has_next) S.a_ready(nxt);
;             if constexpr (SP2) {
;             PG8_LDB(B0, 0, 0); PG8_LDB(B1, 0, 1); PG8_SCHED; PG8_LDA(At, 0, 0); PG8_STAGE(PG8_SA(1, 1), a1 + hstepA, voffA);
;             PG8_WAIT_V(8); PG8_WAIT_L(0); PG8_BAR; PG8_MMA(0, 0, At, B0); PG8_MMA(0, 1, At, B1); PG8_BAR; PG8_SCHED;
;     ...
;         for (int a = 0; a < 2; ++a)
; #pragma unroll
;             for (int b = 0; b < 2; ++b)
; #pragma unroll
;                 for (int m = 0; m < 4; ++m)
; #pragma unroll
;                     for (int n = 0; n < 2; ++n) acc[a][b][m][n] = (f32x4){0.f, 0.f, 0.f, 0.f};
;         cur = nxt; cA = nA; cB = nB; ++ui;
.LBB0_789:
	s_ashr_i32 s21, s20, 31
	s_lshl_b64 s[22:23], s[20:21], 20
	s_add_u32 s22, s2, s22
	s_addc_u32 s23, s30, s23
	s_and_b64 s[24:25], s[36:37], exec
	s_cselect_b32 s21, s23, s27
	s_cselect_b32 s51, s22, s26
	s_ashr_i32 s17, s16, 31
	s_lshl_b64 s[24:25], s[16:17], 20
	s_add_u32 s24, s40, s24
	s_addc_u32 s25, s41, s25
	s_and_b64 s[38:39], s[36:37], exec
	s_cselect_b32 s17, s25, s19
	s_cselect_b32 s52, s24, s18
	s_add_u32 s53, s18, 0x100
	s_addc_u32 s54, s19, 0
	s_add_u32 s18, s26, 0x80080
	v_mov_b32_e32 v4, 0
	s_addc_u32 s19, s27, 0
	s_mov_b32 s55, -2
	v_mov_b32_e32 v5, v4
	v_mov_b32_e32 v6, v4
	v_mov_b32_e32 v7, v4
	v_mov_b32_e32 v12, v4
	v_mov_b32_e32 v13, v4
	v_mov_b32_e32 v14, v4
	v_mov_b32_e32 v15, v4
	v_mov_b32_e32 v20, v4
	v_mov_b32_e32 v21, v4
	v_mov_b32_e32 v22, v4
	v_mov_b32_e32 v23, v4
	v_mov_b32_e32 v28, v4
	v_mov_b32_e32 v29, v4
	v_mov_b32_e32 v30, v4
	v_mov_b32_e32 v31, v4
	v_mov_b32_e32 v36, v4
	v_mov_b32_e32 v37, v4
	v_mov_b32_e32 v38, v4
	v_mov_b32_e32 v39, v4
	v_mov_b32_e32 v44, v4
	v_mov_b32_e32 v45, v4
	v_mov_b32_e32 v46, v4
	v_mov_b32_e32 v47, v4
	v_mov_b32_e32 v52, v4
	v_mov_b32_e32 v53, v4
	v_mov_b32_e32 v54, v4
	v_mov_b32_e32 v55, v4
	v_mov_b32_e32 v60, v4
	v_mov_b32_e32 v61, v4
	v_mov_b32_e32 v62, v4
	v_mov_b32_e32 v63, v4
	v_mov_b32_e32 v8, v4
	v_mov_b32_e32 v9, v4
	v_mov_b32_e32 v10, v4
	v_mov_b32_e32 v11, v4
	v_mov_b32_e32 v16, v4
	v_mov_b32_e32 v17, v4
	v_mov_b32_e32 v18, v4
	v_mov_b32_e32 v19, v4
	v_mov_b32_e32 v24, v4
	v_mov_b32_e32 v25, v4
	v_mov_b32_e32 v26, v4
	v_mov_b32_e32 v27, v4
	v_mov_b32_e32 v32, v4
	v_mov_b32_e32 v33, v4
	v_mov_b32_e32 v34, v4
	v_mov_b32_e32 v35, v4
	v_mov_b32_e32 v40, v4
	v_mov_b32_e32 v41, v4
	v_mov_b32_e32 v42, v4
	v_mov_b32_e32 v43, v4
	v_mov_b32_e32 v48, v4
	v_mov_b32_e32 v49, v4
	v_mov_b32_e32 v50, v4
	v_mov_b32_e32 v51, v4
	v_mov_b32_e32 v56, v4
	v_mov_b32_e32 v57, v4
	v_mov_b32_e32 v58, v4
	v_mov_b32_e32 v59, v4
	v_mov_b32_e32 v64, v4
	v_mov_b32_e32 v65, v4
	v_mov_b32_e32 v66, v4
	v_mov_b32_e32 v67, v4
	v_mov_b32_e32 v68, v4
	v_mov_b32_e32 v69, v4
	v_mov_b32_e32 v70, v4
	v_mov_b32_e32 v71, v4
	v_mov_b32_e32 v76, v4
	v_mov_b32_e32 v77, v4
	v_mov_b32_e32 v78, v4
	v_mov_b32_e32 v79, v4
	v_mov_b32_e32 v84, v4
	v_mov_b32_e32 v85, v4
	v_mov_b32_e32 v86, v4
	v_mov_b32_e32 v87, v4
	v_mov_b32_e32 v92, v4
	v_mov_b32_e32 v93, v4
	v_mov_b32_e32 v94, v4
	v_mov_b32_e32 v95, v4
	v_mov_b32_e32 v100, v4
	v_mov_b32_e32 v101, v4
	v_mov_b32_e32 v102, v4
	v_mov_b32_e32 v103, v4
	s_waitcnt lgkmcnt(0)
	v_mov_b32_e32 v108, v4
	v_mov_b32_e32 v109, v4
	v_mov_b32_e32 v110, v4
	v_mov_b32_e32 v111, v4
	v_mov_b32_e32 v116, v4
	v_mov_b32_e32 v117, v4
	v_mov_b32_e32 v118, v4
	v_mov_b32_e32 v119, v4
	v_mov_b32_e32 v124, v4
	v_mov_b32_e32 v125, v4
	v_mov_b32_e32 v126, v4
	v_mov_b32_e32 v127, v4
	v_mov_b32_e32 v72, v4
	v_mov_b32_e32 v73, v4
	v_mov_b32_e32 v74, v4
	v_mov_b32_e32 v75, v4
	v_mov_b32_e32 v80, v4
	v_mov_b32_e32 v81, v4
	v_mov_b32_e32 v82, v4
	v_mov_b32_e32 v83, v4
	v_mov_b32_e32 v88, v4
	v_mov_b32_e32 v89, v4
	v_mov_b32_e32 v90, v4
	v_mov_b32_e32 v91, v4
	v_mov_b32_e32 v96, v4
	v_mov_b32_e32 v97, v4
	v_mov_b32_e32 v98, v4
	v_mov_b32_e32 v99, v4
	v_mov_b32_e32 v104, v4
	v_mov_b32_e32 v105, v4
	v_mov_b32_e32 v106, v4
	v_mov_b32_e32 v107, v4
	v_mov_b32_e32 v112, v4
	v_mov_b32_e32 v113, v4
	v_mov_b32_e32 v114, v4
	v_mov_b32_e32 v115, v4
	v_mov_b32_e32 v120, v4
	v_mov_b32_e32 v121, v4
	v_mov_b32_e32 v122, v4
	v_mov_b32_e32 v123, v4
	v_mov_b32_e32 v128, v4
	v_mov_b32_e32 v129, v4
	v_mov_b32_e32 v130, v4
	v_mov_b32_e32 v131, v4
	v_add_u32_e32 v255, 0x10000, v143
.LBB0_790:
	s_add_u32 s26, s18, 0xfff80080
	s_addc_u32 s27, s19, -1
	s_add_i32 s56, 0, 0x10000
	s_cmp_eq_u32 s55, 28
	s_cselect_b32 s39, s21, s27
	s_cselect_b32 s38, s51, s26
	s_cselect_b32 s27, s17, s54
	s_cselect_b32 s26, s52, s53
	s_add_i32 s58, 0, 0x14000
	ds_read_b128 v[146:149], v255
	ds_read_b128 v[150:153], v255 offset:1024
	ds_read_b128 v[154:157], v255 offset:2048
	ds_read_b128 v[158:161], v255 offset:3072
	ds_read_b128 v[162:165], v255 offset:16384
	ds_read_b128 v[182:185], v255 offset:17408
	ds_read_b128 v[186:189], v255 offset:18432
	ds_read_b128 v[190:193], v255 offset:19456
	s_add_i32 m0, s43, 0xc000
	ds_read_b128 v[194:197], v145
	ds_read_b128 v[198:201], v145 offset:1024
	ds_read_b128 v[212:215], v145 offset:2048
	ds_read_b128 v[216:219], v145 offset:3072
	ds_read_b128 v[220:223], v145 offset:4096
	ds_read_b128 v[224:227], v145 offset:5120
	ds_read_b128 v[228:231], v145 offset:6144
	ds_read_b128 v[232:235], v145 offset:7168
	global_load_lds_dwordx4 v138, s[18:19]
	s_add_i32 m0, s43, 0xe000
	s_nop 0
	global_load_lds_dwordx4 v136, s[18:19]
	s_waitcnt vmcnt(8)
	s_waitcnt lgkmcnt(0)
	s_barrier
; #define PG8_STAGE(bufoff, gbase, voff) do { _Pragma("unroll") for (int _i = 0; _i < 2; ++_i) \
;         __builtin_amdgcn_global_load_lds((const unsigned*)((const char*)(gbase) + (voff)[_i]), (PG8_LAS unsigned*)(lds + (bufoff) + ldsw + _i * 8192), 16, 0, 0); } while (0)
; #define PG8_LDA(dst, b, h) do { _Pragma("unroll") for (int m = 0; m < 4; ++m) _Pragma("unroll") for (int k = 0; k < 2; ++k) dst[m][k] = *(const PG8_LAS bf16x8*)(lds + PG8_SA(b, h) + aoff + m * 2048 + k * 1024); } while (0)
; #define PG8_MMA(ai, bj, At, Bt) do { __builtin_amdgcn_s_setprio(1); _Pragma("unroll") for (int m = 0; m < 4; ++m) _Pragma("unroll") for (int n = 0; n < 2; ++n) _Pragma("unroll") for (int k = 0; k < 2; ++k) \
;         acc[ai][bj][m][n] = __builtin_amdgcn_mfma_f32_16x16x32_bf16(Bt[n][k], At[m][k], acc[ai][bj][m][n], 0, 0, 0); __builtin_amdgcn_s_setprio(0); } while (0)
; #define PG8_WAIT_V(n) asm volatile("s_waitcnt vmcnt(" #n ")" ::: "memory")
; #define PG8_WAIT_L(n) asm volatile("s_waitcnt lgkmcnt(" #n ")" ::: "memory")
; #define PG8_BAR __builtin_amdgcn_s_barrier()
; #define PG8_SCHED __builtin_amdgcn_sched_barrier(0)
; template <class Epi, class Sched, bool ALIGN_EPI = false, bool SP2 = false>
; __device__ __forceinline__ void gemm_phase(PG8_LAS unsigned char* lds, const Gemm g, const Sched& S, const Epi& E, int wave_s) {
;     ...
;             PG8_WAIT_V(8); PG8_WAIT_L(0); PG8_BAR; PG8_MMA(0, 0, At, B0); PG8_MMA(0, 1, At, B1); PG8_BAR; PG8_SCHED;
;             PG8_LDA(At, 0, 1); PG8_STAGE(PG8_SB(0, 0), b2, voffB); PG8_STAGE(PG8_SB(0, 1), b2 + hstepB, voffB); PG8_STAGE(PG8_SA(0, 0), a2, voffA);
;             PG8_WAIT_V(8); PG8_WAIT_L(0); PG8_BAR; PG8_MMA(1, 0, At, B0); PG8_MMA(1, 1, At, B1); PG8_BAR; PG8_SCHED;
	s_setprio 1
	s_waitcnt lgkmcnt(0)
	v_mfma_f32_16x16x32_bf16 v[128:131], v[146:149], v[194:197], v[128:131]
	v_mfma_f32_16x16x32_bf16 v[120:123], v[154:157], v[194:197], v[120:123]
	v_mfma_f32_16x16x32_bf16 v[112:115], v[146:149], v[212:215], v[112:115]
	v_mfma_f32_16x16x32_bf16 v[104:107], v[154:157], v[212:215], v[104:107]
	v_mfma_f32_16x16x32_bf16 v[96:99], v[146:149], v[220:223], v[96:99]
	v_mfma_f32_16x16x32_bf16 v[88:91], v[154:157], v[220:223], v[88:91]
	v_mfma_f32_16x16x32_bf16 v[80:83], v[146:149], v[228:231], v[80:83]
	v_mfma_f32_16x16x32_bf16 v[72:75], v[154:157], v[228:231], v[72:75]
	v_mfma_f32_16x16x32_bf16 v[128:131], v[150:153], v[198:201], v[128:131]
	v_mfma_f32_16x16x32_bf16 v[120:123], v[158:161], v[198:201], v[120:123]
	v_mfma_f32_16x16x32_bf16 v[112:115], v[150:153], v[216:219], v[112:115]
	v_mfma_f32_16x16x32_bf16 v[104:107], v[158:161], v[216:219], v[104:107]
	v_mfma_f32_16x16x32_bf16 v[96:99], v[150:153], v[224:227], v[96:99]
	v_mfma_f32_16x16x32_bf16 v[88:91], v[158:161], v[224:227], v[88:91]
	v_mfma_f32_16x16x32_bf16 v[80:83], v[150:153], v[232:235], v[80:83]
	v_mfma_f32_16x16x32_bf16 v[72:75], v[158:161], v[232:235], v[72:75]
	s_setprio 0
	s_setprio 1
	v_mfma_f32_16x16x32_bf16 v[124:127], v[162:165], v[194:197], v[124:127]
	v_mfma_f32_16x16x32_bf16 v[116:119], v[186:189], v[194:197], v[116:119]
	v_mfma_f32_16x16x32_bf16 v[108:111], v[162:165], v[212:215], v[108:111]
	v_mfma_f32_16x16x32_bf16 v[100:103], v[186:189], v[212:215], v[100:103]
	v_mfma_f32_16x16x32_bf16 v[92:95], v[162:165], v[220:223], v[92:95]
	v_mfma_f32_16x16x32_bf16 v[84:87], v[186:189], v[220:223], v[84:87]
	v_mfma_f32_16x16x32_bf16 v[76:79], v[162:165], v[228:231], v[76:79]
	v_mfma_f32_16x16x32_bf16 v[68:71], v[186:189], v[228:231], v[68:71]
	v_mfma_f32_16x16x32_bf16 v[124:127], v[182:185], v[198:201], v[124:127]
	v_mfma_f32_16x16x32_bf16 v[116:119], v[190:193], v[198:201], v[116:119]
	v_mfma_f32_16x16x32_bf16 v[108:111], v[182:185], v[216:219], v[108:111]
	v_mfma_f32_16x16x32_bf16 v[100:103], v[190:193], v[216:219], v[100:103]
	v_mfma_f32_16x16x32_bf16 v[92:95], v[182:185], v[224:227], v[92:95]
	v_mfma_f32_16x16x32_bf16 v[84:87], v[190:193], v[224:227], v[84:87]
	v_mfma_f32_16x16x32_bf16 v[76:79], v[182:185], v[232:235], v[76:79]
	v_mfma_f32_16x16x32_bf16 v[68:71], v[190:193], v[232:235], v[68:71]
	s_setprio 0
	s_barrier
	s_add_i32 s56, s56, s42
	s_add_u32 s98, s26, s60
	s_addc_u32 s99, s27, s61
	s_mov_b32 m0, s56
	ds_read_b128 v[194:197], v145 offset:16384
	ds_read_b128 v[198:201], v145 offset:17408
	ds_read_b128 v[212:215], v145 offset:18432
	ds_read_b128 v[216:219], v145 offset:19456
	ds_read_b128 v[220:223], v145 offset:20480
	ds_read_b128 v[224:227], v145 offset:21504
	ds_read_b128 v[228:231], v145 offset:22528
	ds_read_b128 v[232:235], v145 offset:23552
	global_load_lds_dwordx4 v2, s[26:27]
	s_add_i32 m0, s56, 0x2000
	s_add_u32 s56, s26, 0x80000
	s_addc_u32 s57, s27, 0
	s_add_i32 s58, s58, s42
	global_load_lds_dwordx4 v0, s[26:27]
	s_mov_b32 m0, s58
	s_add_u32 s100, s38, s60
	s_addc_u32 s101, s39, s61
	s_nop 0
	global_load_lds_dwordx4 v2, s[56:57]
	s_add_i32 m0, s58, 0x2000
	s_nop 0
	global_load_lds_dwordx4 v0, s[56:57]
	s_mov_b32 m0, s43
	s_nop 0
	global_load_lds_dwordx4 v134, s[38:39]
	s_mov_b32 m0, s44
	s_nop 0
	global_load_lds_dwordx4 v132, s[38:39]
	s_waitcnt vmcnt(8)
	s_waitcnt lgkmcnt(0)
	s_barrier
	s_setprio 1
	s_waitcnt lgkmcnt(0)
	v_mfma_f32_16x16x32_bf16 v[64:67], v[146:149], v[194:197], v[64:67]
	v_mfma_f32_16x16x32_bf16 v[56:59], v[154:157], v[194:197], v[56:59]
	v_mfma_f32_16x16x32_bf16 v[48:51], v[146:149], v[212:215], v[48:51]
	v_mfma_f32_16x16x32_bf16 v[40:43], v[154:157], v[212:215], v[40:43]
	v_mfma_f32_16x16x32_bf16 v[32:35], v[146:149], v[220:223], v[32:35]
	v_mfma_f32_16x16x32_bf16 v[24:27], v[154:157], v[220:223], v[24:27]
	v_mfma_f32_16x16x32_bf16 v[16:19], v[146:149], v[228:231], v[16:19]
	v_mfma_f32_16x16x32_bf16 v[8:11], v[154:157], v[228:231], v[8:11]
	v_mfma_f32_16x16x32_bf16 v[64:67], v[150:153], v[198:201], v[64:67]
	v_mfma_f32_16x16x32_bf16 v[56:59], v[158:161], v[198:201], v[56:59]
	v_mfma_f32_16x16x32_bf16 v[48:51], v[150:153], v[216:219], v[48:51]
	v_mfma_f32_16x16x32_bf16 v[40:43], v[158:161], v[216:219], v[40:43]
	v_mfma_f32_16x16x32_bf16 v[32:35], v[150:153], v[224:227], v[32:35]
	v_mfma_f32_16x16x32_bf16 v[24:27], v[158:161], v[224:227], v[24:27]
	v_mfma_f32_16x16x32_bf16 v[16:19], v[150:153], v[232:235], v[16:19]
	v_mfma_f32_16x16x32_bf16 v[8:11], v[158:161], v[232:235], v[8:11]
	s_setprio 0
	s_setprio 1
	v_mfma_f32_16x16x32_bf16 v[60:63], v[162:165], v[194:197], v[60:63]
	v_mfma_f32_16x16x32_bf16 v[52:55], v[186:189], v[194:197], v[52:55]
	v_mfma_f32_16x16x32_bf16 v[44:47], v[162:165], v[212:215], v[44:47]
	v_mfma_f32_16x16x32_bf16 v[36:39], v[186:189], v[212:215], v[36:39]
	v_mfma_f32_16x16x32_bf16 v[28:31], v[162:165], v[220:223], v[28:31]
	v_mfma_f32_16x16x32_bf16 v[20:23], v[186:189], v[220:223], v[20:23]
	v_mfma_f32_16x16x32_bf16 v[12:15], v[162:165], v[228:231], v[12:15]
	v_mfma_f32_16x16x32_bf16 v[4:7], v[186:189], v[228:231], v[4:7]
	v_mfma_f32_16x16x32_bf16 v[60:63], v[182:185], v[198:201], v[60:63]
	v_mfma_f32_16x16x32_bf16 v[52:55], v[190:193], v[198:201], v[52:55]
	v_mfma_f32_16x16x32_bf16 v[44:47], v[182:185], v[216:219], v[44:47]
	v_mfma_f32_16x16x32_bf16 v[36:39], v[190:193], v[216:219], v[36:39]
	v_mfma_f32_16x16x32_bf16 v[28:31], v[182:185], v[224:227], v[28:31]
	v_mfma_f32_16x16x32_bf16 v[20:23], v[190:193], v[224:227], v[20:23]
	v_mfma_f32_16x16x32_bf16 v[12:15], v[182:185], v[232:235], v[12:15]
	v_mfma_f32_16x16x32_bf16 v[4:7], v[190:193], v[232:235], v[4:7]
	s_setprio 0
	s_barrier
; #define PG8_STAGE(bufoff, gbase, voff) do { _Pragma("unroll") for (int _i = 0; _i < 2; ++_i) \
;         __builtin_amdgcn_global_load_lds((const unsigned*)((const char*)(gbase) + (voff)[_i]), (PG8_LAS unsigned*)(lds + (bufoff) + ldsw + _i * 8192), 16, 0, 0); } while (0)
; #define PG8_LDA(dst, b, h) do { _Pragma("unroll") for (int m = 0; m < 4; ++m) _Pragma("unroll") for (int k = 0; k < 2; ++k) dst[m][k] = *(const PG8_LAS bf16x8*)(lds + PG8_SA(b, h) + aoff + m * 2048 + k * 1024); } while (0)
; #define PG8_LDB(dst, b, h) do { _Pragma("unroll") for (int n = 0; n < 2; ++n) _Pragma("unroll") for (int k = 0; k < 2; ++k) dst[n][k] = *(const PG8_LAS bf16x8*)(lds + PG8_SB(b, h) + boff + n * 2048 + k * 1024); } while (0)
; #define PG8_MMA(ai, bj, At, Bt) do { __builtin_amdgcn_s_setprio(1); _Pragma("unroll") for (int m = 0; m < 4; ++m) _Pragma("unroll") for (int n = 0; n < 2; ++n) _Pragma("unroll") for (int k = 0; k < 2; ++k) \
;         acc[ai][bj][m][n] = __builtin_amdgcn_mfma_f32_16x16x32_bf16(Bt[n][k], At[m][k], acc[ai][bj][m][n], 0, 0, 0); __builtin_amdgcn_s_setprio(0); } while (0)
; #define PG8_WAIT_V(n) asm volatile("s_waitcnt vmcnt(" #n ")" ::: "memory")
; #define PG8_WAIT_L(n) asm volatile("s_waitcnt lgkmcnt(" #n ")" ::: "memory")
; template <class Epi, class Sched, bool ALIGN_EPI = false, bool SP2 = false>
; __device__ __forceinline__ void gemm_phase(PG8_LAS unsigned char* lds, const Gemm g, const Sched& S, const Epi& E, int wave_s) {
;     ...
;         for (int t = 0; t < nt; t += 2) {
;             const bool last = (t == nt - 2);
;             const char* a1 = cA + (size_t)(t + 1) * kstep;
;             const char* a2 = last ? nA : cA + (size_t)(t + 2) * kstep; const char* b2 = last ? nB : cB + (size_t)(t + 2) * kstep;
;             const char* a3 = a2 + kstep; const char* b3 = b2 + kstep;
;             if (last && has_next) S.a_ready(nxt);
;     ...
;             PG8_LDB(B0, 1, 0); PG8_LDB(B1, 1, 1); PG8_SCHED; PG8_LDA(At, 1, 0); PG8_STAGE(PG8_SA(0, 1), a2 + hstepA, voffA);
;             PG8_WAIT_V(8); PG8_WAIT_L(0); PG8_BAR; PG8_MMA(0, 0, At, B0); PG8_MMA(0, 1, At, B1); PG8_BAR; PG8_SCHED;
;             PG8_LDA(At, 1, 1); PG8_STAGE(PG8_SB(1, 0), b3, voffB); PG8_STAGE(PG8_SB(1, 1), b3 + hstepB, voffB); PG8_STAGE(PG8_SA(1, 0), a3, voffA);
;             PG8_WAIT_V(8); PG8_WAIT_L(0); PG8_BAR; PG8_MMA(1, 0, At, B0); PG8_MMA(1, 1, At, B1); PG8_BAR; PG8_SCHED;
	s_add_i32 s56, 0, 0x18000
	s_add_i32 s57, 0, 0x1c000
	ds_read_b128 v[146:149], v255 offset:32768
	ds_read_b128 v[150:153], v255 offset:33792
	ds_read_b128 v[154:157], v255 offset:34816
	ds_read_b128 v[158:161], v255 offset:35840
	ds_read_b128 v[162:165], v255 offset:49152
	ds_read_b128 v[182:185], v255 offset:50176
	ds_read_b128 v[186:189], v255 offset:51200
	ds_read_b128 v[190:193], v255 offset:52224
	s_add_u32 s38, s38, 0x80000
	s_addc_u32 s39, s39, 0
	s_mov_b32 m0, s45
	ds_read_b128 v[194:197], v145 offset:32768
	ds_read_b128 v[198:201], v145 offset:33792
	ds_read_b128 v[212:215], v145 offset:34816
	ds_read_b128 v[216:219], v145 offset:35840
	ds_read_b128 v[220:223], v145 offset:36864
	ds_read_b128 v[224:227], v145 offset:37888
	ds_read_b128 v[228:231], v145 offset:38912
	ds_read_b128 v[232:235], v145 offset:39936
	global_load_lds_dwordx4 v134, s[38:39]
	s_mov_b32 m0, s46
	s_nop 0
	global_load_lds_dwordx4 v132, s[38:39]
	s_waitcnt vmcnt(8)
	s_waitcnt lgkmcnt(0)
	s_barrier
	s_setprio 1
	s_waitcnt lgkmcnt(0)
	v_mfma_f32_16x16x32_bf16 v[128:131], v[146:149], v[194:197], v[128:131]
	v_mfma_f32_16x16x32_bf16 v[120:123], v[154:157], v[194:197], v[120:123]
	v_mfma_f32_16x16x32_bf16 v[112:115], v[146:149], v[212:215], v[112:115]
	v_mfma_f32_16x16x32_bf16 v[104:107], v[154:157], v[212:215], v[104:107]
	v_mfma_f32_16x16x32_bf16 v[96:99], v[146:149], v[220:223], v[96:99]
	v_mfma_f32_16x16x32_bf16 v[88:91], v[154:157], v[220:223], v[88:91]
	v_mfma_f32_16x16x32_bf16 v[80:83], v[146:149], v[228:231], v[80:83]
	v_mfma_f32_16x16x32_bf16 v[72:75], v[154:157], v[228:231], v[72:75]
	v_mfma_f32_16x16x32_bf16 v[128:131], v[150:153], v[198:201], v[128:131]
	v_mfma_f32_16x16x32_bf16 v[120:123], v[158:161], v[198:201], v[120:123]
	v_mfma_f32_16x16x32_bf16 v[112:115], v[150:153], v[216:219], v[112:115]
	v_mfma_f32_16x16x32_bf16 v[104:107], v[158:161], v[216:219], v[104:107]
	v_mfma_f32_16x16x32_bf16 v[96:99], v[150:153], v[224:227], v[96:99]
	v_mfma_f32_16x16x32_bf16 v[88:91], v[158:161], v[224:227], v[88:91]
	v_mfma_f32_16x16x32_bf16 v[80:83], v[150:153], v[232:235], v[80:83]
	v_mfma_f32_16x16x32_bf16 v[72:75], v[158:161], v[232:235], v[72:75]
	s_setprio 0
	s_setprio 1
	v_mfma_f32_16x16x32_bf16 v[124:127], v[162:165], v[194:197], v[124:127]
	v_mfma_f32_16x16x32_bf16 v[116:119], v[186:189], v[194:197], v[116:119]
	v_mfma_f32_16x16x32_bf16 v[108:111], v[162:165], v[212:215], v[108:111]
	v_mfma_f32_16x16x32_bf16 v[100:103], v[186:189], v[212:215], v[100:103]
	v_mfma_f32_16x16x32_bf16 v[92:95], v[162:165], v[220:223], v[92:95]
	v_mfma_f32_16x16x32_bf16 v[84:87], v[186:189], v[220:223], v[84:87]
	v_mfma_f32_16x16x32_bf16 v[76:79], v[162:165], v[228:231], v[76:79]
	v_mfma_f32_16x16x32_bf16 v[68:71], v[186:189], v[228:231], v[68:71]
	v_mfma_f32_16x16x32_bf16 v[124:127], v[182:185], v[198:201], v[124:127]
	v_mfma_f32_16x16x32_bf16 v[116:119], v[190:193], v[198:201], v[116:119]
	v_mfma_f32_16x16x32_bf16 v[108:111], v[182:185], v[216:219], v[108:111]
	v_mfma_f32_16x16x32_bf16 v[100:103], v[190:193], v[216:219], v[100:103]
	v_mfma_f32_16x16x32_bf16 v[92:95], v[182:185], v[224:227], v[92:95]
	v_mfma_f32_16x16x32_bf16 v[84:87], v[190:193], v[224:227], v[84:87]
	v_mfma_f32_16x16x32_bf16 v[76:79], v[182:185], v[232:235], v[76:79]
	v_mfma_f32_16x16x32_bf16 v[68:71], v[190:193], v[232:235], v[68:71]
	s_setprio 0
	s_barrier
	s_add_i32 s38, s56, s42
	s_mov_b32 m0, s38
	ds_read_b128 v[194:197], v145 offset:49152
	ds_read_b128 v[198:201], v145 offset:50176
	ds_read_b128 v[212:215], v145 offset:51200
	ds_read_b128 v[216:219], v145 offset:52224
	ds_read_b128 v[220:223], v145 offset:53248
	ds_read_b128 v[224:227], v145 offset:54272
	ds_read_b128 v[228:231], v145 offset:55296
	ds_read_b128 v[232:235], v145 offset:56320
	global_load_lds_dwordx4 v2, s[98:99]
	s_add_i32 m0, s38, 0x2000
	s_add_u32 s26, s26, 0x80080
	s_addc_u32 s27, s27, 0
	s_add_i32 s38, s57, s42
	global_load_lds_dwordx4 v0, s[98:99]
	s_mov_b32 m0, s38
	s_nop 0
	global_load_lds_dwordx4 v2, s[26:27]
	s_add_i32 m0, s38, 0x2000
	s_nop 0
	global_load_lds_dwordx4 v0, s[26:27]
	s_mov_b32 m0, s47
	s_nop 0
	global_load_lds_dwordx4 v134, s[100:101]
	s_mov_b32 m0, s48
	s_nop 0
	global_load_lds_dwordx4 v132, s[100:101]
	s_waitcnt vmcnt(8)
	s_waitcnt lgkmcnt(0)
	s_barrier
	s_setprio 1
	s_waitcnt lgkmcnt(0)
	v_mfma_f32_16x16x32_bf16 v[64:67], v[146:149], v[194:197], v[64:67]
	v_mfma_f32_16x16x32_bf16 v[56:59], v[154:157], v[194:197], v[56:59]
	v_mfma_f32_16x16x32_bf16 v[48:51], v[146:149], v[212:215], v[48:51]
	v_mfma_f32_16x16x32_bf16 v[40:43], v[154:157], v[212:215], v[40:43]
	v_mfma_f32_16x16x32_bf16 v[32:35], v[146:149], v[220:223], v[32:35]
	v_mfma_f32_16x16x32_bf16 v[24:27], v[154:157], v[220:223], v[24:27]
	v_mfma_f32_16x16x32_bf16 v[16:19], v[146:149], v[228:231], v[16:19]
	v_mfma_f32_16x16x32_bf16 v[8:11], v[154:157], v[228:231], v[8:11]
	v_mfma_f32_16x16x32_bf16 v[64:67], v[150:153], v[198:201], v[64:67]
	v_mfma_f32_16x16x32_bf16 v[56:59], v[158:161], v[198:201], v[56:59]
	v_mfma_f32_16x16x32_bf16 v[48:51], v[150:153], v[216:219], v[48:51]
	v_mfma_f32_16x16x32_bf16 v[40:43], v[158:161], v[216:219], v[40:43]
	v_mfma_f32_16x16x32_bf16 v[32:35], v[150:153], v[224:227], v[32:35]
	v_mfma_f32_16x16x32_bf16 v[24:27], v[158:161], v[224:227], v[24:27]
	v_mfma_f32_16x16x32_bf16 v[16:19], v[150:153], v[232:235], v[16:19]
	v_mfma_f32_16x16x32_bf16 v[8:11], v[158:161], v[232:235], v[8:11]
	s_setprio 0
	s_setprio 1
	v_mfma_f32_16x16x32_bf16 v[60:63], v[162:165], v[194:197], v[60:63]
	v_mfma_f32_16x16x32_bf16 v[52:55], v[186:189], v[194:197], v[52:55]
	v_mfma_f32_16x16x32_bf16 v[44:47], v[162:165], v[212:215], v[44:47]
	v_mfma_f32_16x16x32_bf16 v[36:39], v[186:189], v[212:215], v[36:39]
	v_mfma_f32_16x16x32_bf16 v[28:31], v[162:165], v[220:223], v[28:31]
	v_mfma_f32_16x16x32_bf16 v[20:23], v[186:189], v[220:223], v[20:23]
	v_mfma_f32_16x16x32_bf16 v[12:15], v[162:165], v[228:231], v[12:15]
	v_mfma_f32_16x16x32_bf16 v[4:7], v[186:189], v[228:231], v[4:7]
	v_mfma_f32_16x16x32_bf16 v[60:63], v[182:185], v[198:201], v[60:63]
	v_mfma_f32_16x16x32_bf16 v[52:55], v[190:193], v[198:201], v[52:55]
	v_mfma_f32_16x16x32_bf16 v[44:47], v[182:185], v[216:219], v[44:47]
	v_mfma_f32_16x16x32_bf16 v[36:39], v[190:193], v[216:219], v[36:39]
	v_mfma_f32_16x16x32_bf16 v[28:31], v[182:185], v[224:227], v[28:31]
	v_mfma_f32_16x16x32_bf16 v[20:23], v[190:193], v[224:227], v[20:23]
	v_mfma_f32_16x16x32_bf16 v[12:15], v[182:185], v[232:235], v[12:15]
	v_mfma_f32_16x16x32_bf16 v[4:7], v[190:193], v[232:235], v[4:7]
	s_setprio 0
	s_barrier
	s_add_i32 s55, s55, 2
	s_add_u32 s53, s53, 0x100
	s_addc_u32 s54, s54, 0
	s_add_u32 s18, s18, 0x100
	s_addc_u32 s19, s19, 0
	s_cmp_gt_u32 s55, 29
	s_cbranch_scc0 .LBB0_790
	s_and_b64 vcc, exec, s[6:7]
	s_cbranch_vccz .LBB0_793
	s_barrier

; #define PG8_STAGE(bufoff, gbase, voff) do { _Pragma("unroll") for (int _i = 0; _i < 2; ++_i) \
;         __builtin_amdgcn_global_load_lds((const unsigned*)((const char*)(gbase) + (voff)[_i]), (PG8_LAS unsigned*)(lds + (bufoff) + ldsw + _i * 8192), 16, 0, 0); } while (0)
; #define PG8_LDA(dst, b, h) do { _Pragma("unroll") for (int m = 0; m < 4; ++m) _Pragma("unroll") for (int k = 0; k < 2; ++k) dst[m][k] = *(const PG8_LAS bf16x8*)(lds + PG8_SA(b, h) + aoff + m * 2048 + k * 1024); } while (0)
; #define PG8_LDB(dst, b, h) do { _Pragma("unroll") for (int n = 0; n < 2; ++n) _Pragma("unroll") for (int k = 0; k < 2; ++k) dst[n][k] = *(const PG8_LAS bf16x8*)(lds + PG8_SB(b, h) + boff + n * 2048 + k * 1024); } while (0)
; #define PG8_MMA(ai, bj, At, Bt) do { __builtin_amdgcn_s_setprio(1); _Pragma("unroll") for (int m = 0; m < 4; ++m) _Pragma("unroll") for (int n = 0; n < 2; ++n) _Pragma("unroll") for (int k = 0; k < 2; ++k) \
;         acc[ai][bj][m][n] = __builtin_amdgcn_mfma_f32_16x16x32_bf16(Bt[n][k], At[m][k], acc[ai][bj][m][n], 0, 0, 0); __builtin_amdgcn_s_setprio(0); } while (0)
; #define PG8_WAIT_V(n) asm volatile("s_waitcnt vmcnt(" #n ")" ::: "memory")
; template <class Epi, class Sched, bool ALIGN_EPI = false, bool SP2 = false>
; __device__ __forceinline__ void gemm_phase(PG8_LAS unsigned char* lds, const Gemm g, const Sched& S, const Epi& E, int wave_s) {
;     ...
;         for (int t = 0; t < nt; t += 2) {
;             const bool last = (t == nt - 2);
;             const char* a1 = cA + (size_t)(t + 1) * kstep;
;             const char* a2 = last ? nA : cA + (size_t)(t + 2) * kstep; const char* b2 = last ? nB : cB + (size_t)(t + 2) * kstep;
;             const char* a3 = a2 + kstep; const char* b3 = b2 + kstep;
;             if (last && has_next) S.a_ready(nxt);
;             if constexpr (SP2) {
;             PG8_LDB(B0, 0, 0); PG8_LDB(B1, 0, 1); PG8_SCHED; PG8_LDA(At, 0, 0); PG8_STAGE(PG8_SA(1, 1), a1 + hstepA, voffA);
;             PG8_WAIT_V(8); PG8_WAIT_L(0); PG8_BAR; PG8_MMA(0, 0, At, B0); PG8_MMA(0, 1, At, B1); PG8_BAR; PG8_SCHED;
;     ...
; #pragma unroll
;         for (int a = 0; a < 2; ++a)
; #pragma unroll
;             for (int b = 0; b < 2; ++b)
; #pragma unroll
;                 for (int m = 0; m < 4; ++m)
; #pragma unroll
;                     for (int n = 0; n < 2; ++n) acc[a][b][m][n] = (f32x4){0.f, 0.f, 0.f, 0.f};
.LBB0_862:
	s_add_u32 s36, s22, 0x100
	v_mov_b32_e32 v4, 0
	s_addc_u32 s37, s23, 0
	s_mov_b32 s53, -2
	v_mov_b32_e32 v5, v4
	v_mov_b32_e32 v6, v4
	v_mov_b32_e32 v7, v4
	v_mov_b32_e32 v8, v4
	v_mov_b32_e32 v9, v4
	v_mov_b32_e32 v10, v4
	v_mov_b32_e32 v11, v4
	v_mov_b32_e32 v20, v4
	v_mov_b32_e32 v21, v4
	v_mov_b32_e32 v22, v4
	v_mov_b32_e32 v23, v4
	v_mov_b32_e32 v24, v4
	v_mov_b32_e32 v25, v4
	v_mov_b32_e32 v26, v4
	v_mov_b32_e32 v27, v4
	v_mov_b32_e32 v36, v4
	v_mov_b32_e32 v37, v4
	v_mov_b32_e32 v38, v4
	v_mov_b32_e32 v39, v4
	v_mov_b32_e32 v40, v4
	v_mov_b32_e32 v41, v4
	v_mov_b32_e32 v42, v4
	v_mov_b32_e32 v43, v4
	v_mov_b32_e32 v52, v4
	v_mov_b32_e32 v53, v4
	v_mov_b32_e32 v54, v4
	v_mov_b32_e32 v55, v4
	v_mov_b32_e32 v56, v4
	v_mov_b32_e32 v57, v4
	v_mov_b32_e32 v58, v4
	v_mov_b32_e32 v59, v4
	v_mov_b32_e32 v12, v4
	v_mov_b32_e32 v13, v4
	v_mov_b32_e32 v14, v4
	v_mov_b32_e32 v15, v4
	v_mov_b32_e32 v16, v4
	v_mov_b32_e32 v17, v4
	v_mov_b32_e32 v18, v4
	v_mov_b32_e32 v19, v4
	v_mov_b32_e32 v28, v4
	v_mov_b32_e32 v29, v4
	v_mov_b32_e32 v30, v4
	v_mov_b32_e32 v31, v4
	v_mov_b32_e32 v32, v4
	v_mov_b32_e32 v33, v4
	v_mov_b32_e32 v34, v4
	v_mov_b32_e32 v35, v4
	v_mov_b32_e32 v44, v4
	v_mov_b32_e32 v45, v4
	v_mov_b32_e32 v46, v4
	v_mov_b32_e32 v47, v4
	v_mov_b32_e32 v48, v4
	v_mov_b32_e32 v49, v4
	v_mov_b32_e32 v50, v4
	v_mov_b32_e32 v51, v4
	v_mov_b32_e32 v60, v4
	v_mov_b32_e32 v61, v4
	v_mov_b32_e32 v62, v4
	v_mov_b32_e32 v63, v4
	v_mov_b32_e32 v64, v4
	v_mov_b32_e32 v65, v4
	v_mov_b32_e32 v66, v4
	v_mov_b32_e32 v67, v4
	v_mov_b32_e32 v68, v4
	v_mov_b32_e32 v69, v4
	v_mov_b32_e32 v70, v4
	v_mov_b32_e32 v71, v4
	v_mov_b32_e32 v72, v4
	v_mov_b32_e32 v73, v4
	v_mov_b32_e32 v74, v4
	v_mov_b32_e32 v75, v4
	v_mov_b32_e32 v84, v4
	v_mov_b32_e32 v85, v4
	v_mov_b32_e32 v86, v4
	v_mov_b32_e32 v87, v4
	v_mov_b32_e32 v88, v4
	v_mov_b32_e32 v89, v4
	v_mov_b32_e32 v90, v4
	v_mov_b32_e32 v91, v4
	v_mov_b32_e32 v100, v4
	v_mov_b32_e32 v101, v4
	v_mov_b32_e32 v102, v4
	v_mov_b32_e32 v103, v4
	v_mov_b32_e32 v104, v4
	v_mov_b32_e32 v105, v4
	v_mov_b32_e32 v106, v4
	v_mov_b32_e32 v107, v4
	s_waitcnt vmcnt(0) lgkmcnt(0)
	v_mov_b32_e32 v108, v4
	v_mov_b32_e32 v109, v4
	v_mov_b32_e32 v110, v4
	v_mov_b32_e32 v111, v4
	v_mov_b32_e32 v112, v4
	v_mov_b32_e32 v113, v4
	v_mov_b32_e32 v114, v4
	v_mov_b32_e32 v115, v4
	v_mov_b32_e32 v76, v4
	v_mov_b32_e32 v77, v4
	v_mov_b32_e32 v78, v4
	v_mov_b32_e32 v79, v4
	v_mov_b32_e32 v80, v4
	v_mov_b32_e32 v81, v4
	v_mov_b32_e32 v82, v4
	v_mov_b32_e32 v83, v4
	v_mov_b32_e32 v92, v4
	v_mov_b32_e32 v93, v4
	v_mov_b32_e32 v94, v4
	v_mov_b32_e32 v95, v4
	v_mov_b32_e32 v96, v4
	v_mov_b32_e32 v97, v4
	v_mov_b32_e32 v98, v4
	v_mov_b32_e32 v99, v4
	v_mov_b32_e32 v116, v4
	v_mov_b32_e32 v117, v4
	v_mov_b32_e32 v118, v4
	v_mov_b32_e32 v119, v4
	v_mov_b32_e32 v120, v4
	v_mov_b32_e32 v121, v4
	v_mov_b32_e32 v122, v4
	v_mov_b32_e32 v123, v4
	v_mov_b32_e32 v124, v4
	v_mov_b32_e32 v125, v4
	v_mov_b32_e32 v126, v4
	v_mov_b32_e32 v127, v4
	v_mov_b32_e32 v128, v4
	v_mov_b32_e32 v129, v4
	v_mov_b32_e32 v130, v4
	v_mov_b32_e32 v131, v4
	v_add_u32_e32 v255, 0x10000, v184
.LBB0_863:
	s_add_u32 s22, s20, 0x100
	s_addc_u32 s23, s21, 0
	s_add_i32 s54, 0, 0x10000
	s_cmpk_eq_i32 s53, 0x54
	s_cselect_b32 s27, s17, s23
	s_cselect_b32 s26, s16, s22
	s_cselect_b32 s25, s19, s37
	s_cselect_b32 s24, s18, s36
	s_add_i32 s55, 0, 0x14000
	ds_read_b128 v[132:135], v255
	ds_read_b128 v[136:139], v255 offset:1024
	ds_read_b128 v[140:143], v255 offset:2048
	ds_read_b128 v[144:147], v255 offset:3072
	ds_read_b128 v[148:151], v255 offset:16384
	ds_read_b128 v[160:163], v255 offset:17408
	ds_read_b128 v[164:167], v255 offset:18432
	ds_read_b128 v[188:191], v255 offset:19456
	v_lshl_add_u64 v[182:183], s[20:21], 0, v[158:159]
	s_add_i32 m0, s41, 0xc000
	ds_read_b128 v[192:195], v186
	ds_read_b128 v[196:199], v186 offset:1024
	ds_read_b128 v[212:215], v186 offset:2048
	ds_read_b128 v[216:219], v186 offset:3072
	ds_read_b128 v[220:223], v186 offset:4096
	ds_read_b128 v[224:227], v186 offset:5120
	ds_read_b128 v[228:231], v186 offset:6144
	ds_read_b128 v[232:235], v186 offset:7168
	global_load_lds_dwordx4 v[182:183], off
	v_lshl_add_u64 v[182:183], s[20:21], 0, v[156:157]
	s_add_i32 m0, s41, 0xe000
	s_nop 0
	global_load_lds_dwordx4 v[182:183], off
	s_waitcnt vmcnt(8)
	s_waitcnt lgkmcnt(0)
	s_barrier
	s_setprio 1
	s_waitcnt lgkmcnt(0)
	v_mfma_f32_16x16x32_bf16 v[128:131], v[132:135], v[192:195], v[128:131]
	v_mfma_f32_16x16x32_bf16 v[124:127], v[140:143], v[192:195], v[124:127]
	v_mfma_f32_16x16x32_bf16 v[120:123], v[132:135], v[212:215], v[120:123]
	v_mfma_f32_16x16x32_bf16 v[116:119], v[140:143], v[212:215], v[116:119]
	v_mfma_f32_16x16x32_bf16 v[96:99], v[132:135], v[220:223], v[96:99]
	v_mfma_f32_16x16x32_bf16 v[92:95], v[140:143], v[220:223], v[92:95]
	v_mfma_f32_16x16x32_bf16 v[80:83], v[132:135], v[228:231], v[80:83]
	v_mfma_f32_16x16x32_bf16 v[76:79], v[140:143], v[228:231], v[76:79]
	v_mfma_f32_16x16x32_bf16 v[128:131], v[136:139], v[196:199], v[128:131]
	v_mfma_f32_16x16x32_bf16 v[124:127], v[144:147], v[196:199], v[124:127]
	v_mfma_f32_16x16x32_bf16 v[120:123], v[136:139], v[216:219], v[120:123]
	v_mfma_f32_16x16x32_bf16 v[116:119], v[144:147], v[216:219], v[116:119]
	v_mfma_f32_16x16x32_bf16 v[96:99], v[136:139], v[224:227], v[96:99]
	v_mfma_f32_16x16x32_bf16 v[92:95], v[144:147], v[224:227], v[92:95]
	v_mfma_f32_16x16x32_bf16 v[80:83], v[136:139], v[232:235], v[80:83]
	v_mfma_f32_16x16x32_bf16 v[76:79], v[144:147], v[232:235], v[76:79]
	s_setprio 0
	s_setprio 1
	v_mfma_f32_16x16x32_bf16 v[112:115], v[148:151], v[192:195], v[112:115]
	v_mfma_f32_16x16x32_bf16 v[108:111], v[164:167], v[192:195], v[108:111]
	v_mfma_f32_16x16x32_bf16 v[104:107], v[148:151], v[212:215], v[104:107]
	v_mfma_f32_16x16x32_bf16 v[100:103], v[164:167], v[212:215], v[100:103]
	v_mfma_f32_16x16x32_bf16 v[88:91], v[148:151], v[220:223], v[88:91]
	v_mfma_f32_16x16x32_bf16 v[84:87], v[164:167], v[220:223], v[84:87]
	v_mfma_f32_16x16x32_bf16 v[72:75], v[148:151], v[228:231], v[72:75]
	v_mfma_f32_16x16x32_bf16 v[68:71], v[164:167], v[228:231], v[68:71]
	v_mfma_f32_16x16x32_bf16 v[112:115], v[160:163], v[196:199], v[112:115]
	v_mfma_f32_16x16x32_bf16 v[108:111], v[188:191], v[196:199], v[108:111]
	v_mfma_f32_16x16x32_bf16 v[104:107], v[160:163], v[216:219], v[104:107]
	v_mfma_f32_16x16x32_bf16 v[100:103], v[188:191], v[216:219], v[100:103]
	v_mfma_f32_16x16x32_bf16 v[88:91], v[160:163], v[224:227], v[88:91]
	v_mfma_f32_16x16x32_bf16 v[84:87], v[188:191], v[224:227], v[84:87]
	v_mfma_f32_16x16x32_bf16 v[72:75], v[160:163], v[232:235], v[72:75]
	v_mfma_f32_16x16x32_bf16 v[68:71], v[188:191], v[232:235], v[68:71]
	s_setprio 0
	s_barrier
; #define PG8_STAGE(bufoff, gbase, voff) do { _Pragma("unroll") for (int _i = 0; _i < 2; ++_i) \
;         __builtin_amdgcn_global_load_lds((const unsigned*)((const char*)(gbase) + (voff)[_i]), (PG8_LAS unsigned*)(lds + (bufoff) + ldsw + _i * 8192), 16, 0, 0); } while (0)
; #define PG8_LDA(dst, b, h) do { _Pragma("unroll") for (int m = 0; m < 4; ++m) _Pragma("unroll") for (int k = 0; k < 2; ++k) dst[m][k] = *(const PG8_LAS bf16x8*)(lds + PG8_SA(b, h) + aoff + m * 2048 + k * 1024); } while (0)
; #define PG8_LDB(dst, b, h) do { _Pragma("unroll") for (int n = 0; n < 2; ++n) _Pragma("unroll") for (int k = 0; k < 2; ++k) dst[n][k] = *(const PG8_LAS bf16x8*)(lds + PG8_SB(b, h) + boff + n * 2048 + k * 1024); } while (0)
; #define PG8_MMA(ai, bj, At, Bt) do { __builtin_amdgcn_s_setprio(1); _Pragma("unroll") for (int m = 0; m < 4; ++m) _Pragma("unroll") for (int n = 0; n < 2; ++n) _Pragma("unroll") for (int k = 0; k < 2; ++k) \
;         acc[ai][bj][m][n] = __builtin_amdgcn_mfma_f32_16x16x32_bf16(Bt[n][k], At[m][k], acc[ai][bj][m][n], 0, 0, 0); __builtin_amdgcn_s_setprio(0); } while (0)
; #define PG8_WAIT_V(n) asm volatile("s_waitcnt vmcnt(" #n ")" ::: "memory")
; #define PG8_WAIT_L(n) asm volatile("s_waitcnt lgkmcnt(" #n ")" ::: "memory")
; #define PG8_BAR __builtin_amdgcn_s_barrier()
; #define PG8_SCHED __builtin_amdgcn_sched_barrier(0)
; template <class Epi, class Sched, bool ALIGN_EPI = false, bool SP2 = false>
; __device__ __forceinline__ void gemm_phase(PG8_LAS unsigned char* lds, const Gemm g, const Sched& S, const Epi& E, int wave_s) {
;     ...
;             PG8_WAIT_V(8); PG8_WAIT_L(0); PG8_BAR; PG8_MMA(0, 0, At, B0); PG8_MMA(0, 1, At, B1); PG8_BAR; PG8_SCHED;
;             PG8_LDA(At, 0, 1); PG8_STAGE(PG8_SB(0, 0), b2, voffB); PG8_STAGE(PG8_SB(0, 1), b2 + hstepB, voffB); PG8_STAGE(PG8_SA(0, 0), a2, voffA);
;             PG8_WAIT_V(8); PG8_WAIT_L(0); PG8_BAR; PG8_MMA(1, 0, At, B0); PG8_MMA(1, 1, At, B1); PG8_BAR; PG8_SCHED;
;             PG8_LDB(B0, 1, 0); PG8_LDB(B1, 1, 1); PG8_SCHED; PG8_LDA(At, 1, 0); PG8_STAGE(PG8_SA(0, 1), a2 + hstepA, voffA);
	s_add_i32 s20, s54, s40
	s_add_u32 s98, s24, s60
	s_addc_u32 s99, s25, s61
	s_mov_b32 m0, s20
	ds_read_b128 v[192:195], v186 offset:16384
	ds_read_b128 v[196:199], v186 offset:17408
	ds_read_b128 v[212:215], v186 offset:18432
	ds_read_b128 v[216:219], v186 offset:19456
	ds_read_b128 v[220:223], v186 offset:20480
	ds_read_b128 v[224:227], v186 offset:21504
	ds_read_b128 v[228:231], v186 offset:22528
	ds_read_b128 v[232:235], v186 offset:23552
	global_load_lds_dwordx4 v2, s[24:25]
	s_add_i32 m0, s20, 0x2000
	s_add_u32 s20, s24, 0x160000
	s_addc_u32 s21, s25, 0
	s_add_i32 s54, s55, s40
	global_load_lds_dwordx4 v0, s[24:25]
	s_mov_b32 m0, s54
	s_add_u32 s100, s26, s60
	s_addc_u32 s101, s27, s61
	s_nop 0
	global_load_lds_dwordx4 v2, s[20:21]
	s_add_i32 m0, s54, 0x2000
	s_nop 0
	global_load_lds_dwordx4 v0, s[20:21]
	s_mov_b32 m0, s41
	s_nop 0
	global_load_lds_dwordx4 v154, s[26:27]
	s_mov_b32 m0, s42
	s_nop 0
	global_load_lds_dwordx4 v152, s[26:27]
	s_waitcnt vmcnt(8)
	s_waitcnt lgkmcnt(0)
	s_barrier
	s_setprio 1
	s_waitcnt lgkmcnt(0)
	v_mfma_f32_16x16x32_bf16 v[64:67], v[132:135], v[192:195], v[64:67]
	v_mfma_f32_16x16x32_bf16 v[60:63], v[140:143], v[192:195], v[60:63]
	v_mfma_f32_16x16x32_bf16 v[48:51], v[132:135], v[212:215], v[48:51]
	v_mfma_f32_16x16x32_bf16 v[44:47], v[140:143], v[212:215], v[44:47]
	v_mfma_f32_16x16x32_bf16 v[32:35], v[132:135], v[220:223], v[32:35]
	v_mfma_f32_16x16x32_bf16 v[28:31], v[140:143], v[220:223], v[28:31]
	v_mfma_f32_16x16x32_bf16 v[16:19], v[132:135], v[228:231], v[16:19]
	v_mfma_f32_16x16x32_bf16 v[12:15], v[140:143], v[228:231], v[12:15]
	v_mfma_f32_16x16x32_bf16 v[64:67], v[136:139], v[196:199], v[64:67]
	v_mfma_f32_16x16x32_bf16 v[60:63], v[144:147], v[196:199], v[60:63]
	v_mfma_f32_16x16x32_bf16 v[48:51], v[136:139], v[216:219], v[48:51]
	v_mfma_f32_16x16x32_bf16 v[44:47], v[144:147], v[216:219], v[44:47]
	v_mfma_f32_16x16x32_bf16 v[32:35], v[136:139], v[224:227], v[32:35]
	v_mfma_f32_16x16x32_bf16 v[28:31], v[144:147], v[224:227], v[28:31]
	v_mfma_f32_16x16x32_bf16 v[16:19], v[136:139], v[232:235], v[16:19]
	v_mfma_f32_16x16x32_bf16 v[12:15], v[144:147], v[232:235], v[12:15]
	s_setprio 0
	s_setprio 1
	v_mfma_f32_16x16x32_bf16 v[56:59], v[148:151], v[192:195], v[56:59]
	v_mfma_f32_16x16x32_bf16 v[52:55], v[164:167], v[192:195], v[52:55]
	v_mfma_f32_16x16x32_bf16 v[40:43], v[148:151], v[212:215], v[40:43]
	v_mfma_f32_16x16x32_bf16 v[36:39], v[164:167], v[212:215], v[36:39]
	v_mfma_f32_16x16x32_bf16 v[24:27], v[148:151], v[220:223], v[24:27]
	v_mfma_f32_16x16x32_bf16 v[20:23], v[164:167], v[220:223], v[20:23]
	v_mfma_f32_16x16x32_bf16 v[8:11], v[148:151], v[228:231], v[8:11]
	v_mfma_f32_16x16x32_bf16 v[4:7], v[164:167], v[228:231], v[4:7]
	v_mfma_f32_16x16x32_bf16 v[56:59], v[160:163], v[196:199], v[56:59]
	v_mfma_f32_16x16x32_bf16 v[52:55], v[188:191], v[196:199], v[52:55]
	v_mfma_f32_16x16x32_bf16 v[40:43], v[160:163], v[216:219], v[40:43]
	v_mfma_f32_16x16x32_bf16 v[36:39], v[188:191], v[216:219], v[36:39]
	v_mfma_f32_16x16x32_bf16 v[24:27], v[160:163], v[224:227], v[24:27]
	v_mfma_f32_16x16x32_bf16 v[20:23], v[188:191], v[224:227], v[20:23]
	v_mfma_f32_16x16x32_bf16 v[8:11], v[160:163], v[232:235], v[8:11]
	v_mfma_f32_16x16x32_bf16 v[4:7], v[188:191], v[232:235], v[4:7]
	s_setprio 0
	s_barrier
	s_add_i32 s54, 0, 0x18000
	s_add_i32 s55, 0, 0x1c000
	ds_read_b128 v[132:135], v255 offset:32768
	ds_read_b128 v[136:139], v255 offset:33792
	ds_read_b128 v[140:143], v255 offset:34816
	ds_read_b128 v[144:147], v255 offset:35840
	ds_read_b128 v[148:151], v255 offset:49152
	ds_read_b128 v[160:163], v255 offset:50176
	ds_read_b128 v[164:167], v255 offset:51200
	ds_read_b128 v[188:191], v255 offset:52224
	s_add_u32 s20, s26, 0x160000
	s_addc_u32 s21, s27, 0
	s_mov_b32 m0, s43
	ds_read_b128 v[192:195], v186 offset:32768
	ds_read_b128 v[196:199], v186 offset:33792
	ds_read_b128 v[212:215], v186 offset:34816
	ds_read_b128 v[216:219], v186 offset:35840
	ds_read_b128 v[220:223], v186 offset:36864
	ds_read_b128 v[224:227], v186 offset:37888
	ds_read_b128 v[228:231], v186 offset:38912
	ds_read_b128 v[232:235], v186 offset:39936
	global_load_lds_dwordx4 v154, s[20:21]
	s_mov_b32 m0, s44
	s_nop 0
	global_load_lds_dwordx4 v152, s[20:21]
	s_waitcnt vmcnt(8)
	s_waitcnt lgkmcnt(0)
	s_barrier
; #define PG8_STAGE(bufoff, gbase, voff) do { _Pragma("unroll") for (int _i = 0; _i < 2; ++_i) \
;         __builtin_amdgcn_global_load_lds((const unsigned*)((const char*)(gbase) + (voff)[_i]), (PG8_LAS unsigned*)(lds + (bufoff) + ldsw + _i * 8192), 16, 0, 0); } while (0)
; #define PG8_LDA(dst, b, h) do { _Pragma("unroll") for (int m = 0; m < 4; ++m) _Pragma("unroll") for (int k = 0; k < 2; ++k) dst[m][k] = *(const PG8_LAS bf16x8*)(lds + PG8_SA(b, h) + aoff + m * 2048 + k * 1024); } while (0)
; #define PG8_MMA(ai, bj, At, Bt) do { __builtin_amdgcn_s_setprio(1); _Pragma("unroll") for (int m = 0; m < 4; ++m) _Pragma("unroll") for (int n = 0; n < 2; ++n) _Pragma("unroll") for (int k = 0; k < 2; ++k) \
;         acc[ai][bj][m][n] = __builtin_amdgcn_mfma_f32_16x16x32_bf16(Bt[n][k], At[m][k], acc[ai][bj][m][n], 0, 0, 0); __builtin_amdgcn_s_setprio(0); } while (0)
; #define PG8_WAIT_V(n) asm volatile("s_waitcnt vmcnt(" #n ")" ::: "memory")
; #define PG8_WAIT_L(n) asm volatile("s_waitcnt lgkmcnt(" #n ")" ::: "memory")
; #define PG8_BAR __builtin_amdgcn_s_barrier()
; #define PG8_SCHED __builtin_amdgcn_sched_barrier(0)
; template <class Epi, class Sched, bool ALIGN_EPI = false, bool SP2 = false>
; __device__ __forceinline__ void gemm_phase(PG8_LAS unsigned char* lds, const Gemm g, const Sched& S, const Epi& E, int wave_s) {
;     ...
;             PG8_WAIT_V(8); PG8_WAIT_L(0); PG8_BAR; PG8_MMA(0, 0, At, B0); PG8_MMA(0, 1, At, B1); PG8_BAR; PG8_SCHED;
;             PG8_LDA(At, 1, 1); PG8_STAGE(PG8_SB(1, 0), b3, voffB); PG8_STAGE(PG8_SB(1, 1), b3 + hstepB, voffB); PG8_STAGE(PG8_SA(1, 0), a3, voffA);
;             PG8_WAIT_V(8); PG8_WAIT_L(0); PG8_BAR; PG8_MMA(1, 0, At, B0); PG8_MMA(1, 1, At, B1); PG8_BAR; PG8_SCHED;
	s_setprio 1
	s_waitcnt lgkmcnt(0)
	v_mfma_f32_16x16x32_bf16 v[128:131], v[132:135], v[192:195], v[128:131]
	v_mfma_f32_16x16x32_bf16 v[124:127], v[140:143], v[192:195], v[124:127]
	v_mfma_f32_16x16x32_bf16 v[120:123], v[132:135], v[212:215], v[120:123]
	v_mfma_f32_16x16x32_bf16 v[116:119], v[140:143], v[212:215], v[116:119]
	v_mfma_f32_16x16x32_bf16 v[96:99], v[132:135], v[220:223], v[96:99]
	v_mfma_f32_16x16x32_bf16 v[92:95], v[140:143], v[220:223], v[92:95]
	v_mfma_f32_16x16x32_bf16 v[80:83], v[132:135], v[228:231], v[80:83]
	v_mfma_f32_16x16x32_bf16 v[76:79], v[140:143], v[228:231], v[76:79]
	v_mfma_f32_16x16x32_bf16 v[128:131], v[136:139], v[196:199], v[128:131]
	v_mfma_f32_16x16x32_bf16 v[124:127], v[144:147], v[196:199], v[124:127]
	v_mfma_f32_16x16x32_bf16 v[120:123], v[136:139], v[216:219], v[120:123]
	v_mfma_f32_16x16x32_bf16 v[116:119], v[144:147], v[216:219], v[116:119]
	v_mfma_f32_16x16x32_bf16 v[96:99], v[136:139], v[224:227], v[96:99]
	v_mfma_f32_16x16x32_bf16 v[92:95], v[144:147], v[224:227], v[92:95]
	v_mfma_f32_16x16x32_bf16 v[80:83], v[136:139], v[232:235], v[80:83]
	v_mfma_f32_16x16x32_bf16 v[76:79], v[144:147], v[232:235], v[76:79]
	s_setprio 0
	s_setprio 1
	v_mfma_f32_16x16x32_bf16 v[112:115], v[148:151], v[192:195], v[112:115]
	v_mfma_f32_16x16x32_bf16 v[108:111], v[164:167], v[192:195], v[108:111]
	v_mfma_f32_16x16x32_bf16 v[104:107], v[148:151], v[212:215], v[104:107]
	v_mfma_f32_16x16x32_bf16 v[100:103], v[164:167], v[212:215], v[100:103]
	v_mfma_f32_16x16x32_bf16 v[88:91], v[148:151], v[220:223], v[88:91]
	v_mfma_f32_16x16x32_bf16 v[84:87], v[164:167], v[220:223], v[84:87]
	v_mfma_f32_16x16x32_bf16 v[72:75], v[148:151], v[228:231], v[72:75]
	v_mfma_f32_16x16x32_bf16 v[68:71], v[164:167], v[228:231], v[68:71]
	v_mfma_f32_16x16x32_bf16 v[112:115], v[160:163], v[196:199], v[112:115]
	v_mfma_f32_16x16x32_bf16 v[108:111], v[188:191], v[196:199], v[108:111]
	v_mfma_f32_16x16x32_bf16 v[104:107], v[160:163], v[216:219], v[104:107]
	v_mfma_f32_16x16x32_bf16 v[100:103], v[188:191], v[216:219], v[100:103]
	v_mfma_f32_16x16x32_bf16 v[88:91], v[160:163], v[224:227], v[88:91]
	v_mfma_f32_16x16x32_bf16 v[84:87], v[188:191], v[224:227], v[84:87]
	v_mfma_f32_16x16x32_bf16 v[72:75], v[160:163], v[232:235], v[72:75]
	v_mfma_f32_16x16x32_bf16 v[68:71], v[188:191], v[232:235], v[68:71]
	s_setprio 0
	s_barrier
	s_add_i32 s20, s54, s40
	s_mov_b32 m0, s20
	ds_read_b128 v[192:195], v186 offset:49152
	ds_read_b128 v[196:199], v186 offset:50176
	ds_read_b128 v[212:215], v186 offset:51200
	ds_read_b128 v[216:219], v186 offset:52224
	ds_read_b128 v[220:223], v186 offset:53248
	ds_read_b128 v[224:227], v186 offset:54272
	ds_read_b128 v[228:231], v186 offset:55296
	ds_read_b128 v[232:235], v186 offset:56320
	global_load_lds_dwordx4 v2, s[98:99]
	s_add_i32 m0, s20, 0x2000
	s_add_u32 s20, s24, 0x160080
	s_addc_u32 s21, s25, 0
	s_add_i32 s24, s55, s40
	global_load_lds_dwordx4 v0, s[98:99]
	s_mov_b32 m0, s24
	s_nop 0
	global_load_lds_dwordx4 v2, s[20:21]
	s_add_i32 m0, s24, 0x2000
	s_nop 0
	global_load_lds_dwordx4 v0, s[20:21]
	s_mov_b32 m0, s47
	s_nop 0
	global_load_lds_dwordx4 v154, s[100:101]
	s_mov_b32 m0, s48
	s_nop 0
	global_load_lds_dwordx4 v152, s[100:101]
	s_waitcnt vmcnt(8)
	s_waitcnt lgkmcnt(0)
	s_barrier
	s_setprio 1
	s_waitcnt lgkmcnt(0)
	v_mfma_f32_16x16x32_bf16 v[64:67], v[132:135], v[192:195], v[64:67]
	v_mfma_f32_16x16x32_bf16 v[60:63], v[140:143], v[192:195], v[60:63]
	v_mfma_f32_16x16x32_bf16 v[48:51], v[132:135], v[212:215], v[48:51]
	v_mfma_f32_16x16x32_bf16 v[44:47], v[140:143], v[212:215], v[44:47]
	v_mfma_f32_16x16x32_bf16 v[32:35], v[132:135], v[220:223], v[32:35]
	v_mfma_f32_16x16x32_bf16 v[28:31], v[140:143], v[220:223], v[28:31]
	v_mfma_f32_16x16x32_bf16 v[16:19], v[132:135], v[228:231], v[16:19]
	v_mfma_f32_16x16x32_bf16 v[12:15], v[140:143], v[228:231], v[12:15]
	v_mfma_f32_16x16x32_bf16 v[64:67], v[136:139], v[196:199], v[64:67]
	v_mfma_f32_16x16x32_bf16 v[60:63], v[144:147], v[196:199], v[60:63]
	v_mfma_f32_16x16x32_bf16 v[48:51], v[136:139], v[216:219], v[48:51]
	v_mfma_f32_16x16x32_bf16 v[44:47], v[144:147], v[216:219], v[44:47]
	v_mfma_f32_16x16x32_bf16 v[32:35], v[136:139], v[224:227], v[32:35]
	v_mfma_f32_16x16x32_bf16 v[28:31], v[144:147], v[224:227], v[28:31]
	v_mfma_f32_16x16x32_bf16 v[16:19], v[136:139], v[232:235], v[16:19]
	v_mfma_f32_16x16x32_bf16 v[12:15], v[144:147], v[232:235], v[12:15]
	s_setprio 0
	s_setprio 1
	v_mfma_f32_16x16x32_bf16 v[56:59], v[148:151], v[192:195], v[56:59]
	v_mfma_f32_16x16x32_bf16 v[52:55], v[164:167], v[192:195], v[52:55]
	v_mfma_f32_16x16x32_bf16 v[40:43], v[148:151], v[212:215], v[40:43]
	v_mfma_f32_16x16x32_bf16 v[36:39], v[164:167], v[212:215], v[36:39]
	v_mfma_f32_16x16x32_bf16 v[24:27], v[148:151], v[220:223], v[24:27]
	v_mfma_f32_16x16x32_bf16 v[20:23], v[164:167], v[220:223], v[20:23]
	v_mfma_f32_16x16x32_bf16 v[8:11], v[148:151], v[228:231], v[8:11]
	v_mfma_f32_16x16x32_bf16 v[4:7], v[164:167], v[228:231], v[4:7]
	v_mfma_f32_16x16x32_bf16 v[56:59], v[160:163], v[196:199], v[56:59]
	v_mfma_f32_16x16x32_bf16 v[52:55], v[188:191], v[196:199], v[52:55]
	v_mfma_f32_16x16x32_bf16 v[40:43], v[160:163], v[216:219], v[40:43]
	v_mfma_f32_16x16x32_bf16 v[36:39], v[188:191], v[216:219], v[36:39]
	v_mfma_f32_16x16x32_bf16 v[24:27], v[160:163], v[224:227], v[24:27]
	v_mfma_f32_16x16x32_bf16 v[20:23], v[188:191], v[224:227], v[20:23]
	v_mfma_f32_16x16x32_bf16 v[8:11], v[160:163], v[232:235], v[8:11]
	v_mfma_f32_16x16x32_bf16 v[4:7], v[188:191], v[232:235], v[4:7]
	s_setprio 0
	s_barrier
	s_add_i32 s53, s53, 2
	s_add_u32 s36, s36, 0x100
	s_addc_u32 s37, s37, 0
	s_cmpk_gt_u32 s53, 0x55
	s_mov_b64 s[20:21], s[22:23]
	s_cbranch_scc0 .LBB0_863
	s_and_b64 vcc, exec, s[6:7]
	s_cbranch_vccz .LBB0_866
	s_barrier

; __global__ void __launch_bounds__(512, 2) fwd_kernel(Args a) {
	.amdhsa_kernel _Z10fwd_kernel4Args
		.amdhsa_group_segment_fixed_size 0
		.amdhsa_private_segment_fixed_size 0
		.amdhsa_kernarg_size 440
		.amdhsa_user_sgpr_count 2
		.amdhsa_user_sgpr_dispatch_ptr 0
		.amdhsa_user_sgpr_queue_ptr 0
		.amdhsa_user_sgpr_kernarg_segment_ptr 1
		.amdhsa_user_sgpr_dispatch_id 0
		.amdhsa_user_sgpr_kernarg_preload_length 0
		.amdhsa_user_sgpr_kernarg_preload_offset 0
		.amdhsa_user_sgpr_private_segment_size 0
		.amdhsa_uses_dynamic_stack 0
		.amdhsa_enable_private_segment 0
		.amdhsa_system_sgpr_workgroup_id_x 1
		.amdhsa_system_sgpr_workgroup_id_y 0
		.amdhsa_system_sgpr_workgroup_id_z 0
		.amdhsa_system_sgpr_workgroup_info 0
		.amdhsa_system_vgpr_workitem_id 2
		.amdhsa_next_free_vgpr 256
		.amdhsa_next_free_sgpr 102
		.amdhsa_accum_offset 256
		.amdhsa_reserve_vcc 1
		.amdhsa_float_round_mode_32 0
		.amdhsa_float_round_mode_16_64 0
		.amdhsa_float_denorm_mode_32 3
		.amdhsa_float_denorm_mode_16_64 3
		.amdhsa_dx10_clamp 1
		.amdhsa_ieee_mode 1
		.amdhsa_fp16_overflow 0
		.amdhsa_tg_split 0
		.amdhsa_exception_fp_ieee_invalid_op 0
		.amdhsa_exception_fp_denorm_src 0
		.amdhsa_exception_fp_ieee_div_zero 0
		.amdhsa_exception_fp_ieee_overflow 0
		.amdhsa_exception_fp_ieee_underflow 0
		.amdhsa_exception_fp_ieee_inexact 0
		.amdhsa_exception_int_div_zero 0
	.end_amdhsa_kernel

; __global__ void __launch_bounds__(512, 2) fwd_kernel(Args a) {
amdhsa.kernels:
  - .agpr_count:     0
    .args:
      - .offset:         0
        .size:           184
        .value_kind:     by_value
      - .offset:         184
        .size:           4
        .value_kind:     hidden_block_count_x
      - .offset:         188
        .size:           4
        .value_kind:     hidden_block_count_y
      - .offset:         192
        .size:           4
        .value_kind:     hidden_block_count_z
      - .offset:         196
        .size:           2
        .value_kind:     hidden_group_size_x
      - .offset:         198
        .size:           2
        .value_kind:     hidden_group_size_y
      - .offset:         200
        .size:           2
        .value_kind:     hidden_group_size_z
      - .offset:         202
        .size:           2
        .value_kind:     hidden_remainder_x
      - .offset:         204
        .size:           2
        .value_kind:     hidden_remainder_y
      - .offset:         206
        .size:           2
        .value_kind:     hidden_remainder_z
      - .offset:         224
        .size:           8
        .value_kind:     hidden_global_offset_x
      - .offset:         232
        .size:           8
        .value_kind:     hidden_global_offset_y
      - .offset:         240
        .size:           8
        .value_kind:     hidden_global_offset_z
      - .offset:         248
        .size:           2
        .value_kind:     hidden_grid_dims
      - .offset:         272
        .size:           8
        .value_kind:     hidden_multigrid_sync_arg
      - .offset:         304
        .size:           4
        .value_kind:     hidden_dynamic_lds_size
    .group_segment_fixed_size: 0
    .kernarg_segment_align: 8
    .kernarg_segment_size: 440
    .language:       OpenCL C
    .language_version:
      - 2
      - 0
    .max_flat_workgroup_size: 512
    .name:           _Z10fwd_kernel4Args
    .private_segment_fixed_size: 0
    .sgpr_count:     108
    .sgpr_spill_count: 154
    .symbol:         _Z10fwd_kernel4Args.kd
    .uniform_work_group_size: 1
    .uses_dynamic_stack: false
    .vgpr_count:     256
    .vgpr_spill_count: 0
    .wavefront_size: 64
